# P6 task stage 3: all 16 A-operand loads issued at stage start into free registers (vmcnt ladder recomputed) instead of group-by-group after the previous group's stores
# speedup vs baseline: 1.0083x; 1.0050x over previous
.LBB0_685:
	s_or_b64 exec, exec, s[62:63]
	s_waitcnt lgkmcnt(0)
	v_sub_f32_e32 v43, v131, v43
	v_mul_f32_e32 v43, 0x3fb8aa3b, v43
	v_sub_f32_e32 v42, v131, v42
	v_exp_f32_e32 v43, v43
	v_mul_f32_e32 v42, 0x3fb8aa3b, v42
	v_sub_f32_e32 v41, v131, v41
	v_exp_f32_e32 v42, v42
	v_mul_f32_e32 v41, 0x3fb8aa3b, v41
	v_sub_f32_e32 v40, v131, v40
	v_exp_f32_e32 v41, v41
	v_mul_f32_e32 v40, 0x3fb8aa3b, v40
	v_mul_f32_e32 v44, 0x3db504f3, v49
	v_exp_f32_e32 v40, v40
	v_mul_f32_e32 v43, v44, v43
	v_mul_f32_e32 v44, 0x3db504f3, v48
	v_mul_f32_e32 v42, v44, v42
	v_mul_f32_e32 v44, 0x3db504f3, v47
	v_mul_f32_e32 v41, v44, v41
	v_mul_f32_e32 v44, 0x3db504f3, v46
	v_sub_f32_e32 v45, v162, v131
	v_mul_f32_e32 v40, v44, v40
	v_sub_f32_e32 v44, v162, v130
	v_mul_f32_e32 v45, 0x3fb8aa3b, v45
	v_mul_f32_e32 v44, 0x3fb8aa3b, v44
	v_exp_f32_e32 v45, v45
	v_exp_f32_e32 v44, v44
	v_mul_f32_e32 v17, v17, v163
	v_mul_f32_e32 v33, v33, v163
	v_mul_f32_e32 v17, v17, v45
	v_mul_f32_e32 v211, v33, v44
	v_cndmask_b32_e64 v62, 0, v17, s[60:61]
	v_sub_f32_e32 v17, v160, v130
	v_sub_f32_e32 v33, v160, v131
	v_mul_f32_e32 v17, 0x3fb8aa3b, v17
	v_mul_f32_e32 v33, 0x3fb8aa3b, v33
	v_exp_f32_e32 v17, v17
	v_exp_f32_e32 v33, v33
	v_mul_f32_e32 v32, v32, v161
	v_mul_f32_e32 v16, v16, v161
	v_mul_f32_e32 v212, v32, v17
	v_mul_f32_e32 v16, v16, v33
	v_sub_f32_e32 v17, v158, v131
	v_cndmask_b32_e64 v66, 0, v16, s[58:59]
	v_sub_f32_e32 v16, v158, v130
	v_mul_f32_e32 v17, 0x3fb8aa3b, v17
	v_mul_f32_e32 v16, 0x3fb8aa3b, v16
	v_exp_f32_e32 v17, v17
	v_exp_f32_e32 v16, v16
	v_mul_f32_e32 v15, v15, v159
	v_mul_f32_e32 v31, v31, v159
	v_mul_f32_e32 v15, v15, v17
	v_mul_f32_e32 v213, v31, v16
	v_cndmask_b32_e64 v70, 0, v15, s[56:57]
	v_sub_f32_e32 v15, v156, v130
	v_sub_f32_e32 v16, v156, v131
	v_mul_f32_e32 v15, 0x3fb8aa3b, v15
	v_mul_f32_e32 v16, 0x3fb8aa3b, v16
	v_exp_f32_e32 v15, v15
	v_exp_f32_e32 v16, v16
	v_mul_f32_e32 v17, v30, v157
	v_mul_f32_e32 v14, v14, v157
	v_mul_f32_e32 v214, v17, v15
	v_mul_f32_e32 v14, v14, v16
	v_sub_f32_e32 v15, v154, v130
	v_sub_f32_e32 v16, v154, v131
	v_mul_f32_e32 v15, 0x3fb8aa3b, v15
	v_mul_f32_e32 v16, 0x3fb8aa3b, v16
	v_exp_f32_e32 v15, v15
	v_exp_f32_e32 v16, v16
	v_mul_f32_e32 v17, v29, v155
	v_mul_f32_e32 v13, v13, v155
	v_mul_f32_e32 v215, v17, v15
	v_mul_f32_e32 v13, v13, v16
	v_sub_f32_e32 v15, v152, v131
	v_cndmask_b32_e64 v74, 0, v13, s[52:53]
	v_sub_f32_e32 v13, v152, v130
	v_mul_f32_e32 v15, 0x3fb8aa3b, v15
	v_mul_f32_e32 v13, 0x3fb8aa3b, v13
	v_exp_f32_e32 v15, v15
	v_exp_f32_e32 v13, v13
	v_mul_f32_e32 v12, v12, v153
	v_mul_f32_e32 v16, v28, v153
	v_mul_f32_e32 v12, v12, v15
	v_mul_f32_e32 v216, v16, v13
	v_cndmask_b32_e64 v28, 0, v12, s[50:51]
	v_sub_f32_e32 v12, v150, v130
	v_sub_f32_e32 v13, v150, v131
	v_mul_f32_e32 v12, 0x3fb8aa3b, v12
	v_mul_f32_e32 v13, 0x3fb8aa3b, v13
	v_exp_f32_e32 v12, v12
	v_exp_f32_e32 v13, v13
	v_mul_f32_e32 v15, v27, v151
	v_mul_f32_e32 v11, v11, v151
	v_mul_f32_e32 v217, v15, v12
	v_mul_f32_e32 v11, v11, v13
	v_sub_f32_e32 v12, v148, v131
	v_cndmask_b32_e64 v78, 0, v11, s[48:49]
	v_sub_f32_e32 v11, v148, v130
	v_mul_f32_e32 v12, 0x3fb8aa3b, v12
	v_mul_f32_e32 v11, 0x3fb8aa3b, v11
	v_exp_f32_e32 v12, v12
	v_exp_f32_e32 v11, v11
	v_mul_f32_e32 v10, v10, v149
	v_mul_f32_e32 v13, v26, v149
	v_mul_f32_e32 v10, v10, v12
	v_mul_f32_e32 v218, v13, v11
	v_cndmask_b32_e64 v82, 0, v10, s[46:47]
	v_sub_f32_e32 v10, v146, v130
	v_sub_f32_e32 v11, v146, v131
	v_mul_f32_e32 v10, 0x3fb8aa3b, v10
	v_mul_f32_e32 v11, 0x3fb8aa3b, v11
	v_exp_f32_e32 v10, v10
	v_exp_f32_e32 v11, v11
	v_mul_f32_e32 v12, v25, v147
	v_mul_f32_e32 v9, v9, v147
	v_mul_f32_e32 v219, v12, v10
	v_mul_f32_e32 v9, v9, v11
	v_sub_f32_e32 v10, v144, v131
	v_cndmask_b32_e64 v84, 0, v9, s[44:45]
	v_sub_f32_e32 v9, v144, v130
	v_mul_f32_e32 v10, 0x3fb8aa3b, v10
	v_mul_f32_e32 v9, 0x3fb8aa3b, v9
	v_exp_f32_e32 v10, v10
	v_exp_f32_e32 v9, v9
	v_mul_f32_e32 v8, v8, v145
	v_mul_f32_e32 v11, v24, v145
	v_mul_f32_e32 v8, v8, v10
	v_mul_f32_e32 v220, v11, v9
	v_cndmask_b32_e64 v24, 0, v8, s[42:43]
	v_sub_f32_e32 v8, v142, v130
	v_sub_f32_e32 v9, v142, v131
	v_mul_f32_e32 v8, 0x3fb8aa3b, v8
	v_mul_f32_e32 v9, 0x3fb8aa3b, v9
	v_exp_f32_e32 v8, v8
	v_exp_f32_e32 v9, v9
	v_mul_f32_e32 v10, v23, v143
	v_mul_f32_e32 v7, v7, v143
	v_mul_f32_e32 v221, v10, v8
	v_mul_f32_e32 v7, v7, v9
	v_sub_f32_e32 v8, v140, v131
	v_cndmask_b32_e64 v142, 0, v7, s[40:41]
	v_sub_f32_e32 v7, v140, v130
	v_mul_f32_e32 v8, 0x3fb8aa3b, v8
	v_mul_f32_e32 v7, 0x3fb8aa3b, v7
	v_exp_f32_e32 v8, v8
	v_exp_f32_e32 v7, v7
	v_mul_f32_e32 v6, v6, v141
	v_mul_f32_e32 v9, v22, v141
	v_mul_f32_e32 v6, v6, v8
	v_sub_f32_e32 v8, v138, v131
	v_mul_f32_e32 v222, v9, v7
	v_sub_f32_e32 v7, v138, v130
	v_mul_f32_e32 v8, 0x3fb8aa3b, v8
	v_mul_f32_e32 v7, 0x3fb8aa3b, v7
	v_exp_f32_e32 v8, v8
	v_exp_f32_e32 v7, v7
	v_mul_f32_e32 v5, v5, v139
	v_mul_f32_e32 v9, v21, v139
	v_mul_f32_e32 v5, v5, v8
	v_mul_f32_e32 v223, v9, v7
	v_cndmask_b32_e64 v140, 0, v5, s[8:9]
	v_sub_f32_e32 v5, v136, v130
	v_sub_f32_e32 v7, v136, v131
	v_mul_f32_e32 v5, 0x3fb8aa3b, v5
	v_mul_f32_e32 v7, 0x3fb8aa3b, v7
	v_exp_f32_e32 v5, v5
	v_exp_f32_e32 v7, v7
	v_mul_f32_e32 v8, v20, v137
	v_mul_f32_e32 v4, v4, v137
	v_mul_f32_e32 v224, v8, v5
	v_mul_f32_e32 v4, v4, v7
	v_sub_f32_e32 v5, v134, v131
	v_cndmask_b32_e64 v144, 0, v4, s[6:7]
	v_sub_f32_e32 v4, v134, v130
	v_mul_f32_e32 v5, 0x3fb8aa3b, v5
	v_mul_f32_e32 v4, 0x3fb8aa3b, v4
	v_exp_f32_e32 v5, v5
	v_exp_f32_e32 v4, v4
	v_mul_f32_e32 v3, v3, v135
	v_mul_f32_e32 v7, v19, v135
	v_mul_f32_e32 v3, v3, v5
	v_mul_f32_e32 v225, v7, v4
	v_cndmask_b32_e64 v146, v3, 0, s[4:5]
	v_sub_f32_e32 v3, v132, v130
	v_sub_f32_e32 v4, v132, v131
	v_mul_f32_e32 v3, 0x3fb8aa3b, v3
	v_mul_f32_e32 v4, 0x3fb8aa3b, v4
	v_exp_f32_e32 v3, v3
	v_exp_f32_e32 v4, v4
	v_mul_f32_e32 v5, v18, v133
	v_mul_f32_e32 v2, v2, v133
	v_mul_f32_e32 v226, v5, v3
	v_mul_f32_e32 v2, v2, v4
	v_cvt_pk_bf16_f32 v4, v40, v41
	v_cvt_pk_bf16_f32 v5, v42, v43
	global_store_dwordx2 v[34:35], v[4:5], off offset:48
	v_cvt_pk_bf16_f32 v4, v36, v38
	v_cvt_pk_bf16_f32 v5, v37, v39
	global_store_dwordx2 v[34:35], v[4:5], off offset:112
	v_cndmask_b32_e64 v14, 0, v14, s[54:55]
	v_cndmask_b32_e64 v6, 0, v6, s[38:39]
	v_cndmask_b32_e64 v2, 0, v2, s[0:1]
	v_lshlrev_b64 v[86:87], 1, v[128:129]
	s_add_u32 s0, s94, s28
	v_lshl_add_u64 v[4:5], v[122:123], 0, v[86:87]
	s_addc_u32 s1, s95, s29
	v_lshl_add_u64 v[98:99], s[0:1], 0, v[4:5]
	s_mov_b32 s4, 0x9000000
	v_add_co_u32_e32 v4, vcc, s4, v98
	s_mov_b32 s4, 0x9001000
	s_nop 0
	v_addc_co_u32_e32 v5, vcc, 0, v99, vcc
	v_add_co_u32_e32 v8, vcc, s4, v98
	v_lshlrev_b32_e32 v90, 4, v126
	s_nop 0
	v_addc_co_u32_e32 v9, vcc, 0, v99, vcc
	v_cmp_eq_u32_e32 vcc, 63, v126
	global_load_dwordx4 v[58:61], v[4:5], off offset:32
	global_load_dwordx4 v[54:57], v[4:5], off offset:64
	global_load_dwordx4 v[18:21], v[8:9], off offset:-4096
	global_load_dwordx4 v[50:53], v[4:5], off offset:96
	global_load_dwordx4 v[46:49], v[8:9], off
	global_load_dwordx4 v[42:45], v[8:9], off offset:32
	global_load_dwordx4 v[38:41], v[8:9], off offset:64
	global_load_dwordx4 v[34:37], v[8:9], off offset:96
	v_cndmask_b32_e64 v89, 0, 1.0, vcc
	v_cmp_eq_u32_e32 vcc, 62, v126
	v_add_u32_e32 v92, 0x1000, v90
	v_ashrrev_i32_e32 v93, 31, v92
	v_cndmask_b32_e64 v3, 0, 1.0, vcc
	v_cmp_eq_u32_e32 vcc, 61, v126
	v_lshl_add_u64 v[120:121], v[92:93], 1, s[0:1]
	v_add_u32_e32 v92, 0x1400, v90
	v_cndmask_b32_e64 v4, 0, 1.0, vcc
	v_cmp_eq_u32_e32 vcc, 60, v126
	v_ashrrev_i32_e32 v93, 31, v92
	v_lshl_add_u64 v[112:113], v[92:93], 1, s[0:1]
	v_cndmask_b32_e64 v8, 0, 1.0, vcc
	v_cmp_eq_u32_e32 vcc, 59, v126
	v_add_u32_e32 v92, 0x800, v90
	v_ashrrev_i32_e32 v91, 31, v90
	v_cndmask_b32_e64 v5, 0, 1.0, vcc
	v_cmp_eq_u32_e32 vcc, 58, v126
	v_ashrrev_i32_e32 v93, 31, v92
	v_add_u32_e32 v100, 0x1800, v90
	v_cndmask_b32_e64 v9, 0, 1.0, vcc
	v_cmp_eq_u32_e32 vcc, 57, v126
	v_lshl_add_u64 v[108:109], v[92:93], 1, s[0:1]
	v_add_u32_e32 v92, 0xc00, v90
	v_cndmask_b32_e64 v95, 0, 1.0, vcc
	v_cmp_eq_u32_e32 vcc, 56, v126
	s_nop 7
	s_mov_b32 s54, 62
	s_nop 0
	v_readlane_b32 s4, v62, s54
	s_nop 1
	v_fma_f32 v3, -s4, v89, v3
	s_mov_b32 s55, 61
	v_cndmask_b32_e64 v181, 0, 1.0, vcc
	v_cmp_eq_u32_e32 vcc, 55, v126
	v_add_f32_e32 v88, 0, v3
	s_nop 0
	v_readlane_b32 s4, v66, s55
	s_nop 1
	v_fma_f32 v4, -s4, v88, v4
	v_ashrrev_i32_e32 v101, 31, v100
	v_cndmask_b32_e64 v11, 0, 1.0, vcc
	v_cmp_eq_u32_e32 vcc, 54, v126
	s_nop 0
	v_readlane_b32 s4, v62, s55
	s_nop 1
	v_fma_f32 v4, -s4, v89, v4
	v_lshl_add_u64 v[106:107], v[100:101], 1, s[0:1]
	v_ashrrev_i32_e32 v93, 31, v92
	v_cndmask_b32_e64 v97, 0, 1.0, vcc
	v_cmp_eq_u32_e32 vcc, 53, v126
	s_mov_b32 s56, 60
	v_lshl_add_u64 v[102:103], v[92:93], 1, s[0:1]
	v_cndmask_b32_e64 v13, 0, 1.0, vcc
	v_cmp_eq_u32_e32 vcc, 52, v126
	v_mov_b32_e32 v93, v123
	v_mov_b32_e32 v92, v123
	v_cndmask_b32_e64 v105, 0, 1.0, vcc
	v_cmp_eq_u32_e32 vcc, 51, v126
	s_mov_b32 s57, 59
	s_mov_b32 s53, 26
	v_cndmask_b32_e64 v17, 0, 1.0, vcc
	v_cmp_eq_u32_e32 vcc, 50, v126
	s_mov_b32 s58, 58
	v_mov_b32_e32 v94, v123
	v_cndmask_b32_e64 v111, 0, 1.0, vcc
	v_cmp_eq_u32_e32 vcc, 49, v126
	s_mov_b32 s52, 25
	s_mov_b32 s59, 57
	v_cndmask_b32_e64 v23, 0, 1.0, vcc
	v_cmp_eq_u32_e32 vcc, 48, v126
	v_mul_f32_e32 v10, 0x3fb8aa3b, v166
	v_mov_b32_e32 v180, v123
	v_cndmask_b32_e64 v115, 0, 1.0, vcc
	v_cmp_eq_u32_e32 vcc, 47, v126
	v_exp_f32_e32 v10, v10
	s_mov_b32 s51, 24
	v_cndmask_b32_e64 v27, 0, 1.0, vcc
	v_cmp_eq_u32_e32 vcc, 46, v126
	s_mov_b32 s60, 56
	v_mul_f32_e32 v210, v193, v10
	v_cndmask_b32_e64 v117, 0, 1.0, vcc
	v_cmp_eq_u32_e32 vcc, 45, v126
	v_mov_b32_e32 v10, v123
	s_mov_b32 s70, 23
	v_cndmask_b32_e64 v31, 0, 1.0, vcc
	v_cmp_eq_u32_e32 vcc, 44, v126
	s_mov_b32 s61, 55
	v_mov_b32_e32 v96, v123
	v_cndmask_b32_e64 v119, 0, 1.0, vcc
	v_cmp_eq_u32_e32 vcc, 43, v126
	s_mov_b32 s62, 54
	s_mov_b32 s71, 22
	v_cndmask_b32_e64 v33, 0, 1.0, vcc
	v_cmp_eq_u32_e32 vcc, 42, v126
	v_mov_b32_e32 v12, v123
	s_mov_b32 s63, 53
	v_cndmask_b32_e64 v129, 0, 1.0, vcc
	v_cmp_eq_u32_e32 vcc, 41, v126
	s_mov_b32 s72, 21
	v_mov_b32_e32 v104, v123
	v_cndmask_b32_e64 v65, 0, 1.0, vcc
	v_cmp_eq_u32_e32 vcc, 40, v126
	s_mov_b32 s73, 20
	v_mov_b32_e32 v16, v123
	v_cndmask_b32_e64 v131, 0, 1.0, vcc
	v_cmp_eq_u32_e32 vcc, 39, v126
	s_mov_b32 s64, 51
	s_mov_b32 s50, 19
	v_cndmask_b32_e64 v69, 0, 1.0, vcc
	v_cmp_eq_u32_e32 vcc, 38, v126
	v_mov_b32_e32 v110, v123
	s_mov_b32 s49, 18
	v_cndmask_b32_e64 v133, 0, 1.0, vcc
	v_cmp_eq_u32_e32 vcc, 37, v126
	s_mov_b32 s65, 50
	v_mov_b32_e32 v22, v123
	v_cndmask_b32_e64 v73, 0, 1.0, vcc
	v_cmp_eq_u32_e32 vcc, 36, v126
	s_mov_b32 s48, 17
	v_mov_b32_e32 v114, v123
	v_cndmask_b32_e64 v135, 0, 1.0, vcc
	v_cmp_eq_u32_e32 vcc, 35, v126
	s_mov_b32 s47, 16
	v_mov_b32_e32 v26, v123
	v_cndmask_b32_e64 v77, 0, 1.0, vcc
	v_cmp_eq_u32_e32 vcc, 34, v126
	s_mov_b32 s45, 15
	s_mov_b32 s66, 47
	v_cndmask_b32_e64 v137, 0, 1.0, vcc
	v_cmp_eq_u32_e32 vcc, 33, v126
	v_mov_b32_e32 v116, v123
	s_mov_b32 s39, 14
	v_cndmask_b32_e64 v81, 0, 1.0, vcc
	v_cmp_eq_u32_e32 vcc, 32, v126
	v_mov_b32_e32 v30, v123
	s_mov_b32 s38, 13
	v_cndmask_b32_e64 v139, 0, 1.0, vcc
	v_cmp_eq_u32_e32 vcc, 31, v126
	v_mov_b32_e32 v118, v123
	s_mov_b32 s43, 12
	v_cndmask_b32_e64 v153, 0, 1.0, vcc
	v_cmp_eq_u32_e32 vcc, 30, v126
	v_mov_b32_e32 v32, v123
	s_mov_b32 s67, 43
	v_cndmask_b32_e64 v141, 0, 1.0, vcc
	v_cmp_eq_u32_e32 vcc, 29, v126
	s_mov_b32 s42, 11
	v_mov_b32_e32 v128, v123
	v_cndmask_b32_e64 v159, 0, 1.0, vcc
	v_cmp_eq_u32_e32 vcc, 28, v126
	s_mov_b32 s46, 10
	s_lshl_b32 s4, s20, 4
	v_cndmask_b32_e64 v143, 0, 1.0, vcc
	v_cmp_eq_u32_e32 vcc, 27, v126
	v_mov_b32_e32 v64, v123
	s_or_b32 s4, s37, s4
	v_cndmask_b32_e64 v167, 0, 1.0, vcc
	v_cmp_eq_u32_e32 vcc, 26, v126
	s_mov_b32 s37, 9
	v_mov_b32_e32 v130, v123
	v_cndmask_b32_e64 v145, 0, 1.0, vcc
	v_cmp_eq_u32_e32 vcc, 25, v126
	s_mov_b32 s40, 8
	v_mov_b32_e32 v68, v123
	v_cndmask_b32_e64 v171, 0, 1.0, vcc
	v_cmp_eq_u32_e32 vcc, 24, v126
	s_mov_b32 s44, 7
	s_mov_b32 s68, 39
	v_cndmask_b32_e64 v147, 0, 1.0, vcc
	v_cmp_eq_u32_e32 vcc, 23, v126
	v_mov_b32_e32 v132, v123
	v_mov_b32_e32 v72, v123
	v_cndmask_b32_e64 v175, 0, 1.0, vcc
	v_cmp_eq_u32_e32 vcc, 22, v126
	v_mov_b32_e32 v134, v123
	v_mov_b32_e32 v76, v123
	v_cndmask_b32_e64 v149, 0, 1.0, vcc
	v_cmp_eq_u32_e32 vcc, 21, v126
	s_mov_b32 s69, 35
	s_mov_b32 s12, 3
	v_cndmask_b32_e64 v179, 0, 1.0, vcc
	v_cmp_eq_u32_e32 vcc, 20, v126
	v_mov_b32_e32 v136, v123
	v_mov_b32_e32 v80, v123
	v_cndmask_b32_e64 v151, 0, 1.0, vcc
	v_cmp_eq_u32_e32 vcc, 19, v126
	v_mov_b32_e32 v138, v123
	v_mov_b32_e32 v152, v123
	v_cndmask_b32_e64 v177, 0, 1.0, vcc
	v_cmp_eq_u32_e32 vcc, 18, v126
	s_mov_b32 s41, 31
	s_mov_b32 s20, 63
	v_cndmask_b32_e64 v157, 0, 1.0, vcc
	v_cmp_eq_u32_e32 vcc, 17, v126
	v_mov_b32_e32 v158, v123
	v_mov_b32_e32 v166, v123
	v_cndmask_b32_e64 v173, 0, 1.0, vcc
	v_cmp_eq_u32_e32 vcc, 16, v126
	v_mov_b32_e32 v170, v123
	v_mov_b32_e32 v174, v123
	v_cndmask_b32_e64 v165, 0, 1.0, vcc
	v_cmp_eq_u32_e32 vcc, 15, v126
	v_mov_b32_e32 v148, v123
	v_mov_b32_e32 v178, v123
	v_cndmask_b32_e64 v169, 0, 1.0, vcc
	v_cmp_eq_u32_e32 vcc, 14, v126
	v_mov_b32_e32 v150, v123
	v_mov_b32_e32 v176, v123
	v_cndmask_b32_e64 v163, 0, 1.0, vcc
	v_cmp_eq_u32_e32 vcc, 13, v126
	v_mov_b32_e32 v156, v123
	v_mov_b32_e32 v172, v123
	v_cndmask_b32_e64 v161, 0, 1.0, vcc
	v_cmp_eq_u32_e32 vcc, 12, v126
	v_mov_b32_e32 v164, v123
	v_mov_b32_e32 v168, v123
	v_cndmask_b32_e64 v155, 0, 1.0, vcc
	v_cmp_eq_u32_e32 vcc, 11, v126
	v_mov_b32_e32 v162, v123
	v_mov_b32_e32 v160, v123
	v_cndmask_b32_e64 v85, 0, 1.0, vcc
	v_cmp_eq_u32_e32 vcc, 10, v126
	v_mov_b32_e32 v154, v123
	s_ashr_i32 s5, s4, 31
	v_cndmask_b32_e64 v83, 0, 1.0, vcc
	v_cmp_eq_u32_e32 vcc, 9, v126
	s_nop 1
	v_cndmask_b32_e64 v79, 0, 1.0, vcc
	v_cmp_eq_u32_e32 vcc, 8, v126
	s_nop 1
	v_cndmask_b32_e64 v75, 0, 1.0, vcc
	v_cmp_eq_u32_e32 vcc, 7, v126
	s_nop 1
	v_cndmask_b32_e64 v71, 0, 1.0, vcc
	v_cmp_eq_u32_e32 vcc, 6, v126
	s_nop 1
	v_cndmask_b32_e64 v67, 0, 1.0, vcc
	v_cmp_eq_u32_e32 vcc, 5, v126
	s_nop 1
	v_cndmask_b32_e64 v63, 0, 1.0, vcc
	v_cmp_eq_u32_e32 vcc, 4, v126
	s_nop 1
	v_cndmask_b32_e64 v29, 0, 1.0, vcc
	v_cmp_eq_u32_e32 vcc, 3, v126
	s_nop 1
	v_cndmask_b32_e64 v25, 0, 1.0, vcc
	v_cmp_eq_u32_e32 vcc, 2, v126
	s_nop 1
	v_cndmask_b32_e64 v15, 0, 1.0, vcc
	v_cmp_eq_u32_e32 vcc, 1, v126
	s_nop 1
	v_cndmask_b32_e64 v7, 0, 1.0, vcc
	v_cmp_eq_u32_e32 vcc, 0, v126
	v_lshl_add_u64 v[126:127], v[90:91], 1, s[0:1]
	v_add_u32_e32 v90, 0x1c00, v90
	v_ashrrev_i32_e32 v91, 31, v90
	v_lshl_add_u64 v[100:101], v[90:91], 1, s[0:1]
	v_add_f32_e32 v91, 0, v4
	s_nop 0
	v_readlane_b32 s6, v70, s56
	s_nop 1
	v_fma_f32 v8, -s6, v91, v8
	v_mov_b32_e32 v4, v123
	s_nop 0
	v_readlane_b32 s6, v66, s56
	s_nop 1
	v_fma_f32 v8, -s6, v88, v8
	v_cndmask_b32_e64 v3, 0, 1.0, vcc
	s_nop 0
	v_readlane_b32 s6, v62, s56
	s_nop 1
	v_fma_f32 v8, -s6, v89, v8
	s_nop 0
	v_add_f32_e32 v90, 0, v8
	s_nop 0
	v_readlane_b32 s6, v14, s57
	v_readlane_b32 s7, v70, s57
	v_readlane_b32 s8, v66, s57
	v_readlane_b32 s9, v62, s57
	v_fma_f32 v5, -s6, v90, v5
	v_fma_f32 v93, -s7, v91, v93
	v_fma_f32 v92, -s8, v88, v92
	v_fma_f32 v4, -s9, v89, v4
	v_mov_b32_e32 v8, v123
	v_pk_add_f32 v[4:5], v[92:93], v[4:5]
	v_mov_b32_e32 v93, v123
	v_mov_b32_e32 v92, v123
	v_pk_add_f32 v[4:5], v[4:5], v[4:5] op_sel:[0,1] op_sel_hi:[1,0]
	s_nop 0
	s_nop 0
	v_readlane_b32 s6, v62, s53
	v_readlane_b32 s7, v14, s58
	v_readlane_b32 s8, v70, s58
	v_readlane_b32 s9, v66, s58
	v_fma_f32 v9, -s6, v4, v9
	v_fma_f32 v93, -s7, v90, v93
	v_fma_f32 v92, -s8, v91, v92
	v_fma_f32 v8, -s9, v88, v8
	s_nop 0
	s_nop 0
	v_readlane_b32 s6, v62, s58
	s_nop 1
	v_fma_f32 v9, -s6, v89, v9
	s_nop 0
	v_pk_add_f32 v[8:9], v[92:93], v[8:9]
	s_nop 0
	v_pk_add_f32 v[92:93], v[8:9], v[8:9] op_sel:[0,1] op_sel_hi:[1,0]
	v_mov_b32_e32 v9, v123
	v_mov_b32_e32 v8, v123
	s_nop 0
	v_readlane_b32 s6, v66, s52
	v_readlane_b32 s7, v62, s52
	v_readlane_b32 s8, v14, s59
	v_readlane_b32 s9, v70, s59
	v_fma_f32 v95, -s6, v92, v95
	v_fma_f32 v9, -s7, v4, v9
	v_fma_f32 v8, -s8, v90, v8
	v_fma_f32 v94, -s9, v91, v94
	v_mov_b32_e32 v93, v4
	s_nop 0
	v_readlane_b32 s6, v66, s59
	s_nop 1
	v_fma_f32 v95, -s6, v88, v95
	s_nop 0
	s_nop 0
	v_readlane_b32 s6, v62, s59
	s_nop 1
	v_fma_f32 v95, -s6, v89, v95
	s_nop 0
	v_pk_add_f32 v[8:9], v[8:9], v[94:95]
	v_mov_b32_e32 v95, v123
	v_mov_b32_e32 v94, v123
	v_pk_add_f32 v[8:9], v[8:9], v[8:9] op_sel:[0,1] op_sel_hi:[1,0]
	s_nop 0
	s_nop 0
	v_readlane_b32 s6, v70, s51
	v_readlane_b32 s7, v66, s51
	v_readlane_b32 s8, v62, s51
	v_readlane_b32 s9, v14, s60
	v_fma_f32 v181, -s6, v8, v181
	v_fma_f32 v95, -s7, v92, v95
	v_fma_f32 v94, -s8, v4, v94
	v_fma_f32 v180, -s9, v90, v180
	s_nop 0
	s_nop 0
	v_readlane_b32 s6, v70, s60
	s_nop 1
	v_fma_f32 v181, -s6, v91, v181
	s_nop 0
	s_nop 0
	v_readlane_b32 s6, v66, s60
	s_nop 1
	v_fma_f32 v181, -s6, v88, v181
	s_nop 0
	s_nop 0
	v_readlane_b32 s6, v62, s60
	s_nop 1
	v_fma_f32 v181, -s6, v89, v181
	s_nop 0
	v_pk_add_f32 v[94:95], v[94:95], v[180:181]
	v_mov_b32_e32 v181, v123
	v_mov_b32_e32 v180, v123
	v_pk_add_f32 v[94:95], v[94:95], v[94:95] op_sel:[0,1] op_sel_hi:[1,0]
	s_nop 0
	s_nop 0
	v_readlane_b32 s6, v14, s70
	v_readlane_b32 s7, v70, s70
	v_readlane_b32 s8, v66, s70
	v_readlane_b32 s9, v62, s70
	v_fma_f32 v11, -s6, v94, v11
	v_fma_f32 v181, -s7, v8, v181
	v_fma_f32 v180, -s8, v92, v180
	v_fma_f32 v10, -s9, v4, v10
	v_mov_b32_e32 v95, v8
	s_nop 0
	v_readlane_b32 s6, v14, s61
	v_readlane_b32 s7, v70, s61
	v_readlane_b32 s8, v66, s61
	v_readlane_b32 s9, v62, s61
	v_fma_f32 v11, -s6, v90, v11
	v_fma_f32 v181, -s7, v91, v181
	v_fma_f32 v180, -s8, v88, v180
	v_fma_f32 v10, -s9, v89, v10
	s_nop 0
	v_pk_add_f32 v[10:11], v[180:181], v[10:11]
	v_mov_b32_e32 v181, v123
	v_mov_b32_e32 v180, v123
	v_pk_add_f32 v[10:11], v[10:11], v[10:11] op_sel:[0,1] op_sel_hi:[1,0]
	s_nop 0
	s_nop 0
	v_readlane_b32 s6, v74, s62
	v_readlane_b32 s7, v14, s71
	v_readlane_b32 s8, v70, s71
	v_readlane_b32 s9, v66, s71
	v_fma_f32 v97, -s6, v10, v97
	v_fma_f32 v181, -s7, v94, v181
	v_fma_f32 v180, -s8, v8, v180
	v_fma_f32 v96, -s9, v92, v96
	s_nop 0
	s_nop 0
	v_readlane_b32 s6, v62, s71
	v_readlane_b32 s7, v14, s62
	v_readlane_b32 s8, v70, s62
	v_readlane_b32 s9, v66, s62
	v_fma_f32 v97, -s6, v4, v97
	v_fma_f32 v181, -s7, v90, v181
	v_fma_f32 v180, -s8, v91, v180
	v_fma_f32 v96, -s9, v88, v96
	s_nop 0
	s_nop 0
	v_readlane_b32 s6, v62, s62
	s_nop 1
	v_fma_f32 v97, -s6, v89, v97
	s_nop 0
	v_pk_add_f32 v[96:97], v[180:181], v[96:97]
	v_mov_b32_e32 v181, v123
	v_mov_b32_e32 v180, v123
	v_pk_add_f32 v[96:97], v[96:97], v[96:97] op_sel:[0,1] op_sel_hi:[1,0]
	s_nop 0
	s_nop 0
	v_readlane_b32 s6, v28, s63
	v_readlane_b32 s7, v74, s63
	v_readlane_b32 s8, v14, s72
	v_readlane_b32 s9, v70, s72
	v_fma_f32 v13, -s6, v96, v13
	v_fma_f32 v181, -s7, v10, v181
	v_fma_f32 v180, -s8, v94, v180
	v_fma_f32 v12, -s9, v8, v12
	v_mov_b32_e32 v97, v10
	s_nop 0
	v_readlane_b32 s6, v66, s72
	v_readlane_b32 s7, v62, s72
	v_readlane_b32 s8, v14, s63
	v_readlane_b32 s9, v70, s63
	v_fma_f32 v13, -s6, v92, v13
	v_fma_f32 v181, -s7, v4, v181
	v_fma_f32 v180, -s8, v90, v180
	v_fma_f32 v12, -s9, v91, v12
	s_nop 0
	s_nop 0
	v_readlane_b32 s6, v66, s63
	s_nop 1
	v_fma_f32 v13, -s6, v88, v13
	s_nop 0
	s_nop 0
	v_readlane_b32 s6, v62, s63
	s_nop 1
	v_fma_f32 v13, -s6, v89, v13
	s_nop 0
	v_pk_add_f32 v[12:13], v[180:181], v[12:13]
	v_mov_b32_e32 v181, v123
	v_mov_b32_e32 v180, v123
	v_pk_add_f32 v[12:13], v[12:13], v[12:13] op_sel:[0,1] op_sel_hi:[1,0]
	s_nop 0
	s_nop 0
	v_readlane_b32 s6, v78, s22
	v_readlane_b32 s7, v28, s22
	v_readlane_b32 s8, v74, s22
	v_readlane_b32 s9, v14, s73
	v_fma_f32 v105, -s6, v12, v105
	v_fma_f32 v181, -s7, v96, v181
	v_fma_f32 v180, -s8, v10, v180
	v_fma_f32 v104, -s9, v94, v104
	s_nop 0
	s_nop 0
	v_readlane_b32 s6, v70, s73
	v_readlane_b32 s7, v66, s73
	v_readlane_b32 s8, v62, s73
	v_readlane_b32 s9, v14, s22
	v_fma_f32 v105, -s6, v8, v105
	v_fma_f32 v181, -s7, v92, v181
	v_fma_f32 v180, -s8, v4, v180
	v_fma_f32 v104, -s9, v90, v104
	s_nop 0
	s_nop 0
	v_readlane_b32 s6, v70, s22
	s_nop 1
	v_fma_f32 v105, -s6, v91, v105
	s_nop 0
	s_nop 0
	v_readlane_b32 s6, v66, s22
	s_nop 1
	v_fma_f32 v105, -s6, v88, v105
	s_nop 0
	s_nop 0
	v_readlane_b32 s6, v62, s22
	s_nop 1
	v_fma_f32 v105, -s6, v89, v105
	s_nop 0
	v_pk_add_f32 v[104:105], v[180:181], v[104:105]
	v_mov_b32_e32 v181, v123
	v_mov_b32_e32 v180, v123
	v_pk_add_f32 v[104:105], v[104:105], v[104:105] op_sel:[0,1] op_sel_hi:[1,0]
	s_nop 0
	s_nop 0
	v_readlane_b32 s6, v82, s64
	v_readlane_b32 s7, v78, s64
	v_readlane_b32 s8, v28, s64
	v_readlane_b32 s9, v74, s64
	v_fma_f32 v17, -s6, v104, v17
	v_fma_f32 v181, -s7, v12, v181
	v_fma_f32 v180, -s8, v96, v180
	v_fma_f32 v16, -s9, v10, v16
	v_mov_b32_e32 v105, v12
	s_nop 0
	v_readlane_b32 s6, v14, s50
	v_readlane_b32 s7, v70, s50
	v_readlane_b32 s8, v66, s50
	v_readlane_b32 s9, v62, s50
	v_fma_f32 v17, -s6, v94, v17
	v_fma_f32 v181, -s7, v8, v181
	v_fma_f32 v180, -s8, v92, v180
	v_fma_f32 v16, -s9, v4, v16
	s_nop 0
	s_nop 0
	v_readlane_b32 s6, v14, s64
	v_readlane_b32 s7, v70, s64
	v_readlane_b32 s8, v66, s64
	v_readlane_b32 s9, v62, s64
	v_fma_f32 v17, -s6, v90, v17
	v_fma_f32 v181, -s7, v91, v181
	v_fma_f32 v180, -s8, v88, v180
	v_fma_f32 v16, -s9, v89, v16
	s_nop 0
	v_pk_add_f32 v[16:17], v[180:181], v[16:17]
	v_mov_b32_e32 v181, v123
	v_mov_b32_e32 v180, v123
	v_pk_add_f32 v[16:17], v[16:17], v[16:17] op_sel:[0,1] op_sel_hi:[1,0]
	s_nop 0
	s_nop 0
	v_readlane_b32 s6, v74, s49
	v_readlane_b32 s7, v82, s65
	v_readlane_b32 s8, v78, s65
	v_readlane_b32 s9, v28, s65
	v_fma_f32 v111, -s6, v16, v111
	v_fma_f32 v181, -s7, v104, v181
	v_fma_f32 v180, -s8, v12, v180
	v_fma_f32 v110, -s9, v96, v110
	s_nop 0
	s_nop 0
	v_readlane_b32 s6, v74, s65
	v_readlane_b32 s7, v14, s49
	v_readlane_b32 s8, v70, s49
	v_readlane_b32 s9, v66, s49
	v_fma_f32 v111, -s6, v10, v111
	v_fma_f32 v181, -s7, v94, v181
	v_fma_f32 v180, -s8, v8, v180
	v_fma_f32 v110, -s9, v92, v110
	s_nop 0
	s_nop 0
	v_readlane_b32 s6, v62, s49
	v_readlane_b32 s7, v14, s65
	v_readlane_b32 s8, v70, s65
	v_readlane_b32 s9, v66, s65
	v_fma_f32 v111, -s6, v4, v111
	v_fma_f32 v181, -s7, v90, v181
	v_fma_f32 v180, -s8, v91, v180
	v_fma_f32 v110, -s9, v88, v110
	s_nop 0
	s_nop 0
	v_readlane_b32 s6, v62, s65
	s_nop 1
	v_fma_f32 v111, -s6, v89, v111
	s_nop 0
	v_pk_add_f32 v[110:111], v[180:181], v[110:111]
	v_mov_b32_e32 v181, v123
	v_mov_b32_e32 v180, v123
	v_pk_add_f32 v[110:111], v[110:111], v[110:111] op_sel:[0,1] op_sel_hi:[1,0]
	s_nop 0
	s_nop 0
	v_readlane_b32 s6, v28, s48
	v_readlane_b32 s7, v74, s48
	v_readlane_b32 s8, v82, s21
	v_readlane_b32 s9, v78, s21
	v_fma_f32 v23, -s6, v110, v23
	v_fma_f32 v181, -s7, v16, v181
	v_fma_f32 v180, -s8, v104, v180
	v_fma_f32 v22, -s9, v12, v22
	v_mov_b32_e32 v111, v16
	s_nop 0
	v_readlane_b32 s6, v28, s21
	v_readlane_b32 s7, v74, s21
	v_readlane_b32 s8, v14, s48
	v_readlane_b32 s9, v70, s48
	v_fma_f32 v23, -s6, v96, v23
	v_fma_f32 v181, -s7, v10, v181
	v_fma_f32 v180, -s8, v94, v180
	v_fma_f32 v22, -s9, v8, v22
	s_nop 0
	s_nop 0
	v_readlane_b32 s6, v66, s48
	v_readlane_b32 s7, v62, s48
	v_readlane_b32 s8, v14, s21
	v_readlane_b32 s9, v70, s21
	v_fma_f32 v23, -s6, v92, v23
	v_fma_f32 v181, -s7, v4, v181
	v_fma_f32 v180, -s8, v90, v180
	v_fma_f32 v22, -s9, v91, v22
	s_nop 0
	s_nop 0
	v_readlane_b32 s6, v66, s21
	s_nop 1
	v_fma_f32 v23, -s6, v88, v23
	s_nop 0
	s_nop 0
	v_readlane_b32 s6, v62, s21
	s_nop 1
	v_fma_f32 v23, -s6, v89, v23
	s_nop 0
	v_pk_add_f32 v[22:23], v[180:181], v[22:23]
	v_mov_b32_e32 v181, v123
	v_mov_b32_e32 v180, v123
	v_pk_add_f32 v[22:23], v[22:23], v[22:23] op_sel:[0,1] op_sel_hi:[1,0]
	s_nop 0
	s_nop 0
	v_readlane_b32 s6, v78, s47
	v_readlane_b32 s7, v28, s47
	v_readlane_b32 s8, v74, s47
	v_readlane_b32 s9, v82, s34
	v_fma_f32 v115, -s6, v22, v115
	v_fma_f32 v181, -s7, v110, v181
	v_fma_f32 v180, -s8, v16, v180
	v_fma_f32 v114, -s9, v104, v114
	s_nop 0
	s_nop 0
	v_readlane_b32 s6, v78, s34
	v_readlane_b32 s7, v28, s34
	v_readlane_b32 s8, v74, s34
	v_readlane_b32 s9, v14, s47
	v_fma_f32 v115, -s6, v12, v115
	v_fma_f32 v181, -s7, v96, v181
	v_fma_f32 v180, -s8, v10, v180
	v_fma_f32 v114, -s9, v94, v114
	s_nop 0
	s_nop 0
	v_readlane_b32 s6, v70, s47
	v_readlane_b32 s7, v66, s47
	v_readlane_b32 s8, v62, s47
	v_readlane_b32 s9, v14, s34
	v_fma_f32 v115, -s6, v8, v115
	v_fma_f32 v181, -s7, v92, v181
	v_fma_f32 v180, -s8, v4, v180
	v_fma_f32 v114, -s9, v90, v114
	s_nop 0
	s_nop 0
	v_readlane_b32 s6, v70, s34
	s_nop 1
	v_fma_f32 v115, -s6, v91, v115
	s_nop 0
	s_nop 0
	v_readlane_b32 s6, v66, s34
	s_nop 1
	v_fma_f32 v115, -s6, v88, v115
	s_nop 0
	s_nop 0
	v_readlane_b32 s6, v62, s34
	s_nop 1
	v_fma_f32 v115, -s6, v89, v115
	s_nop 0
	v_pk_add_f32 v[114:115], v[180:181], v[114:115]
	v_mov_b32_e32 v181, v123
	v_mov_b32_e32 v180, v123
	v_pk_add_f32 v[114:115], v[114:115], v[114:115] op_sel:[0,1] op_sel_hi:[1,0]
	s_nop 0
	s_nop 0
	v_readlane_b32 s6, v82, s45
	v_readlane_b32 s7, v78, s45
	v_readlane_b32 s8, v28, s45
	v_readlane_b32 s9, v74, s45
	v_fma_f32 v27, -s6, v114, v27
	v_fma_f32 v181, -s7, v22, v181
	v_fma_f32 v180, -s8, v110, v180
	v_fma_f32 v26, -s9, v16, v26
	v_mov_b32_e32 v115, v22
	s_nop 0
	v_readlane_b32 s6, v82, s66
	v_readlane_b32 s7, v78, s66
	v_readlane_b32 s8, v28, s66
	v_readlane_b32 s9, v74, s66
	v_fma_f32 v27, -s6, v104, v27
	v_fma_f32 v181, -s7, v12, v181
	v_fma_f32 v180, -s8, v96, v180
	v_fma_f32 v26, -s9, v10, v26
	s_nop 0
	s_nop 0
	v_readlane_b32 s6, v14, s45
	v_readlane_b32 s7, v70, s45
	v_readlane_b32 s8, v66, s45
	v_readlane_b32 s9, v62, s45
	v_fma_f32 v27, -s6, v94, v27
	v_fma_f32 v181, -s7, v8, v181
	v_fma_f32 v180, -s8, v92, v180
	v_fma_f32 v26, -s9, v4, v26
	s_nop 0
	s_nop 0
	v_readlane_b32 s6, v14, s66
	v_readlane_b32 s7, v70, s66
	v_readlane_b32 s8, v66, s66
	v_readlane_b32 s9, v62, s66
	v_fma_f32 v27, -s6, v90, v27
	v_fma_f32 v181, -s7, v91, v181
	v_fma_f32 v180, -s8, v88, v180
	v_fma_f32 v26, -s9, v89, v26
	s_nop 0
	v_pk_add_f32 v[26:27], v[180:181], v[26:27]
	v_mov_b32_e32 v181, v123
	v_mov_b32_e32 v180, v123
	v_pk_add_f32 v[26:27], v[26:27], v[26:27] op_sel:[0,1] op_sel_hi:[1,0]
	s_nop 0
	s_nop 0
	v_readlane_b32 s6, v84, s14
	v_readlane_b32 s7, v82, s39
	v_readlane_b32 s8, v78, s39
	v_readlane_b32 s9, v28, s39
	v_fma_f32 v117, -s6, v26, v117
	v_fma_f32 v181, -s7, v114, v181
	v_fma_f32 v180, -s8, v22, v180
	v_fma_f32 v116, -s9, v110, v116
	s_nop 0
	s_nop 0
	v_readlane_b32 s6, v74, s39
	v_readlane_b32 s7, v82, s14
	v_readlane_b32 s8, v78, s14
	v_readlane_b32 s9, v28, s14
	v_fma_f32 v117, -s6, v16, v117
	v_fma_f32 v181, -s7, v104, v181
	v_fma_f32 v180, -s8, v12, v180
	v_fma_f32 v116, -s9, v96, v116
	s_nop 0
	s_nop 0
	v_readlane_b32 s6, v74, s14
	v_readlane_b32 s7, v14, s39
	v_readlane_b32 s8, v70, s39
	v_readlane_b32 s9, v66, s39
	v_fma_f32 v117, -s6, v10, v117
	v_fma_f32 v181, -s7, v94, v181
	v_fma_f32 v180, -s8, v8, v180
	v_fma_f32 v116, -s9, v92, v116
	s_nop 0
	s_nop 0
	v_readlane_b32 s6, v62, s39
	v_readlane_b32 s7, v14, s14
	v_readlane_b32 s8, v70, s14
	v_readlane_b32 s9, v66, s14
	v_fma_f32 v117, -s6, v4, v117
	v_fma_f32 v181, -s7, v90, v181
	v_fma_f32 v180, -s8, v91, v180
	v_fma_f32 v116, -s9, v88, v116
	s_nop 0
	s_nop 0
	v_readlane_b32 s6, v62, s14
	s_nop 1
	v_fma_f32 v117, -s6, v89, v117
	s_nop 0
	v_pk_add_f32 v[116:117], v[180:181], v[116:117]
	v_mov_b32_e32 v181, v123
	v_mov_b32_e32 v180, v123
	v_pk_add_f32 v[116:117], v[116:117], v[116:117] op_sel:[0,1] op_sel_hi:[1,0]
	s_nop 0
	s_nop 0
	v_readlane_b32 s6, v24, s11
	v_readlane_b32 s7, v84, s11
	v_readlane_b32 s8, v82, s38
	v_readlane_b32 s9, v78, s38
	v_fma_f32 v31, -s6, v116, v31
	v_fma_f32 v181, -s7, v26, v181
	v_fma_f32 v180, -s8, v114, v180
	v_fma_f32 v30, -s9, v22, v30
	v_mov_b32_e32 v117, v26
	s_nop 0
	v_readlane_b32 s6, v28, s38
	v_readlane_b32 s7, v74, s38
	v_readlane_b32 s8, v82, s11
	v_readlane_b32 s9, v78, s11
	v_fma_f32 v31, -s6, v110, v31
	v_fma_f32 v181, -s7, v16, v181
	v_fma_f32 v180, -s8, v104, v180
	v_fma_f32 v30, -s9, v12, v30
	s_nop 0
	s_nop 0
	v_readlane_b32 s6, v28, s11
	v_readlane_b32 s7, v74, s11
	v_readlane_b32 s8, v14, s38
	v_readlane_b32 s9, v70, s38
	v_fma_f32 v31, -s6, v96, v31
	v_fma_f32 v181, -s7, v10, v181
	v_fma_f32 v180, -s8, v94, v180
	v_fma_f32 v30, -s9, v8, v30
	s_nop 0
	s_nop 0
	v_readlane_b32 s6, v66, s38
	v_readlane_b32 s7, v62, s38
	v_readlane_b32 s8, v14, s11
	v_readlane_b32 s9, v70, s11
	v_fma_f32 v31, -s6, v92, v31
	v_fma_f32 v181, -s7, v4, v181
	v_fma_f32 v180, -s8, v90, v180
	v_fma_f32 v30, -s9, v91, v30
	s_nop 0
	s_nop 0
	v_readlane_b32 s6, v66, s11
	s_nop 1
	v_fma_f32 v31, -s6, v88, v31
	s_nop 0
	s_nop 0
	v_readlane_b32 s6, v62, s11
	s_nop 1
	v_fma_f32 v31, -s6, v89, v31
	s_nop 0
	v_pk_add_f32 v[30:31], v[180:181], v[30:31]
	v_mov_b32_e32 v181, v123
	v_mov_b32_e32 v180, v123
	v_pk_add_f32 v[30:31], v[30:31], v[30:31] op_sel:[0,1] op_sel_hi:[1,0]
	s_nop 0
	s_nop 0
	v_readlane_b32 s6, v142, s27
	v_readlane_b32 s7, v24, s27
	v_readlane_b32 s8, v84, s27
	v_readlane_b32 s9, v82, s43
	v_fma_f32 v119, -s6, v30, v119
	v_fma_f32 v181, -s7, v116, v181
	v_fma_f32 v180, -s8, v26, v180
	v_fma_f32 v118, -s9, v114, v118
	s_nop 0
	s_nop 0
	v_readlane_b32 s6, v78, s43
	v_readlane_b32 s7, v28, s43
	v_readlane_b32 s8, v74, s43
	v_readlane_b32 s9, v82, s27
	v_fma_f32 v119, -s6, v22, v119
	v_fma_f32 v181, -s7, v110, v181
	v_fma_f32 v180, -s8, v16, v180
	v_fma_f32 v118, -s9, v104, v118
	s_nop 0
	s_nop 0
	v_readlane_b32 s6, v78, s27
	v_readlane_b32 s7, v28, s27
	v_readlane_b32 s8, v74, s27
	v_readlane_b32 s9, v14, s43
	v_fma_f32 v119, -s6, v12, v119
	v_fma_f32 v181, -s7, v96, v181
	v_fma_f32 v180, -s8, v10, v180
	v_fma_f32 v118, -s9, v94, v118
	s_nop 0
	s_nop 0
	v_readlane_b32 s6, v70, s43
	v_readlane_b32 s7, v66, s43
	v_readlane_b32 s8, v62, s43
	v_readlane_b32 s9, v14, s27
	v_fma_f32 v119, -s6, v8, v119
	v_fma_f32 v181, -s7, v92, v181
	v_fma_f32 v180, -s8, v4, v180
	v_fma_f32 v118, -s9, v90, v118
	s_nop 0
	s_nop 0
	v_readlane_b32 s6, v70, s27
	s_nop 1
	v_fma_f32 v119, -s6, v91, v119
	s_nop 0
	s_nop 0
	v_readlane_b32 s6, v66, s27
	s_nop 1
	v_fma_f32 v119, -s6, v88, v119
	s_nop 0
	s_nop 0
	v_readlane_b32 s6, v62, s27
	s_nop 1
	v_fma_f32 v119, -s6, v89, v119
	s_nop 0
	v_pk_add_f32 v[118:119], v[180:181], v[118:119]
	v_mov_b32_e32 v181, v123
	v_mov_b32_e32 v180, v123
	v_pk_add_f32 v[118:119], v[118:119], v[118:119] op_sel:[0,1] op_sel_hi:[1,0]
	s_nop 0
	s_nop 0
	v_readlane_b32 s6, v6, s67
	v_readlane_b32 s7, v142, s67
	v_readlane_b32 s8, v24, s67
	v_readlane_b32 s9, v84, s67
	v_fma_f32 v33, -s6, v118, v33
	v_fma_f32 v181, -s7, v30, v181
	v_fma_f32 v180, -s8, v116, v180
	v_fma_f32 v32, -s9, v26, v32
	v_mov_b32_e32 v119, v30
	s_nop 0
	v_readlane_b32 s6, v82, s42
	v_readlane_b32 s7, v78, s42
	v_readlane_b32 s8, v28, s42
	v_readlane_b32 s9, v74, s42
	v_fma_f32 v33, -s6, v114, v33
	v_fma_f32 v181, -s7, v22, v181
	v_fma_f32 v180, -s8, v110, v180
	v_fma_f32 v32, -s9, v16, v32
	s_nop 0
	s_nop 0
	v_readlane_b32 s6, v82, s67
	v_readlane_b32 s7, v78, s67
	v_readlane_b32 s8, v28, s67
	v_readlane_b32 s9, v74, s67
	v_fma_f32 v33, -s6, v104, v33
	v_fma_f32 v181, -s7, v12, v181
	v_fma_f32 v180, -s8, v96, v180
	v_fma_f32 v32, -s9, v10, v32
	s_nop 0
	s_nop 0
	v_readlane_b32 s6, v14, s42
	v_readlane_b32 s7, v70, s42
	v_readlane_b32 s8, v66, s42
	v_readlane_b32 s9, v62, s42
	v_fma_f32 v33, -s6, v94, v33
	v_fma_f32 v181, -s7, v8, v181
	v_fma_f32 v180, -s8, v92, v180
	v_fma_f32 v32, -s9, v4, v32
	s_nop 0
	s_nop 0
	v_readlane_b32 s6, v14, s67
	v_readlane_b32 s7, v70, s67
	v_readlane_b32 s8, v66, s67
	v_readlane_b32 s9, v62, s67
	v_fma_f32 v33, -s6, v90, v33
	v_fma_f32 v181, -s7, v91, v181
	v_fma_f32 v180, -s8, v88, v180
	v_fma_f32 v32, -s9, v89, v32
	s_nop 0
	v_pk_add_f32 v[32:33], v[180:181], v[32:33]
	v_mov_b32_e32 v181, v123
	v_mov_b32_e32 v180, v123
	v_pk_add_f32 v[32:33], v[32:33], v[32:33] op_sel:[0,1] op_sel_hi:[1,0]
	s_nop 0
	s_nop 0
	v_readlane_b32 s6, v84, s46
	v_readlane_b32 s7, v6, s2
	v_readlane_b32 s8, v142, s2
	v_readlane_b32 s9, v24, s2
	v_fma_f32 v129, -s6, v32, v129
	v_fma_f32 v181, -s7, v118, v181
	v_fma_f32 v180, -s8, v30, v180
	v_fma_f32 v128, -s9, v116, v128
	s_nop 0
	s_nop 0
	v_readlane_b32 s6, v84, s2
	v_readlane_b32 s7, v82, s46
	v_readlane_b32 s8, v78, s46
	v_readlane_b32 s9, v28, s46
	v_fma_f32 v129, -s6, v26, v129
	v_fma_f32 v181, -s7, v114, v181
	v_fma_f32 v180, -s8, v22, v180
	v_fma_f32 v128, -s9, v110, v128
	s_nop 0
	s_nop 0
	v_readlane_b32 s6, v74, s46
	v_readlane_b32 s7, v82, s2
	v_readlane_b32 s8, v78, s2
	v_readlane_b32 s9, v28, s2
	v_fma_f32 v129, -s6, v16, v129
	v_fma_f32 v181, -s7, v104, v181
	v_fma_f32 v180, -s8, v12, v180
	v_fma_f32 v128, -s9, v96, v128
	s_nop 0
	s_nop 0
	v_readlane_b32 s6, v74, s2
	v_readlane_b32 s7, v14, s46
	v_readlane_b32 s8, v70, s46
	v_readlane_b32 s9, v66, s46
	v_fma_f32 v129, -s6, v10, v129
	v_fma_f32 v181, -s7, v94, v181
	v_fma_f32 v180, -s8, v8, v180
	v_fma_f32 v128, -s9, v92, v128
	s_nop 0
	s_nop 0
	v_readlane_b32 s6, v62, s46
	v_readlane_b32 s7, v14, s2
	v_readlane_b32 s8, v70, s2
	v_readlane_b32 s9, v66, s2
	v_fma_f32 v129, -s6, v4, v129
	v_fma_f32 v181, -s7, v90, v181
	v_fma_f32 v180, -s8, v91, v180
	v_fma_f32 v128, -s9, v88, v128
	s_nop 0
	s_nop 0
	v_readlane_b32 s6, v62, s2
	s_nop 1
	v_fma_f32 v129, -s6, v89, v129
	s_nop 0
	v_pk_add_f32 v[128:129], v[180:181], v[128:129]
	v_mov_b32_e32 v181, v123
	v_mov_b32_e32 v180, v123
	v_pk_add_f32 v[128:129], v[128:129], v[128:129] op_sel:[0,1] op_sel_hi:[1,0]
	s_nop 0
	s_nop 0
	v_readlane_b32 s6, v24, s37
	v_readlane_b32 s7, v84, s37
	v_readlane_b32 s8, v6, s18
	v_readlane_b32 s9, v142, s18
	v_fma_f32 v65, -s6, v128, v65
	v_fma_f32 v181, -s7, v32, v181
	v_fma_f32 v180, -s8, v118, v180
	v_fma_f32 v64, -s9, v30, v64
	v_mov_b32_e32 v129, v32
	s_nop 0
	v_readlane_b32 s6, v24, s18
	v_readlane_b32 s7, v84, s18
	v_readlane_b32 s8, v82, s37
	v_readlane_b32 s9, v78, s37
	v_fma_f32 v65, -s6, v116, v65
	v_fma_f32 v181, -s7, v26, v181
	v_fma_f32 v180, -s8, v114, v180
	v_fma_f32 v64, -s9, v22, v64
	s_nop 0
	s_nop 0
	v_readlane_b32 s6, v28, s37
	v_readlane_b32 s7, v74, s37
	v_readlane_b32 s8, v82, s18
	v_readlane_b32 s9, v78, s18
	v_fma_f32 v65, -s6, v110, v65
	v_fma_f32 v181, -s7, v16, v181
	v_fma_f32 v180, -s8, v104, v180
	v_fma_f32 v64, -s9, v12, v64
	s_nop 0
	s_nop 0
	v_readlane_b32 s6, v28, s18
	v_readlane_b32 s7, v74, s18
	v_readlane_b32 s8, v14, s37
	v_readlane_b32 s9, v70, s37
	v_fma_f32 v65, -s6, v96, v65
	v_fma_f32 v181, -s7, v10, v181
	v_fma_f32 v180, -s8, v94, v180
	v_fma_f32 v64, -s9, v8, v64
	s_nop 0
	s_nop 0
	v_readlane_b32 s6, v66, s37
	v_readlane_b32 s7, v62, s37
	v_readlane_b32 s8, v14, s18
	v_readlane_b32 s9, v70, s18
	v_fma_f32 v65, -s6, v92, v65
	v_fma_f32 v181, -s7, v4, v181
	v_fma_f32 v180, -s8, v90, v180
	v_fma_f32 v64, -s9, v91, v64
	s_nop 0
	s_nop 0
	v_readlane_b32 s6, v66, s18
	s_nop 1
	v_fma_f32 v65, -s6, v88, v65
	s_nop 0
	s_nop 0
	v_readlane_b32 s6, v62, s18
	s_nop 1
	v_fma_f32 v65, -s6, v89, v65
	s_nop 0
	v_pk_add_f32 v[64:65], v[180:181], v[64:65]
	v_mov_b32_e32 v181, v123
	v_mov_b32_e32 v180, v123
	v_pk_add_f32 v[64:65], v[64:65], v[64:65] op_sel:[0,1] op_sel_hi:[1,0]
	s_nop 0
	s_nop 0
	v_readlane_b32 s6, v142, s40
	v_readlane_b32 s7, v24, s40
	v_readlane_b32 s8, v84, s40
	v_readlane_b32 s9, v6, s19
	v_fma_f32 v131, -s6, v64, v131
	v_fma_f32 v181, -s7, v128, v181
	v_fma_f32 v180, -s8, v32, v180
	v_fma_f32 v130, -s9, v118, v130
	s_nop 0
	s_nop 0
	v_readlane_b32 s6, v142, s19
	v_readlane_b32 s7, v24, s19
	v_readlane_b32 s8, v84, s19
	v_readlane_b32 s9, v82, s40
	v_fma_f32 v131, -s6, v30, v131
	v_fma_f32 v181, -s7, v116, v181
	v_fma_f32 v180, -s8, v26, v180
	v_fma_f32 v130, -s9, v114, v130
	s_nop 0
	s_nop 0
	v_readlane_b32 s6, v78, s40
	v_readlane_b32 s7, v28, s40
	v_readlane_b32 s8, v74, s40
	v_readlane_b32 s9, v82, s19
	v_fma_f32 v131, -s6, v22, v131
	v_fma_f32 v181, -s7, v110, v181
	v_fma_f32 v180, -s8, v16, v180
	v_fma_f32 v130, -s9, v104, v130
	s_nop 0
	s_nop 0
	v_readlane_b32 s6, v78, s19
	v_readlane_b32 s7, v28, s19
	v_readlane_b32 s8, v74, s19
	v_readlane_b32 s9, v14, s40
	v_fma_f32 v131, -s6, v12, v131
	v_fma_f32 v181, -s7, v96, v181
	v_fma_f32 v180, -s8, v10, v180
	v_fma_f32 v130, -s9, v94, v130
	s_nop 0
	s_nop 0
	v_readlane_b32 s6, v70, s40
	v_readlane_b32 s7, v66, s40
	v_readlane_b32 s8, v62, s40
	v_readlane_b32 s9, v14, s19
	v_fma_f32 v131, -s6, v8, v131
	v_fma_f32 v181, -s7, v92, v181
	v_fma_f32 v180, -s8, v4, v180
	v_fma_f32 v130, -s9, v90, v130
	s_nop 0
	s_nop 0
	v_readlane_b32 s6, v70, s19
	s_nop 1
	v_fma_f32 v131, -s6, v91, v131
	s_nop 0
	s_nop 0
	v_readlane_b32 s6, v66, s19
	s_nop 1
	v_fma_f32 v131, -s6, v88, v131
	s_nop 0
	s_nop 0
	v_readlane_b32 s6, v62, s19
	s_nop 1
	v_fma_f32 v131, -s6, v89, v131
	s_nop 0
	v_pk_add_f32 v[130:131], v[180:181], v[130:131]
	v_mov_b32_e32 v181, v123
	v_mov_b32_e32 v180, v123
	v_pk_add_f32 v[130:131], v[130:131], v[130:131] op_sel:[0,1] op_sel_hi:[1,0]
	s_nop 0
	s_nop 0
	v_readlane_b32 s6, v6, s44
	v_readlane_b32 s7, v142, s44
	v_readlane_b32 s8, v24, s44
	v_readlane_b32 s9, v84, s44
	v_fma_f32 v69, -s6, v130, v69
	v_fma_f32 v181, -s7, v64, v181
	v_fma_f32 v180, -s8, v128, v180
	v_fma_f32 v68, -s9, v32, v68
	v_mov_b32_e32 v131, v64
	s_nop 0
	v_readlane_b32 s6, v6, s68
	v_readlane_b32 s7, v142, s68
	v_readlane_b32 s8, v24, s68
	v_readlane_b32 s9, v84, s68
	v_fma_f32 v69, -s6, v118, v69
	v_fma_f32 v181, -s7, v30, v181
	v_fma_f32 v180, -s8, v116, v180
	v_fma_f32 v68, -s9, v26, v68
	s_nop 0
	s_nop 0
	v_readlane_b32 s6, v82, s44
	v_readlane_b32 s7, v78, s44
	v_readlane_b32 s8, v28, s44
	v_readlane_b32 s9, v74, s44
	v_fma_f32 v69, -s6, v114, v69
	v_fma_f32 v181, -s7, v22, v181
	v_fma_f32 v180, -s8, v110, v180
	v_fma_f32 v68, -s9, v16, v68
	s_nop 0
	s_nop 0
	v_readlane_b32 s6, v82, s68
	v_readlane_b32 s7, v78, s68
	v_readlane_b32 s8, v28, s68
	v_readlane_b32 s9, v74, s68
	v_fma_f32 v69, -s6, v104, v69
	v_fma_f32 v181, -s7, v12, v181
	v_fma_f32 v180, -s8, v96, v180
	v_fma_f32 v68, -s9, v10, v68
	s_nop 0
	s_nop 0
	v_readlane_b32 s6, v14, s44
	v_readlane_b32 s7, v70, s44
	v_readlane_b32 s8, v66, s44
	v_readlane_b32 s9, v62, s44
	v_fma_f32 v69, -s6, v94, v69
	v_fma_f32 v181, -s7, v8, v181
	v_fma_f32 v180, -s8, v92, v180
	v_fma_f32 v68, -s9, v4, v68
	s_nop 0
	s_nop 0
	v_readlane_b32 s6, v14, s68
	v_readlane_b32 s7, v70, s68
	v_readlane_b32 s8, v66, s68
	v_readlane_b32 s9, v62, s68
	v_fma_f32 v69, -s6, v90, v69
	v_fma_f32 v181, -s7, v91, v181
	v_fma_f32 v180, -s8, v88, v180
	v_fma_f32 v68, -s9, v89, v68
	s_nop 0
	v_pk_add_f32 v[68:69], v[180:181], v[68:69]
	v_mov_b32_e32 v181, v123
	v_mov_b32_e32 v180, v123
	v_pk_add_f32 v[68:69], v[68:69], v[68:69] op_sel:[0,1] op_sel_hi:[1,0]
	s_nop 0
	s_nop 0
	v_readlane_b32 s6, v140, s3
	v_readlane_b32 s7, v6, s35
	v_readlane_b32 s8, v142, s35
	v_readlane_b32 s9, v24, s35
	v_fma_f32 v133, -s6, v68, v133
	v_fma_f32 v181, -s7, v130, v181
	v_fma_f32 v180, -s8, v64, v180
	v_fma_f32 v132, -s9, v128, v132
	s_nop 0
	s_nop 0
	v_readlane_b32 s6, v84, s35
	v_readlane_b32 s7, v6, s3
	v_readlane_b32 s8, v142, s3
	v_readlane_b32 s9, v24, s3
	v_fma_f32 v133, -s6, v32, v133
	v_fma_f32 v181, -s7, v118, v181
	v_fma_f32 v180, -s8, v30, v180
	v_fma_f32 v132, -s9, v116, v132
	s_nop 0
	s_nop 0
	v_readlane_b32 s6, v84, s3
	v_readlane_b32 s7, v82, s35
	v_readlane_b32 s8, v78, s35
	v_readlane_b32 s9, v28, s35
	v_fma_f32 v133, -s6, v26, v133
	v_fma_f32 v181, -s7, v114, v181
	v_fma_f32 v180, -s8, v22, v180
	v_fma_f32 v132, -s9, v110, v132
	s_nop 0
	s_nop 0
	v_readlane_b32 s6, v74, s35
	v_readlane_b32 s7, v82, s3
	v_readlane_b32 s8, v78, s3
	v_readlane_b32 s9, v28, s3
	v_fma_f32 v133, -s6, v16, v133
	v_fma_f32 v181, -s7, v104, v181
	v_fma_f32 v180, -s8, v12, v180
	v_fma_f32 v132, -s9, v96, v132
	s_nop 0
	s_nop 0
	v_readlane_b32 s6, v74, s3
	v_readlane_b32 s7, v14, s35
	v_readlane_b32 s8, v70, s35
	v_readlane_b32 s9, v66, s35
	v_fma_f32 v133, -s6, v10, v133
	v_fma_f32 v181, -s7, v94, v181
	v_fma_f32 v180, -s8, v8, v180
	v_fma_f32 v132, -s9, v92, v132
	s_nop 0
	s_nop 0
	v_readlane_b32 s6, v62, s35
	v_readlane_b32 s7, v14, s3
	v_readlane_b32 s8, v70, s3
	v_readlane_b32 s9, v66, s3
	v_fma_f32 v133, -s6, v4, v133
	v_fma_f32 v181, -s7, v90, v181
	v_fma_f32 v180, -s8, v91, v180
	v_fma_f32 v132, -s9, v88, v132
	s_nop 0
	s_nop 0
	v_readlane_b32 s6, v62, s3
	s_nop 1
	v_fma_f32 v133, -s6, v89, v133
	s_nop 0
	v_pk_add_f32 v[132:133], v[180:181], v[132:133]
	v_mov_b32_e32 v181, v123
	v_mov_b32_e32 v180, v123
	v_pk_add_f32 v[132:133], v[132:133], v[132:133] op_sel:[0,1] op_sel_hi:[1,0]
	s_nop 0
	s_nop 0
	v_readlane_b32 s6, v144, s16
	v_readlane_b32 s7, v140, s16
	v_readlane_b32 s8, v6, s30
	v_readlane_b32 s9, v142, s30
	v_fma_f32 v73, -s6, v132, v73
	v_fma_f32 v181, -s7, v68, v181
	v_fma_f32 v180, -s8, v130, v180
	v_fma_f32 v72, -s9, v64, v72
	v_mov_b32_e32 v133, v68
	s_nop 0
	v_readlane_b32 s6, v24, s30
	v_readlane_b32 s7, v84, s30
	v_readlane_b32 s8, v6, s16
	v_readlane_b32 s9, v142, s16
	v_fma_f32 v73, -s6, v128, v73
	v_fma_f32 v181, -s7, v32, v181
	v_fma_f32 v180, -s8, v118, v180
	v_fma_f32 v72, -s9, v30, v72
	s_nop 0
	s_nop 0
	v_readlane_b32 s6, v24, s16
	v_readlane_b32 s7, v84, s16
	v_readlane_b32 s8, v82, s30
	v_readlane_b32 s9, v78, s30
	v_fma_f32 v73, -s6, v116, v73
	v_fma_f32 v181, -s7, v26, v181
	v_fma_f32 v180, -s8, v114, v180
	v_fma_f32 v72, -s9, v22, v72
	s_nop 0
	s_nop 0
	v_readlane_b32 s6, v28, s30
	v_readlane_b32 s7, v74, s30
	v_readlane_b32 s8, v82, s16
	v_readlane_b32 s9, v78, s16
	v_fma_f32 v73, -s6, v110, v73
	v_fma_f32 v181, -s7, v16, v181
	v_fma_f32 v180, -s8, v104, v180
	v_fma_f32 v72, -s9, v12, v72
	s_nop 0
	s_nop 0
	v_readlane_b32 s6, v28, s16
	v_readlane_b32 s7, v74, s16
	v_readlane_b32 s8, v14, s30
	v_readlane_b32 s9, v70, s30
	v_fma_f32 v73, -s6, v96, v73
	v_fma_f32 v181, -s7, v10, v181
	v_fma_f32 v180, -s8, v94, v180
	v_fma_f32 v72, -s9, v8, v72
	s_nop 0
	s_nop 0
	v_readlane_b32 s6, v66, s30
	v_readlane_b32 s7, v62, s30
	v_readlane_b32 s8, v14, s16
	v_readlane_b32 s9, v70, s16
	v_fma_f32 v73, -s6, v92, v73
	v_fma_f32 v181, -s7, v4, v181
	v_fma_f32 v180, -s8, v90, v180
	v_fma_f32 v72, -s9, v91, v72
	s_nop 0
	s_nop 0
	v_readlane_b32 s6, v66, s16
	s_nop 1
	v_fma_f32 v73, -s6, v88, v73
	s_nop 0
	s_nop 0
	v_readlane_b32 s6, v62, s16
	s_nop 1
	v_fma_f32 v73, -s6, v89, v73
	s_nop 0
	v_pk_add_f32 v[72:73], v[180:181], v[72:73]
	v_mov_b32_e32 v181, v123
	v_mov_b32_e32 v180, v123
	v_pk_add_f32 v[72:73], v[72:73], v[72:73] op_sel:[0,1] op_sel_hi:[1,0]
	s_nop 0
	s_nop 0
	v_readlane_b32 s6, v146, s17
	v_readlane_b32 s7, v144, s17
	v_readlane_b32 s8, v140, s17
	v_readlane_b32 s9, v6, s36
	v_fma_f32 v135, -s6, v72, v135
	v_fma_f32 v181, -s7, v132, v181
	v_fma_f32 v180, -s8, v68, v180
	v_fma_f32 v134, -s9, v130, v134
	s_nop 0
	s_nop 0
	v_readlane_b32 s6, v142, s36
	v_readlane_b32 s7, v24, s36
	v_readlane_b32 s8, v84, s36
	v_readlane_b32 s9, v6, s17
	v_fma_f32 v135, -s6, v64, v135
	v_fma_f32 v181, -s7, v128, v181
	v_fma_f32 v180, -s8, v32, v180
	v_fma_f32 v134, -s9, v118, v134
	s_nop 0
	s_nop 0
	v_readlane_b32 s6, v142, s17
	v_readlane_b32 s7, v24, s17
	v_readlane_b32 s8, v84, s17
	v_readlane_b32 s9, v82, s36
	v_fma_f32 v135, -s6, v30, v135
	v_fma_f32 v181, -s7, v116, v181
	v_fma_f32 v180, -s8, v26, v180
	v_fma_f32 v134, -s9, v114, v134
	s_nop 0
	s_nop 0
	v_readlane_b32 s6, v78, s36
	v_readlane_b32 s7, v28, s36
	v_readlane_b32 s8, v74, s36
	v_readlane_b32 s9, v82, s17
	v_fma_f32 v135, -s6, v22, v135
	v_fma_f32 v181, -s7, v110, v181
	v_fma_f32 v180, -s8, v16, v180
	v_fma_f32 v134, -s9, v104, v134
	s_nop 0
	s_nop 0
	v_readlane_b32 s6, v78, s17
	v_readlane_b32 s7, v28, s17
	v_readlane_b32 s8, v74, s17
	v_readlane_b32 s9, v14, s36
	v_fma_f32 v135, -s6, v12, v135
	v_fma_f32 v181, -s7, v96, v181
	v_fma_f32 v180, -s8, v10, v180
	v_fma_f32 v134, -s9, v94, v134
	s_nop 0
	s_nop 0
	v_readlane_b32 s6, v70, s36
	v_readlane_b32 s7, v66, s36
	v_readlane_b32 s8, v62, s36
	v_readlane_b32 s9, v14, s17
	v_fma_f32 v135, -s6, v8, v135
	v_fma_f32 v181, -s7, v92, v181
	v_fma_f32 v180, -s8, v4, v180
	v_fma_f32 v134, -s9, v90, v134
	s_nop 0
	s_nop 0
	v_readlane_b32 s6, v70, s17
	s_nop 1
	v_fma_f32 v135, -s6, v91, v135
	s_nop 0
	s_nop 0
	v_readlane_b32 s6, v66, s17
	s_nop 1
	v_fma_f32 v135, -s6, v88, v135
	s_nop 0
	s_nop 0
	v_readlane_b32 s6, v62, s17
	s_nop 1
	v_fma_f32 v135, -s6, v89, v135
	s_nop 0
	v_pk_add_f32 v[134:135], v[180:181], v[134:135]
	v_mov_b32_e32 v181, v123
	v_mov_b32_e32 v180, v123
	v_pk_add_f32 v[134:135], v[134:135], v[134:135] op_sel:[0,1] op_sel_hi:[1,0]
	s_nop 0
	s_nop 0
	v_readlane_b32 s6, v2, s69
	v_readlane_b32 s7, v146, s69
	v_readlane_b32 s8, v144, s69
	v_readlane_b32 s9, v140, s69
	v_fma_f32 v77, -s6, v134, v77
	v_fma_f32 v181, -s7, v72, v181
	v_fma_f32 v180, -s8, v132, v180
	v_fma_f32 v76, -s9, v68, v76
	v_mov_b32_e32 v135, v72
	s_nop 0
	v_readlane_b32 s6, v6, s12
	v_readlane_b32 s7, v142, s12
	v_readlane_b32 s8, v24, s12
	v_readlane_b32 s9, v84, s12
	v_fma_f32 v77, -s6, v130, v77
	v_fma_f32 v181, -s7, v64, v181
	v_fma_f32 v180, -s8, v128, v180
	v_fma_f32 v76, -s9, v32, v76
	s_nop 0
	s_nop 0
	v_readlane_b32 s6, v6, s69
	v_readlane_b32 s7, v142, s69
	v_readlane_b32 s8, v24, s69
	v_readlane_b32 s9, v84, s69
	v_fma_f32 v77, -s6, v118, v77
	v_fma_f32 v181, -s7, v30, v181
	v_fma_f32 v180, -s8, v116, v180
	v_fma_f32 v76, -s9, v26, v76
	s_nop 0
	s_nop 0
	v_readlane_b32 s6, v82, s12
	v_readlane_b32 s7, v78, s12
	v_readlane_b32 s8, v28, s12
	v_readlane_b32 s9, v74, s12
	v_fma_f32 v77, -s6, v114, v77
	v_fma_f32 v181, -s7, v22, v181
	v_fma_f32 v180, -s8, v110, v180
	v_fma_f32 v76, -s9, v16, v76
	s_nop 0
	s_nop 0
	v_readlane_b32 s6, v82, s69
	v_readlane_b32 s7, v78, s69
	v_readlane_b32 s8, v28, s69
	v_readlane_b32 s9, v74, s69
	v_fma_f32 v77, -s6, v104, v77
	v_fma_f32 v181, -s7, v12, v181
	v_fma_f32 v180, -s8, v96, v180
	v_fma_f32 v76, -s9, v10, v76
	s_nop 0
	s_nop 0
	v_readlane_b32 s6, v14, s12
	v_readlane_b32 s7, v70, s12
	v_readlane_b32 s8, v66, s12
	v_readlane_b32 s9, v62, s12
	v_fma_f32 v77, -s6, v94, v77
	v_fma_f32 v181, -s7, v8, v181
	v_fma_f32 v180, -s8, v92, v180
	v_fma_f32 v76, -s9, v4, v76
	s_nop 0
	s_nop 0
	v_readlane_b32 s6, v14, s69
	v_readlane_b32 s7, v70, s69
	v_readlane_b32 s8, v66, s69
	v_readlane_b32 s9, v62, s69
	v_fma_f32 v77, -s6, v90, v77
	v_fma_f32 v181, -s7, v91, v181
	v_fma_f32 v180, -s8, v88, v180
	v_fma_f32 v76, -s9, v89, v76
	s_nop 0
	v_pk_add_f32 v[76:77], v[180:181], v[76:77]
	v_mov_b32_e32 v181, v123
	v_mov_b32_e32 v180, v123
	v_pk_add_f32 v[76:77], v[76:77], v[76:77] op_sel:[0,1] op_sel_hi:[1,0]
	s_nop 0
	s_nop 0
	v_readlane_b32 s6, v140, s15
	v_readlane_b32 s7, v2, s23
	v_readlane_b32 s8, v146, s23
	v_readlane_b32 s9, v144, s23
	v_fma_f32 v137, -s6, v76, v137
	v_fma_f32 v181, -s7, v134, v181
	v_fma_f32 v180, -s8, v72, v180
	v_fma_f32 v136, -s9, v132, v136
	s_nop 0
	s_nop 0
	v_readlane_b32 s6, v140, s23
	v_readlane_b32 s7, v6, s15
	v_readlane_b32 s8, v142, s15
	v_readlane_b32 s9, v24, s15
	v_fma_f32 v137, -s6, v68, v137
	v_fma_f32 v181, -s7, v130, v181
	v_fma_f32 v180, -s8, v64, v180
	v_fma_f32 v136, -s9, v128, v136
	s_nop 0
	s_nop 0
	v_readlane_b32 s6, v84, s15
	v_readlane_b32 s7, v6, s23
	v_readlane_b32 s8, v142, s23
	v_readlane_b32 s9, v24, s23
	v_fma_f32 v137, -s6, v32, v137
	v_fma_f32 v181, -s7, v118, v181
	v_fma_f32 v180, -s8, v30, v180
	v_fma_f32 v136, -s9, v116, v136
	s_nop 0
	s_nop 0
	v_readlane_b32 s6, v84, s23
	v_readlane_b32 s7, v82, s15
	v_readlane_b32 s8, v78, s15
	v_readlane_b32 s9, v28, s15
	v_fma_f32 v137, -s6, v26, v137
	v_fma_f32 v181, -s7, v114, v181
	v_fma_f32 v180, -s8, v22, v180
	v_fma_f32 v136, -s9, v110, v136
	s_nop 0
	s_nop 0
	v_readlane_b32 s6, v74, s15
	v_readlane_b32 s7, v82, s23
	v_readlane_b32 s8, v78, s23
	v_readlane_b32 s9, v28, s23
	v_fma_f32 v137, -s6, v16, v137
	v_fma_f32 v181, -s7, v104, v181
	v_fma_f32 v180, -s8, v12, v180
	v_fma_f32 v136, -s9, v96, v136
	s_nop 0
	s_nop 0
	v_readlane_b32 s6, v74, s23
	v_readlane_b32 s7, v14, s15
	v_readlane_b32 s8, v70, s15
	v_readlane_b32 s9, v66, s15
	v_fma_f32 v137, -s6, v10, v137
	v_fma_f32 v181, -s7, v94, v181
	v_fma_f32 v180, -s8, v8, v180
	v_fma_f32 v136, -s9, v92, v136
	s_nop 0
	s_nop 0
	v_readlane_b32 s6, v62, s15
	v_readlane_b32 s7, v14, s23
	v_readlane_b32 s8, v70, s23
	v_readlane_b32 s9, v66, s23
	v_fma_f32 v137, -s6, v4, v137
	v_fma_f32 v181, -s7, v90, v181
	v_fma_f32 v180, -s8, v91, v180
	v_fma_f32 v136, -s9, v88, v136
	s_nop 0
	s_nop 0
	v_readlane_b32 s6, v62, s23
	s_nop 1
	v_fma_f32 v137, -s6, v89, v137
	s_nop 0
	v_pk_add_f32 v[136:137], v[180:181], v[136:137]
	v_mov_b32_e32 v181, v123
	v_mov_b32_e32 v180, v123
	v_pk_add_f32 v[136:137], v[136:137], v[136:137] op_sel:[0,1] op_sel_hi:[1,0]
	s_nop 0
	s_nop 0
	v_readlane_b32 s6, v144, s26
	v_readlane_b32 s7, v140, s26
	v_readlane_b32 s8, v2, s10
	v_readlane_b32 s9, v146, s10
	v_fma_f32 v81, -s6, v136, v81
	v_fma_f32 v181, -s7, v76, v181
	v_fma_f32 v180, -s8, v134, v180
	v_fma_f32 v80, -s9, v72, v80
	v_mov_b32_e32 v137, v76
	s_nop 0
	v_readlane_b32 s6, v144, s10
	v_readlane_b32 s7, v140, s10
	v_readlane_b32 s8, v6, s26
	v_readlane_b32 s9, v142, s26
	v_fma_f32 v81, -s6, v132, v81
	v_fma_f32 v181, -s7, v68, v181
	v_fma_f32 v180, -s8, v130, v180
	v_fma_f32 v80, -s9, v64, v80
	s_nop 0
	s_nop 0
	v_readlane_b32 s6, v24, s26
	v_readlane_b32 s7, v84, s26
	v_readlane_b32 s8, v6, s10
	v_readlane_b32 s9, v142, s10
	v_fma_f32 v81, -s6, v128, v81
	v_fma_f32 v181, -s7, v32, v181
	v_fma_f32 v180, -s8, v118, v180
	v_fma_f32 v80, -s9, v30, v80
	s_nop 0
	s_nop 0
	v_readlane_b32 s6, v24, s10
	v_readlane_b32 s7, v84, s10
	v_readlane_b32 s8, v82, s26
	v_readlane_b32 s9, v78, s26
	v_fma_f32 v81, -s6, v116, v81
	v_fma_f32 v181, -s7, v26, v181
	v_fma_f32 v180, -s8, v114, v180
	v_fma_f32 v80, -s9, v22, v80
	s_nop 0
	s_nop 0
	v_readlane_b32 s6, v28, s26
	v_readlane_b32 s7, v74, s26
	v_readlane_b32 s8, v82, s10
	v_readlane_b32 s9, v78, s10
	v_fma_f32 v81, -s6, v110, v81
	v_fma_f32 v181, -s7, v16, v181
	v_fma_f32 v180, -s8, v104, v180
	v_fma_f32 v80, -s9, v12, v80
	s_nop 0
	s_nop 0
	v_readlane_b32 s6, v28, s10
	v_readlane_b32 s7, v74, s10
	v_readlane_b32 s8, v14, s26
	v_readlane_b32 s9, v70, s26
	v_fma_f32 v81, -s6, v96, v81
	v_fma_f32 v181, -s7, v10, v181
	v_fma_f32 v180, -s8, v94, v180
	v_fma_f32 v80, -s9, v8, v80
	s_nop 0
	s_nop 0
	v_readlane_b32 s6, v66, s26
	v_readlane_b32 s7, v62, s26
	v_readlane_b32 s8, v14, s10
	v_readlane_b32 s9, v70, s10
	v_fma_f32 v81, -s6, v92, v81
	v_fma_f32 v181, -s7, v4, v181
	v_fma_f32 v180, -s8, v90, v180
	v_fma_f32 v80, -s9, v91, v80
	s_nop 0
	s_nop 0
	v_readlane_b32 s6, v66, s10
	s_nop 1
	v_fma_f32 v81, -s6, v88, v81
	s_nop 0
	s_nop 0
	v_readlane_b32 s6, v62, s10
	s_nop 1
	v_fma_f32 v81, -s6, v89, v81
	s_nop 0
	v_pk_add_f32 v[80:81], v[180:181], v[80:81]
	v_mov_b32_e32 v181, v123
	v_mov_b32_e32 v180, v123
	v_pk_add_f32 v[80:81], v[80:81], v[80:81] op_sel:[0,1] op_sel_hi:[1,0]
	s_nop 0
	s_nop 0
	v_readlane_b32 s6, v146, s13
	v_readlane_b32 s7, v144, s13
	v_readlane_b32 s8, v140, s13
	v_readlane_b32 s9, v2, s31
	v_fma_f32 v139, -s6, v80, v139
	v_fma_f32 v181, -s7, v136, v181
	v_fma_f32 v180, -s8, v76, v180
	v_fma_f32 v138, -s9, v134, v138
	v_mov_b32_e32 v2, v123
	s_nop 0
	v_readlane_b32 s6, v146, s31
	v_readlane_b32 s7, v144, s31
	v_readlane_b32 s8, v140, s31
	v_readlane_b32 s9, v6, s13
	v_fma_f32 v139, -s6, v72, v139
	v_fma_f32 v181, -s7, v132, v181
	v_fma_f32 v180, -s8, v68, v180
	v_fma_f32 v138, -s9, v130, v138
	v_mov_b32_e32 v140, v123
	s_nop 0
	v_readlane_b32 s6, v142, s13
	v_readlane_b32 s7, v24, s13
	v_readlane_b32 s8, v84, s13
	v_readlane_b32 s9, v6, s31
	v_fma_f32 v139, -s6, v64, v139
	v_fma_f32 v181, -s7, v128, v181
	v_fma_f32 v180, -s8, v32, v180
	v_fma_f32 v138, -s9, v118, v138
	v_mov_b32_e32 v144, v123
	s_nop 0
	v_readlane_b32 s6, v142, s31
	v_readlane_b32 s7, v24, s31
	v_readlane_b32 s8, v84, s31
	v_readlane_b32 s9, v82, s13
	v_fma_f32 v139, -s6, v30, v139
	v_fma_f32 v181, -s7, v116, v181
	v_fma_f32 v180, -s8, v26, v180
	v_fma_f32 v138, -s9, v114, v138
	v_mov_b32_e32 v142, v123
	s_nop 0
	v_readlane_b32 s6, v78, s13
	v_readlane_b32 s7, v28, s13
	v_readlane_b32 s8, v74, s13
	v_readlane_b32 s9, v82, s31
	v_fma_f32 v139, -s6, v22, v139
	v_fma_f32 v181, -s7, v110, v181
	v_fma_f32 v180, -s8, v16, v180
	v_fma_f32 v138, -s9, v104, v138
	v_mov_b32_e32 v146, v123
	s_nop 0
	v_readlane_b32 s6, v78, s31
	v_readlane_b32 s7, v28, s31
	v_readlane_b32 s8, v74, s31
	v_readlane_b32 s9, v14, s13
	v_fma_f32 v139, -s6, v12, v139
	v_fma_f32 v181, -s7, v96, v181
	v_fma_f32 v180, -s8, v10, v180
	v_fma_f32 v138, -s9, v94, v138
	v_mov_b32_e32 v84, v123
	s_nop 0
	v_readlane_b32 s6, v70, s13
	v_readlane_b32 s7, v66, s13
	v_readlane_b32 s8, v62, s13
	v_readlane_b32 s9, v14, s31
	v_fma_f32 v139, -s6, v8, v139
	v_fma_f32 v181, -s7, v92, v181
	v_fma_f32 v180, -s8, v4, v180
	v_fma_f32 v138, -s9, v90, v138
	v_mov_b32_e32 v82, v123
	s_nop 0
	v_readlane_b32 s6, v70, s31
	s_nop 1
	v_fma_f32 v139, -s6, v91, v139
	v_mov_b32_e32 v78, v123
	s_nop 0
	v_readlane_b32 s6, v66, s31
	s_nop 1
	v_fma_f32 v139, -s6, v88, v139
	v_mov_b32_e32 v74, v123
	s_nop 0
	v_readlane_b32 s6, v62, s31
	s_nop 1
	v_fma_f32 v139, -s6, v89, v139
	v_mov_b32_e32 v70, v123
	v_pk_add_f32 v[138:139], v[180:181], v[138:139]
	v_mov_b32_e32 v181, v123
	v_mov_b32_e32 v180, v123
	v_pk_add_f32 v[138:139], v[138:139], v[138:139] op_sel:[0,1] op_sel_hi:[1,0]
	v_mov_b32_e32 v66, v123
	v_readlane_b32 s98, v251, 55
	s_nop 3
	s_mul_i32 s98, s98, 9
	s_add_i32 s98, s98, 0x4000
	v_mbcnt_lo_u32_b32 v255, -1, 0
	v_mbcnt_hi_u32_b32 v255, -1, v255
	v_and_b32_e32 v253, 31, v255
	v_lshrrev_b32_e32 v254, 5, v255
	v_cmp_lt_u32_e64 s[96:97], 31, v255
	v_mul_u32_u24_e32 v248, 0x210, v254
	v_lshl_add_u32 v248, v253, 2, v248
	v_add_u32_e32 v248, s98, v248
	v_mul_u32_u24_e32 v249, 0x84, v253
	v_add_u32_e32 v249, s98, v249
	v_lshlrev_b32_e32 v255, 2, v253
	v_add_u32_e32 v255, 0x1080, v255
	v_add_u32_e32 v255, s98, v255
	ds_write_b32 v255, v123
	s_add_i32 s98, s98, 0x1080
	v_mov_b32_e32 v253, s98
	s_nop 1
	v_cndmask_b32_e64 v249, v253, v249, s[96:97]
	v_mov_b32_e32 v244, v134
	v_mov_b32_e32 v245, v138
	s_nop 1
	v_permlane32_swap_b32_e32 v245, v244
	s_nop 1
	v_mfma_f32_32x32x2_f32 v[228:243], v244, v226, 0
	v_mov_b32_e32 v246, v72
	v_mov_b32_e32 v247, v80
	s_nop 1
	v_permlane32_swap_b32_e32 v247, v246
	s_nop 1
	v_mfma_f32_32x32x2_f32 v[228:243], v246, v225, v[228:243]
	v_mov_b32_e32 v244, v132
	v_mov_b32_e32 v245, v136
	s_nop 1
	v_permlane32_swap_b32_e32 v245, v244
	s_nop 1
	v_mfma_f32_32x32x2_f32 v[228:243], v244, v224, v[228:243]
	v_mov_b32_e32 v246, v68
	v_mov_b32_e32 v247, v76
	s_nop 1
	v_permlane32_swap_b32_e32 v247, v246
	s_nop 1
	v_mfma_f32_32x32x2_f32 v[228:243], v246, v223, v[228:243]
	v_mov_b32_e32 v244, v118
	v_mov_b32_e32 v245, v130
	s_nop 1
	v_permlane32_swap_b32_e32 v245, v244
	s_nop 1
	v_mfma_f32_32x32x2_f32 v[228:243], v244, v222, v[228:243]
	v_mov_b32_e32 v246, v30
	v_mov_b32_e32 v247, v64
	s_nop 1
	v_permlane32_swap_b32_e32 v247, v246
	s_nop 1
	v_mfma_f32_32x32x2_f32 v[228:243], v246, v221, v[228:243]
	v_mov_b32_e32 v244, v116
	v_mov_b32_e32 v245, v128
	s_nop 1
	v_permlane32_swap_b32_e32 v245, v244
	s_nop 1
	v_mfma_f32_32x32x2_f32 v[228:243], v244, v220, v[228:243]
	v_mov_b32_e32 v246, v26
	v_mov_b32_e32 v247, v32
	s_nop 1
	v_permlane32_swap_b32_e32 v247, v246
	s_nop 1
	v_mfma_f32_32x32x2_f32 v[228:243], v246, v219, v[228:243]
	v_mov_b32_e32 v244, v104
	v_mov_b32_e32 v245, v114
	s_nop 1
	v_permlane32_swap_b32_e32 v245, v244
	s_nop 1
	v_mfma_f32_32x32x2_f32 v[228:243], v244, v218, v[228:243]
	v_mov_b32_e32 v246, v12
	v_mov_b32_e32 v247, v22
	s_nop 1
	v_permlane32_swap_b32_e32 v247, v246
	s_nop 1
	v_mfma_f32_32x32x2_f32 v[228:243], v246, v217, v[228:243]
	v_mov_b32_e32 v244, v96
	v_mov_b32_e32 v245, v110
	s_nop 1
	v_permlane32_swap_b32_e32 v245, v244
	s_nop 1
	v_mfma_f32_32x32x2_f32 v[228:243], v244, v216, v[228:243]
	v_mov_b32_e32 v246, v10
	v_mov_b32_e32 v247, v16
	s_nop 1
	v_permlane32_swap_b32_e32 v247, v246
	s_nop 1
	v_mfma_f32_32x32x2_f32 v[228:243], v246, v215, v[228:243]
	v_mov_b32_e32 v244, v90
	v_mov_b32_e32 v245, v94
	s_nop 1
	v_permlane32_swap_b32_e32 v245, v244
	s_nop 1
	v_mfma_f32_32x32x2_f32 v[228:243], v244, v214, v[228:243]
	v_mov_b32_e32 v246, v91
	v_mov_b32_e32 v247, v8
	s_nop 1
	v_permlane32_swap_b32_e32 v247, v246
	s_nop 1
	v_mfma_f32_32x32x2_f32 v[228:243], v246, v213, v[228:243]
	v_mov_b32_e32 v244, v88
	v_mov_b32_e32 v245, v92
	s_nop 1
	v_permlane32_swap_b32_e32 v245, v244
	s_nop 1
	v_mfma_f32_32x32x2_f32 v[228:243], v244, v212, v[228:243]
	v_mov_b32_e32 v246, v89
	v_mov_b32_e32 v247, v4
	s_nop 1
	v_permlane32_swap_b32_e32 v247, v246
	s_nop 1
	v_mfma_f32_32x32x2_f32 v[228:243], v246, v211, v[228:243]
	s_nop 15
	s_nop 3
	ds_write_b32 v248, v228 offset:0
	ds_write_b32 v248, v229 offset:132
	ds_write_b32 v248, v230 offset:264
	ds_write_b32 v248, v231 offset:396
	ds_write_b32 v248, v232 offset:1056
	ds_write_b32 v248, v233 offset:1188
	ds_write_b32 v248, v234 offset:1320
	ds_write_b32 v248, v235 offset:1452
	ds_write_b32 v248, v236 offset:2112
	ds_write_b32 v248, v237 offset:2244
	ds_write_b32 v248, v238 offset:2376
	ds_write_b32 v248, v239 offset:2508
	ds_write_b32 v248, v240 offset:3168
	ds_write_b32 v248, v241 offset:3300
	ds_write_b32 v248, v242 offset:3432
	ds_write_b32 v248, v243 offset:3564
	s_waitcnt lgkmcnt(0)
	ds_read_b32 v246, v249 offset:124
	s_mov_b32 s96, 0x9003000
	s_mov_b32 s97, 0
	v_lshl_add_u64 v[244:245], v[98:99], 0, s[96:97]
	global_load_dwordx4 v[212:215], v[244:245], off offset:-4096
	global_load_dwordx4 v[216:219], v[244:245], off offset:-4064
	global_load_dwordx4 v[220:223], v[244:245], off offset:-4032
	global_load_dwordx4 v[224:227], v[244:245], off offset:-4000
	global_load_dwordx4 v[228:231], v[244:245], off
	global_load_dwordx4 v[232:235], v[244:245], off offset:32
	global_load_dwordx4 v[236:239], v[244:245], off offset:64
	global_load_dwordx4 v[240:243], v[244:245], off offset:96
	s_waitcnt lgkmcnt(0)
	v_sub_f32_e32 v153, v153, v246
	ds_read_b32 v247, v249 offset:120
	s_nop 0
	v_mov_b32_e32 v62, v123
	s_nop 0
	v_mov_b32_e32 v28, v123
	s_nop 0
	v_mov_b32_e32 v24, v123
	s_nop 0
	v_mov_b32_e32 v14, v123
	s_nop 0
	v_mov_b32_e32 v6, v123
	s_nop 0
	v_mov_b32_e32 v139, v80
	s_nop 0
	s_nop 0
	s_nop 0
	s_mov_b32 s20, 30
	v_pk_add_f32 v[152:153], v[180:181], v[152:153]
	v_mov_b32_e32 v181, v123
	v_mov_b32_e32 v180, v123
	v_pk_add_f32 v[152:153], v[152:153], v[152:153] op_sel:[0,1] op_sel_hi:[1,0]
	s_nop 0
	s_waitcnt lgkmcnt(0)
	v_sub_f32_e32 v141, v141, v247
	ds_read_b32 v246, v249 offset:116
	s_nop 0
	v_readlane_b32 s6, v209, s54
	s_nop 1
	v_fma_f32 v141, -s6, v152, v141
	s_nop 0
	s_nop 0
	s_nop 0
	s_nop 0
	s_nop 0
	s_nop 0
	s_nop 0
	s_nop 0
	s_nop 0
	s_nop 0
	s_nop 0
	s_nop 0
	s_nop 0
	s_nop 0
	s_mov_b32 s20, 29
	s_nop 0
	s_nop 1
	s_nop 0
	v_pk_add_f32 v[140:141], v[180:181], v[140:141]
	v_mov_b32_e32 v181, v123
	v_mov_b32_e32 v180, v123
	v_pk_add_f32 v[140:141], v[140:141], v[140:141] op_sel:[0,1] op_sel_hi:[1,0]
	s_nop 0
	s_waitcnt lgkmcnt(0)
	v_sub_f32_e32 v159, v159, v246
	ds_read_b32 v247, v249 offset:112
	s_nop 0
	v_readlane_b32 s6, v207, s55
	v_readlane_b32 s7, v209, s55
	s_nop 0
	v_fma_f32 v159, -s6, v140, v159
	v_fma_f32 v181, -s7, v152, v181
	v_mov_b32_e32 v141, v152
	s_nop 0
	s_nop 0
	s_nop 0
	s_nop 0
	s_nop 0
	s_nop 0
	s_nop 0
	s_nop 0
	s_nop 0
	s_nop 0
	s_nop 0
	s_nop 0
	s_nop 0
	s_mov_b32 s20, 28
	s_nop 0
	s_nop 1
	s_nop 0
	s_nop 0
	s_nop 1
	s_nop 0
	v_pk_add_f32 v[158:159], v[180:181], v[158:159]
	v_mov_b32_e32 v181, v123
	v_mov_b32_e32 v180, v123
	v_pk_add_f32 v[158:159], v[158:159], v[158:159] op_sel:[0,1] op_sel_hi:[1,0]
	s_nop 0
	s_waitcnt lgkmcnt(0)
	v_sub_f32_e32 v143, v143, v247
	ds_read_b32 v246, v249 offset:108
	s_nop 0
	v_readlane_b32 s6, v208, s56
	v_readlane_b32 s7, v207, s56
	v_readlane_b32 s8, v209, s56
	v_fma_f32 v143, -s6, v158, v143
	v_fma_f32 v181, -s7, v140, v181
	v_fma_f32 v180, -s8, v152, v180
	s_nop 0
	s_nop 0
	s_nop 0
	s_nop 0
	s_nop 0
	s_nop 0
	s_nop 0
	s_nop 0
	s_nop 0
	s_nop 0
	s_nop 0
	s_nop 0
	s_nop 0
	s_nop 0
	s_mov_b32 s20, 27
	s_nop 0
	s_nop 1
	s_nop 0
	s_nop 0
	s_nop 1
	s_nop 0
	s_nop 0
	s_nop 1
	s_nop 0
	v_pk_add_f32 v[142:143], v[180:181], v[142:143]
	v_mov_b32_e32 v181, v123
	v_mov_b32_e32 v180, v123
	v_pk_add_f32 v[142:143], v[142:143], v[142:143] op_sel:[0,1] op_sel_hi:[1,0]
	s_nop 0
	s_waitcnt lgkmcnt(0)
	v_sub_f32_e32 v167, v167, v246
	ds_read_b32 v247, v249 offset:104
	s_nop 0
	v_readlane_b32 s6, v205, s57
	v_readlane_b32 s7, v208, s57
	v_readlane_b32 s8, v207, s57
	v_readlane_b32 s9, v209, s57
	v_fma_f32 v167, -s6, v142, v167
	v_fma_f32 v181, -s7, v158, v181
	v_fma_f32 v180, -s8, v140, v180
	v_fma_f32 v166, -s9, v152, v166
	v_mov_b32_e32 v143, v158
	s_nop 0
	s_nop 0
	s_nop 0
	s_nop 0
	s_nop 0
	s_nop 0
	s_nop 0
	s_nop 0
	s_nop 0
	s_nop 0
	s_nop 0
	s_nop 0
	s_nop 0
	s_nop 0
	s_nop 0
	s_nop 0
	v_pk_add_f32 v[166:167], v[180:181], v[166:167]
	v_mov_b32_e32 v181, v123
	v_mov_b32_e32 v180, v123
	v_pk_add_f32 v[166:167], v[166:167], v[166:167] op_sel:[0,1] op_sel_hi:[1,0]
	s_nop 0
	s_waitcnt lgkmcnt(0)
	v_sub_f32_e32 v145, v145, v247
	ds_read_b32 v246, v249 offset:100
	s_nop 0
	v_readlane_b32 s6, v209, s53
	v_readlane_b32 s7, v205, s58
	v_readlane_b32 s8, v208, s58
	v_readlane_b32 s9, v207, s58
	v_fma_f32 v145, -s6, v166, v145
	v_fma_f32 v181, -s7, v142, v181
	v_fma_f32 v180, -s8, v158, v180
	v_fma_f32 v144, -s9, v140, v144
	s_nop 0
	s_nop 0
	v_readlane_b32 s6, v209, s58
	s_nop 1
	v_fma_f32 v145, -s6, v152, v145
	s_nop 0
	s_nop 0
	s_nop 0
	s_nop 0
	s_nop 0
	s_nop 0
	s_nop 0
	s_nop 0
	s_nop 0
	s_nop 0
	s_nop 0
	s_nop 0
	s_nop 0
	s_nop 0
	s_nop 0
	s_nop 0
	s_nop 1
	s_nop 0
	v_pk_add_f32 v[144:145], v[180:181], v[144:145]
	v_mov_b32_e32 v181, v123
	v_mov_b32_e32 v180, v123
	v_pk_add_f32 v[144:145], v[144:145], v[144:145] op_sel:[0,1] op_sel_hi:[1,0]
	s_nop 0
	s_waitcnt lgkmcnt(0)
	v_sub_f32_e32 v171, v171, v246
	ds_read_b32 v247, v249 offset:96
	s_nop 0
	v_readlane_b32 s6, v207, s52
	v_readlane_b32 s7, v209, s52
	v_readlane_b32 s8, v205, s59
	v_readlane_b32 s9, v208, s59
	v_fma_f32 v171, -s6, v144, v171
	v_fma_f32 v181, -s7, v166, v181
	v_fma_f32 v180, -s8, v142, v180
	v_fma_f32 v170, -s9, v158, v170
	v_mov_b32_e32 v145, v166
	s_nop 0
	v_readlane_b32 s6, v207, s59
	v_readlane_b32 s7, v209, s59
	s_nop 0
	v_fma_f32 v171, -s6, v140, v171
	v_fma_f32 v181, -s7, v152, v181
	s_nop 0
	s_nop 0
	s_nop 0
	s_nop 0
	s_nop 0
	s_nop 0
	s_nop 0
	s_nop 0
	s_nop 0
	s_nop 0
	s_nop 0
	s_nop 0
	s_nop 0
	s_nop 0
	s_nop 0
	s_nop 0
	s_nop 1
	s_nop 0
	s_nop 0
	s_nop 1
	s_nop 0
	v_pk_add_f32 v[170:171], v[180:181], v[170:171]
	v_mov_b32_e32 v181, v123
	v_mov_b32_e32 v180, v123
	v_pk_add_f32 v[170:171], v[170:171], v[170:171] op_sel:[0,1] op_sel_hi:[1,0]
	s_nop 0
	s_waitcnt lgkmcnt(0)
	v_sub_f32_e32 v147, v147, v247
	ds_read_b32 v246, v249 offset:92
	s_nop 0
	v_readlane_b32 s6, v208, s51
	v_readlane_b32 s7, v207, s51
	v_readlane_b32 s8, v209, s51
	v_readlane_b32 s9, v205, s60
	v_fma_f32 v147, -s6, v170, v147
	v_fma_f32 v181, -s7, v144, v181
	v_fma_f32 v180, -s8, v166, v180
	v_fma_f32 v146, -s9, v142, v146
	s_nop 0
	s_nop 0
	v_readlane_b32 s6, v208, s60
	v_readlane_b32 s7, v207, s60
	v_readlane_b32 s8, v209, s60
	v_fma_f32 v147, -s6, v158, v147
	v_fma_f32 v181, -s7, v140, v181
	v_fma_f32 v180, -s8, v152, v180
	s_nop 0
	s_nop 0
	s_nop 0
	s_nop 0
	s_nop 0
	s_nop 0
	s_nop 0
	s_nop 0
	s_nop 0
	s_nop 0
	s_nop 0
	s_nop 0
	s_nop 0
	s_nop 0
	s_nop 0
	s_nop 0
	s_nop 1
	s_nop 0
	s_nop 0
	s_nop 1
	s_nop 0
	s_nop 0
	s_nop 1
	s_nop 0
	v_pk_add_f32 v[146:147], v[180:181], v[146:147]
	v_mov_b32_e32 v181, v123
	v_mov_b32_e32 v180, v123
	v_pk_add_f32 v[146:147], v[146:147], v[146:147] op_sel:[0,1] op_sel_hi:[1,0]
	s_nop 0
	s_waitcnt lgkmcnt(0)
	v_sub_f32_e32 v175, v175, v246
	ds_read_b32 v247, v249 offset:88
	s_nop 0
	v_readlane_b32 s6, v205, s70
	v_readlane_b32 s7, v208, s70
	v_readlane_b32 s8, v207, s70
	v_readlane_b32 s9, v209, s70
	v_fma_f32 v175, -s6, v146, v175
	v_fma_f32 v181, -s7, v170, v181
	v_fma_f32 v180, -s8, v144, v180
	v_fma_f32 v174, -s9, v166, v174
	v_mov_b32_e32 v147, v170
	s_nop 0
	v_readlane_b32 s6, v205, s61
	v_readlane_b32 s7, v208, s61
	v_readlane_b32 s8, v207, s61
	v_readlane_b32 s9, v209, s61
	v_fma_f32 v175, -s6, v142, v175
	v_fma_f32 v181, -s7, v158, v181
	v_fma_f32 v180, -s8, v140, v180
	v_fma_f32 v174, -s9, v152, v174
	s_nop 0
	s_nop 0
	s_nop 0
	s_nop 0
	s_nop 0
	s_nop 0
	s_nop 0
	s_nop 0
	s_nop 0
	s_nop 0
	s_nop 0
	s_nop 0
	s_nop 0
	s_nop 0
	s_nop 0
	s_nop 0
	s_nop 0
	v_pk_add_f32 v[174:175], v[180:181], v[174:175]
	v_mov_b32_e32 v181, v123
	v_mov_b32_e32 v180, v123
	v_pk_add_f32 v[174:175], v[174:175], v[174:175] op_sel:[0,1] op_sel_hi:[1,0]
	s_nop 0
	s_waitcnt lgkmcnt(0)
	v_sub_f32_e32 v149, v149, v247
	ds_read_b32 v246, v249 offset:84
	s_nop 0
	v_readlane_b32 s6, v206, s62
	v_readlane_b32 s7, v205, s71
	v_readlane_b32 s8, v208, s71
	v_readlane_b32 s9, v207, s71
	v_fma_f32 v149, -s6, v174, v149
	v_fma_f32 v181, -s7, v146, v181
	v_fma_f32 v180, -s8, v170, v180
	v_fma_f32 v148, -s9, v144, v148
	s_nop 0
	s_nop 0
	v_readlane_b32 s6, v209, s71
	v_readlane_b32 s7, v205, s62
	v_readlane_b32 s8, v208, s62
	v_readlane_b32 s9, v207, s62
	v_fma_f32 v149, -s6, v166, v149
	v_fma_f32 v181, -s7, v142, v181
	v_fma_f32 v180, -s8, v158, v180
	v_fma_f32 v148, -s9, v140, v148
	s_nop 0
	s_nop 0
	v_readlane_b32 s6, v209, s62
	s_nop 1
	v_fma_f32 v149, -s6, v152, v149
	s_nop 0
	s_nop 0
	s_nop 0
	s_nop 0
	s_nop 0
	s_nop 0
	s_nop 0
	s_nop 0
	s_nop 0
	s_nop 0
	s_nop 0
	s_nop 0
	s_nop 0
	s_nop 0
	s_nop 0
	s_nop 0
	s_nop 1
	s_nop 0
	v_pk_add_f32 v[148:149], v[180:181], v[148:149]
	v_mov_b32_e32 v181, v123
	v_mov_b32_e32 v180, v123
	v_pk_add_f32 v[148:149], v[148:149], v[148:149] op_sel:[0,1] op_sel_hi:[1,0]
	s_nop 0
	s_waitcnt lgkmcnt(0)
	v_sub_f32_e32 v179, v179, v246
	ds_read_b32 v247, v249 offset:80
	s_nop 0
	v_readlane_b32 s6, v203, s63
	v_readlane_b32 s7, v206, s63
	v_readlane_b32 s8, v205, s72
	v_readlane_b32 s9, v208, s72
	v_fma_f32 v179, -s6, v148, v179
	v_fma_f32 v181, -s7, v174, v181
	v_fma_f32 v180, -s8, v146, v180
	v_fma_f32 v178, -s9, v170, v178
	v_mov_b32_e32 v149, v174
	s_nop 0
	v_readlane_b32 s6, v207, s72
	v_readlane_b32 s7, v209, s72
	v_readlane_b32 s8, v205, s63
	v_readlane_b32 s9, v208, s63
	v_fma_f32 v179, -s6, v144, v179
	v_fma_f32 v181, -s7, v166, v181
	v_fma_f32 v180, -s8, v142, v180
	v_fma_f32 v178, -s9, v158, v178
	s_nop 0
	s_nop 0
	v_readlane_b32 s6, v207, s63
	v_readlane_b32 s7, v209, s63
	s_nop 0
	v_fma_f32 v179, -s6, v140, v179
	v_fma_f32 v181, -s7, v152, v181
	s_nop 0
	s_nop 0
	s_nop 0
	s_nop 0
	s_nop 0
	s_nop 0
	s_nop 0
	s_nop 0
	s_nop 0
	s_nop 0
	s_nop 0
	s_nop 0
	s_nop 0
	s_nop 0
	s_nop 0
	s_nop 0
	s_nop 1
	s_nop 0
	s_nop 0
	s_nop 1
	s_nop 0
	v_pk_add_f32 v[178:179], v[180:181], v[178:179]
	v_mov_b32_e32 v181, v123
	v_mov_b32_e32 v180, v123
	v_pk_add_f32 v[178:179], v[178:179], v[178:179] op_sel:[0,1] op_sel_hi:[1,0]
	s_nop 0
	s_waitcnt lgkmcnt(0)
	v_sub_f32_e32 v151, v151, v247
	ds_read_b32 v246, v249 offset:76
	s_nop 0
	v_readlane_b32 s6, v204, s22
	v_readlane_b32 s7, v203, s22
	v_readlane_b32 s8, v206, s22
	v_readlane_b32 s9, v205, s73
	v_fma_f32 v151, -s6, v178, v151
	v_fma_f32 v181, -s7, v148, v181
	v_fma_f32 v180, -s8, v174, v180
	v_fma_f32 v150, -s9, v146, v150
	s_nop 0
	s_nop 0
	v_readlane_b32 s6, v208, s73
	v_readlane_b32 s7, v207, s73
	v_readlane_b32 s8, v209, s73
	v_readlane_b32 s9, v205, s22
	v_fma_f32 v151, -s6, v170, v151
	v_fma_f32 v181, -s7, v144, v181
	v_fma_f32 v180, -s8, v166, v180
	v_fma_f32 v150, -s9, v142, v150
	s_nop 0
	s_nop 0
	v_readlane_b32 s6, v208, s22
	v_readlane_b32 s7, v207, s22
	v_readlane_b32 s8, v209, s22
	v_fma_f32 v151, -s6, v158, v151
	v_fma_f32 v181, -s7, v140, v181
	v_fma_f32 v180, -s8, v152, v180
	s_nop 0
	s_nop 0
	s_nop 0
	s_nop 0
	s_nop 0
	s_nop 0
	s_nop 0
	s_nop 0
	s_nop 0
	s_nop 0
	s_nop 0
	s_nop 0
	s_nop 0
	s_nop 0
	s_nop 0
	s_nop 0
	s_nop 1
	s_nop 0
	s_nop 0
	s_nop 1
	s_nop 0
	s_nop 0
	s_nop 1
	s_nop 0
	v_pk_add_f32 v[150:151], v[180:181], v[150:151]
	v_mov_b32_e32 v181, v123
	v_mov_b32_e32 v180, v123
	v_pk_add_f32 v[150:151], v[150:151], v[150:151] op_sel:[0,1] op_sel_hi:[1,0]
	s_nop 0
	s_waitcnt lgkmcnt(0)
	v_sub_f32_e32 v177, v177, v246
	ds_read_b32 v247, v249 offset:72
	s_nop 0
	v_readlane_b32 s6, v201, s64
	v_readlane_b32 s7, v204, s64
	v_readlane_b32 s8, v203, s64
	v_readlane_b32 s9, v206, s64
	v_fma_f32 v177, -s6, v150, v177
	v_fma_f32 v181, -s7, v178, v181
	v_fma_f32 v180, -s8, v148, v180
	v_fma_f32 v176, -s9, v174, v176
	v_mov_b32_e32 v151, v178
	s_nop 0
	v_readlane_b32 s6, v205, s50
	v_readlane_b32 s7, v208, s50
	v_readlane_b32 s8, v207, s50
	v_readlane_b32 s9, v209, s50
	v_fma_f32 v177, -s6, v146, v177
	v_fma_f32 v181, -s7, v170, v181
	v_fma_f32 v180, -s8, v144, v180
	v_fma_f32 v176, -s9, v166, v176
	s_nop 0
	s_nop 0
	v_readlane_b32 s6, v205, s64
	v_readlane_b32 s7, v208, s64
	v_readlane_b32 s8, v207, s64
	v_readlane_b32 s9, v209, s64
	v_fma_f32 v177, -s6, v142, v177
	v_fma_f32 v181, -s7, v158, v181
	v_fma_f32 v180, -s8, v140, v180
	v_fma_f32 v176, -s9, v152, v176
	s_nop 0
	s_nop 0
	s_nop 0
	s_nop 0
	s_nop 0
	s_nop 0
	s_nop 0
	s_nop 0
	s_nop 0
	s_nop 0
	s_nop 0
	s_nop 0
	s_nop 0
	s_nop 0
	s_nop 0
	s_nop 0
	s_nop 0
	v_pk_add_f32 v[176:177], v[180:181], v[176:177]
	v_mov_b32_e32 v181, v123
	v_mov_b32_e32 v180, v123
	v_pk_add_f32 v[176:177], v[176:177], v[176:177] op_sel:[0,1] op_sel_hi:[1,0]
	s_nop 0
	s_waitcnt lgkmcnt(0)
	v_sub_f32_e32 v157, v157, v247
	ds_read_b32 v246, v249 offset:68
	s_nop 0
	v_readlane_b32 s6, v206, s49
	v_readlane_b32 s7, v201, s65
	v_readlane_b32 s8, v204, s65
	v_readlane_b32 s9, v203, s65
	v_fma_f32 v157, -s6, v176, v157
	v_fma_f32 v181, -s7, v150, v181
	v_fma_f32 v180, -s8, v178, v180
	v_fma_f32 v156, -s9, v148, v156
	s_nop 0
	s_nop 0
	v_readlane_b32 s6, v206, s65
	v_readlane_b32 s7, v205, s49
	v_readlane_b32 s8, v208, s49
	v_readlane_b32 s9, v207, s49
	v_fma_f32 v157, -s6, v174, v157
	v_fma_f32 v181, -s7, v146, v181
	v_fma_f32 v180, -s8, v170, v180
	v_fma_f32 v156, -s9, v144, v156
	s_nop 0
	s_nop 0
	v_readlane_b32 s6, v209, s49
	v_readlane_b32 s7, v205, s65
	v_readlane_b32 s8, v208, s65
	v_readlane_b32 s9, v207, s65
	v_fma_f32 v157, -s6, v166, v157
	v_fma_f32 v181, -s7, v142, v181
	v_fma_f32 v180, -s8, v158, v180
	v_fma_f32 v156, -s9, v140, v156
	s_nop 0
	s_nop 0
	v_readlane_b32 s6, v209, s65
	s_nop 1
	v_fma_f32 v157, -s6, v152, v157
	s_nop 0
	s_nop 0
	s_nop 0
	s_nop 0
	s_nop 0
	s_nop 0
	s_nop 0
	s_nop 0
	s_nop 0
	s_nop 0
	s_nop 0
	s_nop 0
	s_nop 0
	s_nop 0
	s_nop 0
	s_nop 0
	s_nop 1
	s_nop 0
	v_pk_add_f32 v[156:157], v[180:181], v[156:157]
	v_mov_b32_e32 v181, v123
	v_mov_b32_e32 v180, v123
	v_pk_add_f32 v[156:157], v[156:157], v[156:157] op_sel:[0,1] op_sel_hi:[1,0]
	s_nop 0
	s_waitcnt lgkmcnt(0)
	v_sub_f32_e32 v173, v173, v246
	ds_read_b32 v247, v249 offset:64
	s_nop 0
	v_readlane_b32 s6, v203, s48
	v_readlane_b32 s7, v206, s48
	v_readlane_b32 s8, v201, s21
	v_readlane_b32 s9, v204, s21
	v_fma_f32 v173, -s6, v156, v173
	v_fma_f32 v181, -s7, v176, v181
	v_fma_f32 v180, -s8, v150, v180
	v_fma_f32 v172, -s9, v178, v172
	v_mov_b32_e32 v157, v176
	s_nop 0
	v_readlane_b32 s6, v203, s21
	v_readlane_b32 s7, v206, s21
	v_readlane_b32 s8, v205, s48
	v_readlane_b32 s9, v208, s48
	v_fma_f32 v173, -s6, v148, v173
	v_fma_f32 v181, -s7, v174, v181
	v_fma_f32 v180, -s8, v146, v180
	v_fma_f32 v172, -s9, v170, v172
	s_nop 0
	s_nop 0
	v_readlane_b32 s6, v207, s48
	v_readlane_b32 s7, v209, s48
	v_readlane_b32 s8, v205, s21
	v_readlane_b32 s9, v208, s21
	v_fma_f32 v173, -s6, v144, v173
	v_fma_f32 v181, -s7, v166, v181
	v_fma_f32 v180, -s8, v142, v180
	v_fma_f32 v172, -s9, v158, v172
	s_nop 0
	s_nop 0
	v_readlane_b32 s6, v207, s21
	v_readlane_b32 s7, v209, s21
	s_nop 0
	v_fma_f32 v173, -s6, v140, v173
	v_fma_f32 v181, -s7, v152, v181
	s_nop 0
	s_nop 0
	s_nop 0
	s_nop 0
	s_nop 0
	s_nop 0
	s_nop 0
	s_nop 0
	s_nop 0
	s_nop 0
	s_nop 0
	s_nop 0
	s_nop 0
	s_nop 0
	s_nop 0
	s_nop 0
	s_nop 1
	s_nop 0
	s_nop 0
	s_nop 1
	s_nop 0
	v_pk_add_f32 v[172:173], v[180:181], v[172:173]
	v_mov_b32_e32 v181, v123
	v_mov_b32_e32 v180, v123
	v_pk_add_f32 v[172:173], v[172:173], v[172:173] op_sel:[0,1] op_sel_hi:[1,0]
	s_nop 0
	s_waitcnt lgkmcnt(0)
	v_sub_f32_e32 v165, v165, v247
	ds_read_b32 v246, v249 offset:60
	s_nop 0
	v_readlane_b32 s6, v204, s47
	v_readlane_b32 s7, v203, s47
	v_readlane_b32 s8, v206, s47
	v_readlane_b32 s9, v201, s34
	v_fma_f32 v165, -s6, v172, v165
	v_fma_f32 v181, -s7, v156, v181
	v_fma_f32 v180, -s8, v176, v180
	v_fma_f32 v164, -s9, v150, v164
	s_nop 0
	s_nop 0
	v_readlane_b32 s6, v204, s34
	v_readlane_b32 s7, v203, s34
	v_readlane_b32 s8, v206, s34
	v_readlane_b32 s9, v205, s47
	v_fma_f32 v165, -s6, v178, v165
	v_fma_f32 v181, -s7, v148, v181
	v_fma_f32 v180, -s8, v174, v180
	v_fma_f32 v164, -s9, v146, v164
	s_nop 0
	s_nop 0
	v_readlane_b32 s6, v208, s47
	v_readlane_b32 s7, v207, s47
	v_readlane_b32 s8, v209, s47
	v_readlane_b32 s9, v205, s34
	v_fma_f32 v165, -s6, v170, v165
	v_fma_f32 v181, -s7, v144, v181
	v_fma_f32 v180, -s8, v166, v180
	v_fma_f32 v164, -s9, v142, v164
	s_nop 0
	s_nop 0
	v_readlane_b32 s6, v208, s34
	v_readlane_b32 s7, v207, s34
	v_readlane_b32 s8, v209, s34
	v_fma_f32 v165, -s6, v158, v165
	v_fma_f32 v181, -s7, v140, v181
	v_fma_f32 v180, -s8, v152, v180
	s_nop 0
	s_nop 0
	s_nop 0
	s_nop 0
	s_nop 0
	s_nop 0
	s_nop 0
	s_nop 0
	s_nop 0
	s_nop 0
	s_nop 0
	s_nop 0
	s_nop 0
	s_nop 0
	s_nop 0
	s_nop 0
	s_nop 1
	s_nop 0
	s_nop 0
	s_nop 1
	s_nop 0
	s_nop 0
	s_nop 1
	s_nop 0
	v_pk_add_f32 v[164:165], v[180:181], v[164:165]
	v_mov_b32_e32 v181, v123
	v_mov_b32_e32 v180, v123
	v_pk_add_f32 v[164:165], v[164:165], v[164:165] op_sel:[0,1] op_sel_hi:[1,0]
	s_nop 0
	s_waitcnt lgkmcnt(0)
	v_sub_f32_e32 v169, v169, v246
	ds_read_b32 v247, v249 offset:56
	s_nop 0
	v_readlane_b32 s6, v201, s45
	v_readlane_b32 s7, v204, s45
	v_readlane_b32 s8, v203, s45
	v_readlane_b32 s9, v206, s45
	v_fma_f32 v169, -s6, v164, v169
	v_fma_f32 v181, -s7, v172, v181
	v_fma_f32 v180, -s8, v156, v180
	v_fma_f32 v168, -s9, v176, v168
	v_mov_b32_e32 v165, v172
	s_nop 0
	v_readlane_b32 s6, v201, s66
	v_readlane_b32 s7, v204, s66
	v_readlane_b32 s8, v203, s66
	v_readlane_b32 s9, v206, s66
	v_fma_f32 v169, -s6, v150, v169
	v_fma_f32 v181, -s7, v178, v181
	v_fma_f32 v180, -s8, v148, v180
	v_fma_f32 v168, -s9, v174, v168
	s_nop 0
	s_nop 0
	v_readlane_b32 s6, v205, s45
	v_readlane_b32 s7, v208, s45
	v_readlane_b32 s8, v207, s45
	v_readlane_b32 s9, v209, s45
	v_fma_f32 v169, -s6, v146, v169
	v_fma_f32 v181, -s7, v170, v181
	v_fma_f32 v180, -s8, v144, v180
	v_fma_f32 v168, -s9, v166, v168
	s_nop 0
	s_nop 0
	v_readlane_b32 s6, v205, s66
	v_readlane_b32 s7, v208, s66
	v_readlane_b32 s8, v207, s66
	v_readlane_b32 s9, v209, s66
	v_fma_f32 v169, -s6, v142, v169
	v_fma_f32 v181, -s7, v158, v181
	v_fma_f32 v180, -s8, v140, v180
	v_fma_f32 v168, -s9, v152, v168
	s_nop 0
	s_nop 0
	s_nop 0
	s_nop 0
	s_nop 0
	s_nop 0
	s_nop 0
	s_nop 0
	s_nop 0
	s_nop 0
	s_nop 0
	s_nop 0
	s_nop 0
	s_nop 0
	s_nop 0
	s_nop 0
	s_nop 0
	v_pk_add_f32 v[168:169], v[180:181], v[168:169]
	s_nop 0
	v_pk_add_f32 v[180:181], v[168:169], v[168:169] op_sel:[0,1] op_sel_hi:[1,0]
	v_mov_b32_e32 v169, v123
	v_mov_b32_e32 v168, v123
	s_waitcnt lgkmcnt(0)
	v_sub_f32_e32 v163, v163, v247
	ds_read_b32 v246, v249 offset:52
	s_nop 0
	v_readlane_b32 s6, v202, s14
	v_readlane_b32 s7, v201, s39
	v_readlane_b32 s8, v204, s39
	v_readlane_b32 s9, v203, s39
	v_fma_f32 v163, -s6, v180, v163
	v_fma_f32 v169, -s7, v164, v169
	v_fma_f32 v168, -s8, v172, v168
	v_fma_f32 v162, -s9, v156, v162
	s_nop 0
	s_nop 0
	v_readlane_b32 s6, v206, s39
	v_readlane_b32 s7, v201, s14
	v_readlane_b32 s8, v204, s14
	v_readlane_b32 s9, v203, s14
	v_fma_f32 v163, -s6, v176, v163
	v_fma_f32 v169, -s7, v150, v169
	v_fma_f32 v168, -s8, v178, v168
	v_fma_f32 v162, -s9, v148, v162
	s_nop 0
	s_nop 0
	v_readlane_b32 s6, v206, s14
	v_readlane_b32 s7, v205, s39
	v_readlane_b32 s8, v208, s39
	v_readlane_b32 s9, v207, s39
	v_fma_f32 v163, -s6, v174, v163
	v_fma_f32 v169, -s7, v146, v169
	v_fma_f32 v168, -s8, v170, v168
	v_fma_f32 v162, -s9, v144, v162
	s_nop 0
	s_nop 0
	v_readlane_b32 s6, v209, s39
	v_readlane_b32 s7, v205, s14
	v_readlane_b32 s8, v208, s14
	v_readlane_b32 s9, v207, s14
	v_fma_f32 v163, -s6, v166, v163
	v_fma_f32 v169, -s7, v142, v169
	v_fma_f32 v168, -s8, v158, v168
	v_fma_f32 v162, -s9, v140, v162
	s_nop 0
	s_nop 0
	v_readlane_b32 s6, v209, s14
	s_nop 1
	v_fma_f32 v163, -s6, v152, v163
	s_nop 0
	s_nop 0
	s_nop 0
	s_nop 0
	s_nop 0
	s_nop 0
	s_nop 0
	s_nop 0
	s_nop 0
	s_nop 0
	s_nop 0
	s_nop 0
	s_nop 0
	s_nop 0
	s_nop 0
	s_nop 0
	s_nop 1
	s_nop 0
	v_pk_add_f32 v[162:163], v[168:169], v[162:163]
	v_mov_b32_e32 v169, v123
	v_mov_b32_e32 v168, v123
	v_pk_add_f32 v[162:163], v[162:163], v[162:163] op_sel:[0,1] op_sel_hi:[1,0]
	s_nop 0
	s_waitcnt lgkmcnt(0)
	v_sub_f32_e32 v161, v161, v246
	ds_read_b32 v247, v249 offset:48
	s_nop 0
	v_readlane_b32 s6, v199, s11
	v_readlane_b32 s7, v202, s11
	v_readlane_b32 s8, v201, s38
	v_readlane_b32 s9, v204, s38
	v_fma_f32 v161, -s6, v162, v161
	v_fma_f32 v169, -s7, v180, v169
	v_fma_f32 v168, -s8, v164, v168
	v_fma_f32 v160, -s9, v172, v160
	v_mov_b32_e32 v163, v180
	s_nop 0
	v_readlane_b32 s6, v203, s38
	v_readlane_b32 s7, v206, s38
	v_readlane_b32 s8, v201, s11
	v_readlane_b32 s9, v204, s11
	v_fma_f32 v161, -s6, v156, v161
	v_fma_f32 v169, -s7, v176, v169
	v_fma_f32 v168, -s8, v150, v168
	v_fma_f32 v160, -s9, v178, v160
	s_nop 0
	s_nop 0
	v_readlane_b32 s6, v203, s11
	v_readlane_b32 s7, v206, s11
	v_readlane_b32 s8, v205, s38
	v_readlane_b32 s9, v208, s38
	v_fma_f32 v161, -s6, v148, v161
	v_fma_f32 v169, -s7, v174, v169
	v_fma_f32 v168, -s8, v146, v168
	v_fma_f32 v160, -s9, v170, v160
	s_nop 0
	s_nop 0
	v_readlane_b32 s6, v207, s38
	v_readlane_b32 s7, v209, s38
	v_readlane_b32 s8, v205, s11
	v_readlane_b32 s9, v208, s11
	v_fma_f32 v161, -s6, v144, v161
	v_fma_f32 v169, -s7, v166, v169
	v_fma_f32 v168, -s8, v142, v168
	v_fma_f32 v160, -s9, v158, v160
	s_nop 0
	s_nop 0
	v_readlane_b32 s6, v207, s11
	v_readlane_b32 s7, v209, s11
	s_nop 0
	v_fma_f32 v161, -s6, v140, v161
	v_fma_f32 v169, -s7, v152, v169
	s_nop 0
	s_nop 0
	s_nop 0
	s_nop 0
	s_nop 0
	s_nop 0
	s_nop 0
	s_nop 0
	s_nop 0
	s_nop 0
	s_nop 0
	s_nop 0
	s_nop 0
	s_nop 0
	s_nop 0
	s_nop 0
	s_nop 1
	s_nop 0
	s_nop 0
	s_nop 1
	s_nop 0
	v_pk_add_f32 v[160:161], v[168:169], v[160:161]
	s_nop 0
	v_pk_add_f32 v[184:185], v[160:161], v[160:161] op_sel:[0,1] op_sel_hi:[1,0]
	v_mov_b32_e32 v161, v123
	v_mov_b32_e32 v160, v123
	s_waitcnt lgkmcnt(0)
	v_sub_f32_e32 v155, v155, v247
	ds_read_b32 v246, v249 offset:44
	s_nop 0
	v_readlane_b32 s6, v200, s27
	v_readlane_b32 s7, v199, s27
	v_readlane_b32 s8, v202, s27
	v_readlane_b32 s9, v201, s43
	v_fma_f32 v155, -s6, v184, v155
	v_fma_f32 v161, -s7, v162, v161
	v_fma_f32 v160, -s8, v180, v160
	v_fma_f32 v154, -s9, v164, v154
	s_nop 0
	s_nop 0
	v_readlane_b32 s6, v204, s43
	v_readlane_b32 s7, v203, s43
	v_readlane_b32 s8, v206, s43
	v_readlane_b32 s9, v201, s27
	v_fma_f32 v155, -s6, v172, v155
	v_fma_f32 v161, -s7, v156, v161
	v_fma_f32 v160, -s8, v176, v160
	v_fma_f32 v154, -s9, v150, v154
	s_nop 0
	s_nop 0
	v_readlane_b32 s6, v204, s27
	v_readlane_b32 s7, v203, s27
	v_readlane_b32 s8, v206, s27
	v_readlane_b32 s9, v205, s43
	v_fma_f32 v155, -s6, v178, v155
	v_fma_f32 v161, -s7, v148, v161
	v_fma_f32 v160, -s8, v174, v160
	v_fma_f32 v154, -s9, v146, v154
	s_nop 0
	s_nop 0
	v_readlane_b32 s6, v208, s43
	v_readlane_b32 s7, v207, s43
	v_readlane_b32 s8, v209, s43
	v_readlane_b32 s9, v205, s27
	v_fma_f32 v155, -s6, v170, v155
	v_fma_f32 v161, -s7, v144, v161
	v_fma_f32 v160, -s8, v166, v160
	v_fma_f32 v154, -s9, v142, v154
	s_nop 0
	s_nop 0
	v_readlane_b32 s6, v208, s27
	v_readlane_b32 s7, v207, s27
	v_readlane_b32 s8, v209, s27
	v_fma_f32 v155, -s6, v158, v155
	v_fma_f32 v161, -s7, v140, v161
	v_fma_f32 v160, -s8, v152, v160
	s_nop 0
	s_nop 0
	s_nop 0
	s_nop 0
	s_nop 0
	s_nop 0
	s_nop 0
	s_nop 0
	s_nop 0
	s_nop 0
	s_nop 0
	s_nop 0
	s_nop 0
	s_nop 0
	s_nop 0
	s_nop 0
	s_nop 1
	s_nop 0
	s_nop 0
	s_nop 1
	s_nop 0
	s_nop 0
	s_nop 1
	s_nop 0
	v_pk_add_f32 v[154:155], v[160:161], v[154:155]
	v_mov_b32_e32 v161, v123
	v_mov_b32_e32 v160, v123
	v_pk_add_f32 v[154:155], v[154:155], v[154:155] op_sel:[0,1] op_sel_hi:[1,0]
	s_nop 0
	s_waitcnt lgkmcnt(0)
	v_sub_f32_e32 v85, v85, v246
	ds_read_b32 v247, v249 offset:40
	s_nop 0
	v_readlane_b32 s6, v197, s67
	v_readlane_b32 s7, v200, s67
	v_readlane_b32 s8, v199, s67
	v_readlane_b32 s9, v202, s67
	v_fma_f32 v85, -s6, v154, v85
	v_fma_f32 v161, -s7, v184, v161
	v_fma_f32 v160, -s8, v162, v160
	v_fma_f32 v84, -s9, v180, v84
	v_mov_b32_e32 v155, v184
	s_nop 0
	v_readlane_b32 s6, v201, s42
	v_readlane_b32 s7, v204, s42
	v_readlane_b32 s8, v203, s42
	v_readlane_b32 s9, v206, s42
	v_fma_f32 v85, -s6, v164, v85
	v_fma_f32 v161, -s7, v172, v161
	v_fma_f32 v160, -s8, v156, v160
	v_fma_f32 v84, -s9, v176, v84
	s_nop 0
	s_nop 0
	v_readlane_b32 s6, v201, s67
	v_readlane_b32 s7, v204, s67
	v_readlane_b32 s8, v203, s67
	v_readlane_b32 s9, v206, s67
	v_fma_f32 v85, -s6, v150, v85
	v_fma_f32 v161, -s7, v178, v161
	v_fma_f32 v160, -s8, v148, v160
	v_fma_f32 v84, -s9, v174, v84
	s_nop 0
	s_nop 0
	v_readlane_b32 s6, v205, s42
	v_readlane_b32 s7, v208, s42
	v_readlane_b32 s8, v207, s42
	v_readlane_b32 s9, v209, s42
	v_fma_f32 v85, -s6, v146, v85
	v_fma_f32 v161, -s7, v170, v161
	v_fma_f32 v160, -s8, v144, v160
	v_fma_f32 v84, -s9, v166, v84
	s_nop 0
	s_nop 0
	v_readlane_b32 s6, v205, s67
	v_readlane_b32 s7, v208, s67
	v_readlane_b32 s8, v207, s67
	v_readlane_b32 s9, v209, s67
	v_fma_f32 v85, -s6, v142, v85
	v_fma_f32 v161, -s7, v158, v161
	v_fma_f32 v160, -s8, v140, v160
	v_fma_f32 v84, -s9, v152, v84
	s_nop 0
	s_nop 0
	s_nop 0
	s_nop 0
	s_nop 0
	s_nop 0
	s_nop 0
	s_nop 0
	s_nop 0
	s_nop 0
	s_nop 0
	s_nop 0
	s_nop 0
	s_nop 0
	s_nop 0
	s_nop 0
	s_nop 0
	v_pk_add_f32 v[84:85], v[160:161], v[84:85]
	v_mov_b32_e32 v161, v123
	v_mov_b32_e32 v160, v123
	v_pk_add_f32 v[84:85], v[84:85], v[84:85] op_sel:[0,1] op_sel_hi:[1,0]
	s_nop 0
	s_waitcnt lgkmcnt(0)
	v_sub_f32_e32 v83, v83, v247
	ds_read_b32 v246, v249 offset:36
	s_nop 0
	v_readlane_b32 s6, v202, s46
	v_readlane_b32 s7, v197, s2
	v_readlane_b32 s8, v200, s2
	v_readlane_b32 s9, v199, s2
	v_fma_f32 v83, -s6, v84, v83
	v_fma_f32 v161, -s7, v154, v161
	v_fma_f32 v160, -s8, v184, v160
	v_fma_f32 v82, -s9, v162, v82
	s_nop 0
	s_nop 0
	v_readlane_b32 s6, v202, s2
	v_readlane_b32 s7, v201, s46
	v_readlane_b32 s8, v204, s46
	v_readlane_b32 s9, v203, s46
	v_fma_f32 v83, -s6, v180, v83
	v_fma_f32 v161, -s7, v164, v161
	v_fma_f32 v160, -s8, v172, v160
	v_fma_f32 v82, -s9, v156, v82
	s_nop 0
	s_nop 0
	v_readlane_b32 s6, v206, s46
	v_readlane_b32 s7, v201, s2
	v_readlane_b32 s8, v204, s2
	v_readlane_b32 s9, v203, s2
	v_fma_f32 v83, -s6, v176, v83
	v_fma_f32 v161, -s7, v150, v161
	v_fma_f32 v160, -s8, v178, v160
	v_fma_f32 v82, -s9, v148, v82
	s_nop 0
	s_nop 0
	v_readlane_b32 s6, v206, s2
	v_readlane_b32 s7, v205, s46
	v_readlane_b32 s8, v208, s46
	v_readlane_b32 s9, v207, s46
	v_fma_f32 v83, -s6, v174, v83
	v_fma_f32 v161, -s7, v146, v161
	v_fma_f32 v160, -s8, v170, v160
	v_fma_f32 v82, -s9, v144, v82
	s_nop 0
	s_nop 0
	v_readlane_b32 s6, v209, s46
	v_readlane_b32 s7, v205, s2
	v_readlane_b32 s8, v208, s2
	v_readlane_b32 s9, v207, s2
	v_fma_f32 v83, -s6, v166, v83
	v_fma_f32 v161, -s7, v142, v161
	v_fma_f32 v160, -s8, v158, v160
	v_fma_f32 v82, -s9, v140, v82
	s_nop 0
	s_nop 0
	v_readlane_b32 s6, v209, s2
	s_nop 1
	v_fma_f32 v83, -s6, v152, v83
	s_nop 0
	s_nop 0
	s_nop 0
	s_nop 0
	s_nop 0
	s_nop 0
	s_nop 0
	s_nop 0
	s_nop 0
	s_nop 0
	s_nop 0
	s_nop 0
	s_nop 0
	s_nop 0
	s_nop 0
	s_nop 0
	s_nop 1
	s_nop 0
	v_pk_add_f32 v[82:83], v[160:161], v[82:83]
	s_nop 0
	v_pk_add_f32 v[160:161], v[82:83], v[82:83] op_sel:[0,1] op_sel_hi:[1,0]
	v_mov_b32_e32 v83, v123
	v_mov_b32_e32 v82, v123
	s_waitcnt lgkmcnt(0)
	v_sub_f32_e32 v79, v79, v246
	ds_read_b32 v247, v249 offset:32
	s_nop 0
	v_readlane_b32 s6, v199, s37
	v_readlane_b32 s7, v202, s37
	v_readlane_b32 s8, v197, s18
	v_readlane_b32 s9, v200, s18
	v_fma_f32 v79, -s6, v160, v79
	v_fma_f32 v83, -s7, v84, v83
	v_fma_f32 v82, -s8, v154, v82
	v_fma_f32 v78, -s9, v184, v78
	v_mov_b32_e32 v161, v84
	s_nop 0
	v_readlane_b32 s6, v199, s18
	v_readlane_b32 s7, v202, s18
	v_readlane_b32 s8, v201, s37
	v_readlane_b32 s9, v204, s37
	v_fma_f32 v79, -s6, v162, v79
	v_fma_f32 v83, -s7, v180, v83
	v_fma_f32 v82, -s8, v164, v82
	v_fma_f32 v78, -s9, v172, v78
	s_nop 0
	s_nop 0
	v_readlane_b32 s6, v203, s37
	v_readlane_b32 s7, v206, s37
	v_readlane_b32 s8, v201, s18
	v_readlane_b32 s9, v204, s18
	v_fma_f32 v79, -s6, v156, v79
	v_fma_f32 v83, -s7, v176, v83
	v_fma_f32 v82, -s8, v150, v82
	v_fma_f32 v78, -s9, v178, v78
	s_nop 0
	s_nop 0
	v_readlane_b32 s6, v203, s18
	v_readlane_b32 s7, v206, s18
	v_readlane_b32 s8, v205, s37
	v_readlane_b32 s9, v208, s37
	v_fma_f32 v79, -s6, v148, v79
	v_fma_f32 v83, -s7, v174, v83
	v_fma_f32 v82, -s8, v146, v82
	v_fma_f32 v78, -s9, v170, v78
	s_nop 0
	s_nop 0
	v_readlane_b32 s6, v207, s37
	v_readlane_b32 s7, v209, s37
	v_readlane_b32 s8, v205, s18
	v_readlane_b32 s9, v208, s18
	v_fma_f32 v79, -s6, v144, v79
	v_fma_f32 v83, -s7, v166, v83
	v_fma_f32 v82, -s8, v142, v82
	v_fma_f32 v78, -s9, v158, v78
	s_nop 0
	s_nop 0
	v_readlane_b32 s6, v207, s18
	v_readlane_b32 s7, v209, s18
	s_nop 0
	v_fma_f32 v79, -s6, v140, v79
	v_fma_f32 v83, -s7, v152, v83
	s_nop 0
	s_nop 0
	s_nop 0
	s_nop 0
	s_nop 0
	s_nop 0
	s_nop 0
	s_nop 0
	s_nop 0
	s_nop 0
	s_nop 0
	s_nop 0
	s_nop 0
	s_nop 0
	s_nop 0
	s_nop 0
	s_nop 1
	s_nop 0
	s_nop 0
	s_nop 1
	s_nop 0
	v_pk_add_f32 v[78:79], v[82:83], v[78:79]
	v_mov_b32_e32 v83, v123
	v_mov_b32_e32 v82, v123
	v_pk_add_f32 v[78:79], v[78:79], v[78:79] op_sel:[0,1] op_sel_hi:[1,0]
	s_nop 0
	s_waitcnt lgkmcnt(0)
	v_sub_f32_e32 v75, v75, v247
	ds_read_b32 v246, v249 offset:28
	s_nop 0
	v_readlane_b32 s6, v200, s40
	v_readlane_b32 s7, v199, s40
	v_readlane_b32 s8, v202, s40
	v_readlane_b32 s9, v197, s19
	v_fma_f32 v75, -s6, v78, v75
	v_fma_f32 v83, -s7, v160, v83
	v_fma_f32 v82, -s8, v84, v82
	v_fma_f32 v74, -s9, v154, v74
	s_nop 0
	s_nop 0
	v_readlane_b32 s6, v200, s19
	v_readlane_b32 s7, v199, s19
	v_readlane_b32 s8, v202, s19
	v_readlane_b32 s9, v201, s40
	v_fma_f32 v75, -s6, v184, v75
	v_fma_f32 v83, -s7, v162, v83
	v_fma_f32 v82, -s8, v180, v82
	v_fma_f32 v74, -s9, v164, v74
	s_nop 0
	s_nop 0
	v_readlane_b32 s6, v204, s40
	v_readlane_b32 s7, v203, s40
	v_readlane_b32 s8, v206, s40
	v_readlane_b32 s9, v201, s19
	v_fma_f32 v75, -s6, v172, v75
	v_fma_f32 v83, -s7, v156, v83
	v_fma_f32 v82, -s8, v176, v82
	v_fma_f32 v74, -s9, v150, v74
	s_nop 0
	s_nop 0
	v_readlane_b32 s6, v204, s19
	v_readlane_b32 s7, v203, s19
	v_readlane_b32 s8, v206, s19
	v_readlane_b32 s9, v205, s40
	v_fma_f32 v75, -s6, v178, v75
	v_fma_f32 v83, -s7, v148, v83
	v_fma_f32 v82, -s8, v174, v82
	v_fma_f32 v74, -s9, v146, v74
	s_nop 0
	s_nop 0
	v_readlane_b32 s6, v208, s40
	v_readlane_b32 s7, v207, s40
	v_readlane_b32 s8, v209, s40
	v_readlane_b32 s9, v205, s19
	v_fma_f32 v75, -s6, v170, v75
	v_fma_f32 v83, -s7, v144, v83
	v_fma_f32 v82, -s8, v166, v82
	v_fma_f32 v74, -s9, v142, v74
	s_nop 0
	s_nop 0
	v_readlane_b32 s6, v208, s19
	v_readlane_b32 s7, v207, s19
	v_readlane_b32 s8, v209, s19
	v_fma_f32 v75, -s6, v158, v75
	v_fma_f32 v83, -s7, v140, v83
	v_fma_f32 v82, -s8, v152, v82
	s_nop 0
	s_nop 0
	s_nop 0
	s_nop 0
	s_nop 0
	s_nop 0
	s_nop 0
	s_nop 0
	s_nop 0
	s_nop 0
	s_nop 0
	s_nop 0
	s_nop 0
	s_nop 0
	s_nop 0
	s_nop 0
	s_nop 1
	s_nop 0
	s_nop 0
	s_nop 1
	s_nop 0
	s_nop 0
	s_nop 1
	s_nop 0
	v_pk_add_f32 v[74:75], v[82:83], v[74:75]
	s_nop 0
	v_pk_add_f32 v[168:169], v[74:75], v[74:75] op_sel:[0,1] op_sel_hi:[1,0]
	v_mov_b32_e32 v75, v123
	v_mov_b32_e32 v74, v123
	s_waitcnt lgkmcnt(0)
	v_sub_f32_e32 v71, v71, v246
	ds_read_b32 v247, v249 offset:24
	s_nop 0
	v_readlane_b32 s6, v197, s44
	v_readlane_b32 s7, v200, s44
	v_readlane_b32 s8, v199, s44
	v_readlane_b32 s9, v202, s44
	v_fma_f32 v71, -s6, v168, v71
	v_fma_f32 v75, -s7, v78, v75
	v_fma_f32 v74, -s8, v160, v74
	v_fma_f32 v70, -s9, v84, v70
	v_mov_b32_e32 v169, v78
	s_nop 0
	v_readlane_b32 s6, v197, s68
	v_readlane_b32 s7, v200, s68
	v_readlane_b32 s8, v199, s68
	v_readlane_b32 s9, v202, s68
	v_fma_f32 v71, -s6, v154, v71
	v_fma_f32 v75, -s7, v184, v75
	v_fma_f32 v74, -s8, v162, v74
	v_fma_f32 v70, -s9, v180, v70
	s_nop 0
	s_nop 0
	v_readlane_b32 s6, v201, s44
	v_readlane_b32 s7, v204, s44
	v_readlane_b32 s8, v203, s44
	v_readlane_b32 s9, v206, s44
	v_fma_f32 v71, -s6, v164, v71
	v_fma_f32 v75, -s7, v172, v75
	v_fma_f32 v74, -s8, v156, v74
	v_fma_f32 v70, -s9, v176, v70
	s_nop 0
	s_nop 0
	v_readlane_b32 s6, v201, s68
	v_readlane_b32 s7, v204, s68
	v_readlane_b32 s8, v203, s68
	v_readlane_b32 s9, v206, s68
	v_fma_f32 v71, -s6, v150, v71
	v_fma_f32 v75, -s7, v178, v75
	v_fma_f32 v74, -s8, v148, v74
	v_fma_f32 v70, -s9, v174, v70
	s_nop 0
	s_nop 0
	v_readlane_b32 s6, v205, s44
	v_readlane_b32 s7, v208, s44
	v_readlane_b32 s8, v207, s44
	v_readlane_b32 s9, v209, s44
	v_fma_f32 v71, -s6, v146, v71
	v_fma_f32 v75, -s7, v170, v75
	v_fma_f32 v74, -s8, v144, v74
	v_fma_f32 v70, -s9, v166, v70
	s_nop 0
	s_nop 0
	v_readlane_b32 s6, v205, s68
	v_readlane_b32 s7, v208, s68
	v_readlane_b32 s8, v207, s68
	v_readlane_b32 s9, v209, s68
	v_fma_f32 v71, -s6, v142, v71
	v_fma_f32 v75, -s7, v158, v75
	v_fma_f32 v74, -s8, v140, v74
	v_fma_f32 v70, -s9, v152, v70
	s_nop 0
	s_nop 0
	s_nop 0
	s_nop 0
	s_nop 0
	s_nop 0
	s_nop 0
	s_nop 0
	s_nop 0
	s_nop 0
	s_nop 0
	s_nop 0
	s_nop 0
	s_nop 0
	s_nop 0
	s_nop 0
	s_nop 0
	v_pk_add_f32 v[70:71], v[74:75], v[70:71]
	v_mov_b32_e32 v75, v123
	v_mov_b32_e32 v74, v123
	v_pk_add_f32 v[70:71], v[70:71], v[70:71] op_sel:[0,1] op_sel_hi:[1,0]
	s_nop 0
	s_waitcnt lgkmcnt(0)
	v_sub_f32_e32 v67, v67, v247
	ds_read_b32 v246, v249 offset:20
	s_nop 0
	v_readlane_b32 s6, v198, s3
	v_readlane_b32 s7, v197, s35
	v_readlane_b32 s8, v200, s35
	v_readlane_b32 s9, v199, s35
	v_fma_f32 v67, -s6, v70, v67
	v_fma_f32 v75, -s7, v168, v75
	v_fma_f32 v74, -s8, v78, v74
	v_fma_f32 v66, -s9, v160, v66
	s_nop 0
	s_nop 0
	v_readlane_b32 s6, v202, s35
	v_readlane_b32 s7, v197, s3
	v_readlane_b32 s8, v200, s3
	v_readlane_b32 s9, v199, s3
	v_fma_f32 v67, -s6, v84, v67
	v_fma_f32 v75, -s7, v154, v75
	v_fma_f32 v74, -s8, v184, v74
	v_fma_f32 v66, -s9, v162, v66
	s_nop 0
	s_nop 0
	v_readlane_b32 s6, v202, s3
	v_readlane_b32 s7, v201, s35
	v_readlane_b32 s8, v204, s35
	v_readlane_b32 s9, v203, s35
	v_fma_f32 v67, -s6, v180, v67
	v_fma_f32 v75, -s7, v164, v75
	v_fma_f32 v74, -s8, v172, v74
	v_fma_f32 v66, -s9, v156, v66
	s_nop 0
	s_nop 0
	v_readlane_b32 s6, v206, s35
	v_readlane_b32 s7, v201, s3
	v_readlane_b32 s8, v204, s3
	v_readlane_b32 s9, v203, s3
	v_fma_f32 v67, -s6, v176, v67
	v_fma_f32 v75, -s7, v150, v75
	v_fma_f32 v74, -s8, v178, v74
	v_fma_f32 v66, -s9, v148, v66
	s_nop 0
	s_nop 0
	v_readlane_b32 s6, v206, s3
	v_readlane_b32 s7, v205, s35
	v_readlane_b32 s8, v208, s35
	v_readlane_b32 s9, v207, s35
	v_fma_f32 v67, -s6, v174, v67
	v_fma_f32 v75, -s7, v146, v75
	v_fma_f32 v74, -s8, v170, v74
	v_fma_f32 v66, -s9, v144, v66
	s_nop 0
	s_nop 0
	v_readlane_b32 s6, v209, s35
	v_readlane_b32 s7, v205, s3
	v_readlane_b32 s8, v208, s3
	v_readlane_b32 s9, v207, s3
	v_fma_f32 v67, -s6, v166, v67
	v_fma_f32 v75, -s7, v142, v75
	v_fma_f32 v74, -s8, v158, v74
	v_fma_f32 v66, -s9, v140, v66
	s_nop 0
	s_nop 0
	v_readlane_b32 s6, v209, s3
	s_nop 1
	v_fma_f32 v67, -s6, v152, v67
	s_nop 0
	s_nop 0
	s_nop 0
	s_nop 0
	s_nop 0
	s_nop 0
	s_nop 0
	s_nop 0
	s_nop 0
	s_nop 0
	s_nop 0
	s_nop 0
	s_nop 0
	s_nop 0
	s_nop 0
	s_nop 0
	s_nop 1
	s_nop 0
	v_pk_add_f32 v[66:67], v[74:75], v[66:67]
	s_nop 0
	v_pk_add_f32 v[182:183], v[66:67], v[66:67] op_sel:[0,1] op_sel_hi:[1,0]
	v_mov_b32_e32 v67, v123
	v_mov_b32_e32 v66, v123
	s_waitcnt lgkmcnt(0)
	v_sub_f32_e32 v63, v63, v246
	ds_read_b32 v247, v249 offset:16
	s_nop 0
	v_readlane_b32 s6, v195, s16
	v_readlane_b32 s7, v198, s16
	v_readlane_b32 s8, v197, s30
	v_readlane_b32 s9, v200, s30
	v_fma_f32 v63, -s6, v182, v63
	v_fma_f32 v67, -s7, v70, v67
	v_fma_f32 v66, -s8, v168, v66
	v_fma_f32 v62, -s9, v78, v62
	v_mov_b32_e32 v183, v70
	s_nop 0
	v_readlane_b32 s6, v199, s30
	v_readlane_b32 s7, v202, s30
	v_readlane_b32 s8, v197, s16
	v_readlane_b32 s9, v200, s16
	v_fma_f32 v63, -s6, v160, v63
	v_fma_f32 v67, -s7, v84, v67
	v_fma_f32 v66, -s8, v154, v66
	v_fma_f32 v62, -s9, v184, v62
	s_nop 0
	s_nop 0
	v_readlane_b32 s6, v199, s16
	v_readlane_b32 s7, v202, s16
	v_readlane_b32 s8, v201, s30
	v_readlane_b32 s9, v204, s30
	v_fma_f32 v63, -s6, v162, v63
	v_fma_f32 v67, -s7, v180, v67
	v_fma_f32 v66, -s8, v164, v66
	v_fma_f32 v62, -s9, v172, v62
	s_nop 0
	s_nop 0
	v_readlane_b32 s6, v203, s30
	v_readlane_b32 s7, v206, s30
	v_readlane_b32 s8, v201, s16
	v_readlane_b32 s9, v204, s16
	v_fma_f32 v63, -s6, v156, v63
	v_fma_f32 v67, -s7, v176, v67
	v_fma_f32 v66, -s8, v150, v66
	v_fma_f32 v62, -s9, v178, v62
	s_nop 0
	s_nop 0
	v_readlane_b32 s6, v203, s16
	v_readlane_b32 s7, v206, s16
	v_readlane_b32 s8, v205, s30
	v_readlane_b32 s9, v208, s30
	v_fma_f32 v63, -s6, v148, v63
	v_fma_f32 v67, -s7, v174, v67
	v_fma_f32 v66, -s8, v146, v66
	v_fma_f32 v62, -s9, v170, v62
	s_nop 0
	s_nop 0
	v_readlane_b32 s6, v207, s30
	v_readlane_b32 s7, v209, s30
	v_readlane_b32 s8, v205, s16
	v_readlane_b32 s9, v208, s16
	v_fma_f32 v63, -s6, v144, v63
	v_fma_f32 v67, -s7, v166, v67
	v_fma_f32 v66, -s8, v142, v66
	v_fma_f32 v62, -s9, v158, v62
	s_nop 0
	s_nop 0
	v_readlane_b32 s6, v207, s16
	v_readlane_b32 s7, v209, s16
	s_nop 0
	v_fma_f32 v63, -s6, v140, v63
	v_fma_f32 v67, -s7, v152, v67
	s_nop 0
	s_nop 0
	s_nop 0
	s_nop 0
	s_nop 0
	s_nop 0
	s_nop 0
	s_nop 0
	s_nop 0
	s_nop 0
	s_nop 0
	s_nop 0
	s_nop 0
	s_nop 0
	s_nop 0
	s_nop 0
	s_nop 1
	s_nop 0
	s_nop 0
	s_nop 1
	s_nop 0
	v_pk_add_f32 v[62:63], v[66:67], v[62:63]
	v_mov_b32_e32 v67, v123
	v_mov_b32_e32 v66, v123
	v_pk_add_f32 v[62:63], v[62:63], v[62:63] op_sel:[0,1] op_sel_hi:[1,0]
	s_nop 0
	s_waitcnt lgkmcnt(0)
	v_sub_f32_e32 v29, v29, v247
	ds_read_b32 v246, v249 offset:12
	s_nop 0
	v_readlane_b32 s6, v196, s17
	v_readlane_b32 s7, v195, s17
	v_readlane_b32 s8, v198, s17
	v_readlane_b32 s9, v197, s36
	v_fma_f32 v29, -s6, v62, v29
	v_fma_f32 v67, -s7, v182, v67
	v_fma_f32 v66, -s8, v70, v66
	v_fma_f32 v28, -s9, v168, v28
	s_nop 0
	s_nop 0
	v_readlane_b32 s6, v200, s36
	v_readlane_b32 s7, v199, s36
	v_readlane_b32 s8, v202, s36
	v_readlane_b32 s9, v197, s17
	v_fma_f32 v29, -s6, v78, v29
	v_fma_f32 v67, -s7, v160, v67
	v_fma_f32 v66, -s8, v84, v66
	v_fma_f32 v28, -s9, v154, v28
	s_nop 0
	s_nop 0
	v_readlane_b32 s6, v200, s17
	v_readlane_b32 s7, v199, s17
	v_readlane_b32 s8, v202, s17
	v_readlane_b32 s9, v201, s36
	v_fma_f32 v29, -s6, v184, v29
	v_fma_f32 v67, -s7, v162, v67
	v_fma_f32 v66, -s8, v180, v66
	v_fma_f32 v28, -s9, v164, v28
	s_nop 0
	s_nop 0
	v_readlane_b32 s6, v204, s36
	v_readlane_b32 s7, v203, s36
	v_readlane_b32 s8, v206, s36
	v_readlane_b32 s9, v201, s17
	v_fma_f32 v29, -s6, v172, v29
	v_fma_f32 v67, -s7, v156, v67
	v_fma_f32 v66, -s8, v176, v66
	v_fma_f32 v28, -s9, v150, v28
	s_nop 0
	s_nop 0
	v_readlane_b32 s6, v204, s17
	v_readlane_b32 s7, v203, s17
	v_readlane_b32 s8, v206, s17
	v_readlane_b32 s9, v205, s36
	v_fma_f32 v29, -s6, v178, v29
	v_fma_f32 v67, -s7, v148, v67
	v_fma_f32 v66, -s8, v174, v66
	v_fma_f32 v28, -s9, v146, v28
	s_nop 0
	s_nop 0
	v_readlane_b32 s6, v208, s36
	v_readlane_b32 s7, v207, s36
	v_readlane_b32 s8, v209, s36
	v_readlane_b32 s9, v205, s17
	v_fma_f32 v29, -s6, v170, v29
	v_fma_f32 v67, -s7, v144, v67
	v_fma_f32 v66, -s8, v166, v66
	v_fma_f32 v28, -s9, v142, v28
	s_nop 0
	s_nop 0
	v_readlane_b32 s6, v208, s17
	v_readlane_b32 s7, v207, s17
	v_readlane_b32 s8, v209, s17
	v_fma_f32 v29, -s6, v158, v29
	v_fma_f32 v67, -s7, v140, v67
	v_fma_f32 v66, -s8, v152, v66
	s_nop 0
	s_nop 0
	s_nop 0
	s_nop 0
	s_nop 0
	s_nop 0
	s_nop 0
	s_nop 0
	s_nop 0
	s_nop 0
	s_nop 0
	s_nop 0
	s_nop 0
	s_nop 0
	s_nop 0
	s_nop 0
	s_nop 1
	s_nop 0
	s_nop 0
	s_nop 1
	s_nop 0
	s_nop 0
	s_nop 1
	s_nop 0
	v_pk_add_f32 v[28:29], v[66:67], v[28:29]
	s_nop 0
	v_pk_add_f32 v[186:187], v[28:29], v[28:29] op_sel:[0,1] op_sel_hi:[1,0]
	v_mov_b32_e32 v29, v123
	v_mov_b32_e32 v28, v123
	s_waitcnt lgkmcnt(0)
	v_sub_f32_e32 v25, v25, v246
	ds_read_b32 v247, v249 offset:8
	s_nop 0
	v_readlane_b32 s6, v194, s69
	v_readlane_b32 s7, v196, s69
	v_readlane_b32 s8, v195, s69
	v_readlane_b32 s9, v198, s69
	v_fma_f32 v25, -s6, v186, v25
	v_fma_f32 v29, -s7, v62, v29
	v_fma_f32 v28, -s8, v182, v28
	v_fma_f32 v24, -s9, v70, v24
	v_mov_b32_e32 v187, v62
	s_nop 0
	v_readlane_b32 s6, v197, s12
	v_readlane_b32 s7, v200, s12
	v_readlane_b32 s8, v199, s12
	v_readlane_b32 s9, v202, s12
	v_fma_f32 v25, -s6, v168, v25
	v_fma_f32 v29, -s7, v78, v29
	v_fma_f32 v28, -s8, v160, v28
	v_fma_f32 v24, -s9, v84, v24
	s_nop 0
	s_nop 0
	v_readlane_b32 s6, v197, s69
	v_readlane_b32 s7, v200, s69
	v_readlane_b32 s8, v199, s69
	v_readlane_b32 s9, v202, s69
	v_fma_f32 v25, -s6, v154, v25
	v_fma_f32 v29, -s7, v184, v29
	v_fma_f32 v28, -s8, v162, v28
	v_fma_f32 v24, -s9, v180, v24
	s_nop 0
	s_nop 0
	v_readlane_b32 s6, v201, s12
	v_readlane_b32 s7, v204, s12
	v_readlane_b32 s8, v203, s12
	v_readlane_b32 s9, v206, s12
	v_fma_f32 v25, -s6, v164, v25
	v_fma_f32 v29, -s7, v172, v29
	v_fma_f32 v28, -s8, v156, v28
	v_fma_f32 v24, -s9, v176, v24
	s_nop 0
	s_nop 0
	v_readlane_b32 s6, v201, s69
	v_readlane_b32 s7, v204, s69
	v_readlane_b32 s8, v203, s69
	v_readlane_b32 s9, v206, s69
	v_fma_f32 v25, -s6, v150, v25
	v_fma_f32 v29, -s7, v178, v29
	v_fma_f32 v28, -s8, v148, v28
	v_fma_f32 v24, -s9, v174, v24
	s_nop 0
	s_nop 0
	v_readlane_b32 s6, v205, s12
	v_readlane_b32 s7, v208, s12
	v_readlane_b32 s8, v207, s12
	v_readlane_b32 s9, v209, s12
	v_fma_f32 v25, -s6, v146, v25
	v_fma_f32 v29, -s7, v170, v29
	v_fma_f32 v28, -s8, v144, v28
	v_fma_f32 v24, -s9, v166, v24
	s_nop 0
	s_nop 0
	v_readlane_b32 s6, v205, s69
	v_readlane_b32 s7, v208, s69
	v_readlane_b32 s8, v207, s69
	v_readlane_b32 s9, v209, s69
	v_fma_f32 v25, -s6, v142, v25
	v_fma_f32 v29, -s7, v158, v29
	v_fma_f32 v28, -s8, v140, v28
	v_fma_f32 v24, -s9, v152, v24
	s_nop 0
	s_nop 0
	s_nop 0
	s_nop 0
	s_nop 0
	s_nop 0
	s_nop 0
	s_nop 0
	s_nop 0
	s_nop 0
	s_nop 0
	s_nop 0
	s_nop 0
	s_nop 0
	s_nop 0
	s_nop 0
	s_nop 0
	v_pk_add_f32 v[24:25], v[28:29], v[24:25]
	v_mov_b32_e32 v29, v123
	v_mov_b32_e32 v28, v123
	v_pk_add_f32 v[24:25], v[24:25], v[24:25] op_sel:[0,1] op_sel_hi:[1,0]
	s_nop 0
	s_waitcnt lgkmcnt(0)
	v_sub_f32_e32 v15, v15, v247
	ds_read_b32 v246, v249 offset:4
	s_nop 0
	v_readlane_b32 s6, v198, s15
	v_readlane_b32 s7, v194, s23
	v_readlane_b32 s8, v196, s23
	v_readlane_b32 s9, v195, s23
	v_fma_f32 v15, -s6, v24, v15
	v_fma_f32 v29, -s7, v186, v29
	v_fma_f32 v28, -s8, v62, v28
	v_fma_f32 v14, -s9, v182, v14
	s_nop 0
	s_nop 0
	v_readlane_b32 s6, v198, s23
	v_readlane_b32 s7, v197, s15
	v_readlane_b32 s8, v200, s15
	v_readlane_b32 s9, v199, s15
	v_fma_f32 v15, -s6, v70, v15
	v_fma_f32 v29, -s7, v168, v29
	v_fma_f32 v28, -s8, v78, v28
	v_fma_f32 v14, -s9, v160, v14
	s_nop 0
	s_nop 0
	v_readlane_b32 s6, v202, s15
	v_readlane_b32 s7, v197, s23
	v_readlane_b32 s8, v200, s23
	v_readlane_b32 s9, v199, s23
	v_fma_f32 v15, -s6, v84, v15
	v_fma_f32 v29, -s7, v154, v29
	v_fma_f32 v28, -s8, v184, v28
	v_fma_f32 v14, -s9, v162, v14
	s_nop 0
	s_nop 0
	v_readlane_b32 s6, v202, s23
	v_readlane_b32 s7, v201, s15
	v_readlane_b32 s8, v204, s15
	v_readlane_b32 s9, v203, s15
	v_fma_f32 v15, -s6, v180, v15
	v_fma_f32 v29, -s7, v164, v29
	v_fma_f32 v28, -s8, v172, v28
	v_fma_f32 v14, -s9, v156, v14
	s_nop 0
	s_nop 0
	v_readlane_b32 s6, v206, s15
	v_readlane_b32 s7, v201, s23
	v_readlane_b32 s8, v204, s23
	v_readlane_b32 s9, v203, s23
	v_fma_f32 v15, -s6, v176, v15
	v_fma_f32 v29, -s7, v150, v29
	v_fma_f32 v28, -s8, v178, v28
	v_fma_f32 v14, -s9, v148, v14
	s_nop 0
	s_nop 0
	v_readlane_b32 s6, v206, s23
	v_readlane_b32 s7, v205, s15
	v_readlane_b32 s8, v208, s15
	v_readlane_b32 s9, v207, s15
	v_fma_f32 v15, -s6, v174, v15
	v_fma_f32 v29, -s7, v146, v29
	v_fma_f32 v28, -s8, v170, v28
	v_fma_f32 v14, -s9, v144, v14
	s_nop 0
	s_nop 0
	v_readlane_b32 s6, v209, s15
	v_readlane_b32 s7, v205, s23
	v_readlane_b32 s8, v208, s23
	v_readlane_b32 s9, v207, s23
	v_fma_f32 v15, -s6, v166, v15
	v_fma_f32 v29, -s7, v142, v29
	v_fma_f32 v28, -s8, v158, v28
	v_fma_f32 v14, -s9, v140, v14
	s_nop 0
	s_nop 0
	v_readlane_b32 s6, v209, s23
	s_nop 1
	v_fma_f32 v15, -s6, v152, v15
	s_nop 0
	s_nop 0
	s_nop 0
	s_nop 0
	s_nop 0
	s_nop 0
	s_nop 0
	s_nop 0
	s_nop 0
	s_nop 0
	s_nop 0
	s_nop 0
	s_nop 0
	s_nop 0
	s_nop 0
	s_nop 0
	s_nop 1
	s_nop 0
	v_pk_add_f32 v[14:15], v[28:29], v[14:15]
	s_nop 0
	v_pk_add_f32 v[188:189], v[14:15], v[14:15] op_sel:[0,1] op_sel_hi:[1,0]
	v_mov_b32_e32 v15, v123
	v_mov_b32_e32 v14, v123
	s_waitcnt lgkmcnt(0)
	v_sub_f32_e32 v7, v7, v246
	ds_read_b32 v247, v249 offset:0
	s_nop 0
	v_readlane_b32 s6, v195, s26
	v_readlane_b32 s7, v198, s26
	v_readlane_b32 s8, v194, s10
	v_readlane_b32 s9, v196, s10
	v_fma_f32 v7, -s6, v188, v7
	v_fma_f32 v15, -s7, v24, v15
	v_fma_f32 v14, -s8, v186, v14
	v_fma_f32 v6, -s9, v62, v6
	v_mov_b32_e32 v189, v24
	s_nop 0
	v_readlane_b32 s6, v195, s10
	v_readlane_b32 s7, v198, s10
	v_readlane_b32 s8, v197, s26
	v_readlane_b32 s9, v200, s26
	v_fma_f32 v7, -s6, v182, v7
	v_fma_f32 v15, -s7, v70, v15
	v_fma_f32 v14, -s8, v168, v14
	v_fma_f32 v6, -s9, v78, v6
	s_nop 0
	s_nop 0
	v_readlane_b32 s6, v199, s26
	v_readlane_b32 s7, v202, s26
	v_readlane_b32 s8, v197, s10
	v_readlane_b32 s9, v200, s10
	v_fma_f32 v7, -s6, v160, v7
	v_fma_f32 v15, -s7, v84, v15
	v_fma_f32 v14, -s8, v154, v14
	v_fma_f32 v6, -s9, v184, v6
	s_nop 0
	s_nop 0
	v_readlane_b32 s6, v199, s10
	v_readlane_b32 s7, v202, s10
	v_readlane_b32 s8, v201, s26
	v_readlane_b32 s9, v204, s26
	v_fma_f32 v7, -s6, v162, v7
	v_fma_f32 v15, -s7, v180, v15
	v_fma_f32 v14, -s8, v164, v14
	v_fma_f32 v6, -s9, v172, v6
	s_nop 0
	s_nop 0
	v_readlane_b32 s6, v203, s26
	v_readlane_b32 s7, v206, s26
	v_readlane_b32 s8, v201, s10
	v_readlane_b32 s9, v204, s10
	v_fma_f32 v7, -s6, v156, v7
	v_fma_f32 v15, -s7, v176, v15
	v_fma_f32 v14, -s8, v150, v14
	v_fma_f32 v6, -s9, v178, v6
	s_nop 0
	s_nop 0
	v_readlane_b32 s6, v203, s10
	v_readlane_b32 s7, v206, s10
	v_readlane_b32 s8, v205, s26
	v_readlane_b32 s9, v208, s26
	v_fma_f32 v7, -s6, v148, v7
	v_fma_f32 v15, -s7, v174, v15
	v_fma_f32 v14, -s8, v146, v14
	v_fma_f32 v6, -s9, v170, v6
	s_nop 0
	s_nop 0
	v_readlane_b32 s6, v207, s26
	v_readlane_b32 s7, v209, s26
	v_readlane_b32 s8, v205, s10
	v_readlane_b32 s9, v208, s10
	v_fma_f32 v7, -s6, v144, v7
	v_fma_f32 v15, -s7, v166, v15
	v_fma_f32 v14, -s8, v142, v14
	v_fma_f32 v6, -s9, v158, v6
	s_nop 0
	s_nop 0
	v_readlane_b32 s6, v207, s10
	v_readlane_b32 s7, v209, s10
	s_nop 0
	v_fma_f32 v7, -s6, v140, v7
	v_fma_f32 v15, -s7, v152, v15
	s_nop 0
	s_nop 0
	s_nop 0
	s_nop 0
	s_nop 0
	s_nop 0
	s_nop 0
	s_nop 0
	s_nop 0
	s_nop 0
	s_nop 0
	s_nop 0
	s_nop 0
	s_nop 0
	s_nop 0
	s_nop 0
	s_nop 1
	s_nop 0
	s_nop 0
	s_nop 1
	s_nop 0
	v_pk_add_f32 v[6:7], v[14:15], v[6:7]
	v_mov_b32_e32 v15, v123
	v_mov_b32_e32 v14, v123
	v_pk_add_f32 v[6:7], v[6:7], v[6:7] op_sel:[0,1] op_sel_hi:[1,0]
	s_nop 0
	s_waitcnt lgkmcnt(0)
	v_sub_f32_e32 v3, v3, v247
	s_nop 0
	v_readlane_b32 s6, v196, s13
	v_readlane_b32 s7, v195, s13
	v_readlane_b32 s8, v198, s13
	v_readlane_b32 s9, v194, s31
	v_fma_f32 v3, -s6, v6, v3
	v_fma_f32 v15, -s7, v188, v15
	v_fma_f32 v14, -s8, v24, v14
	v_fma_f32 v2, -s9, v186, v2
	s_nop 0
	s_nop 0
	v_readlane_b32 s6, v196, s31
	v_readlane_b32 s7, v195, s31
	v_readlane_b32 s8, v198, s31
	v_readlane_b32 s9, v197, s13
	v_fma_f32 v3, -s6, v62, v3
	v_fma_f32 v15, -s7, v182, v15
	v_fma_f32 v14, -s8, v70, v14
	v_fma_f32 v2, -s9, v168, v2
	s_nop 0
	s_nop 0
	v_readlane_b32 s6, v200, s13
	v_readlane_b32 s7, v199, s13
	v_readlane_b32 s8, v202, s13
	v_readlane_b32 s9, v197, s31
	v_fma_f32 v3, -s6, v78, v3
	v_fma_f32 v15, -s7, v160, v15
	v_fma_f32 v14, -s8, v84, v14
	v_fma_f32 v2, -s9, v154, v2
	s_nop 0
	s_nop 0
	v_readlane_b32 s6, v200, s31
	v_readlane_b32 s7, v199, s31
	v_readlane_b32 s8, v202, s31
	v_readlane_b32 s9, v201, s13
	v_fma_f32 v3, -s6, v184, v3
	v_fma_f32 v15, -s7, v162, v15
	v_fma_f32 v14, -s8, v180, v14
	v_fma_f32 v2, -s9, v164, v2
	s_nop 0
	s_nop 0
	v_readlane_b32 s6, v204, s13
	v_readlane_b32 s7, v203, s13
	v_readlane_b32 s8, v206, s13
	v_readlane_b32 s9, v201, s31
	v_fma_f32 v3, -s6, v172, v3
	v_fma_f32 v15, -s7, v156, v15
	v_fma_f32 v14, -s8, v176, v14
	v_fma_f32 v2, -s9, v150, v2
	s_nop 0
	s_nop 0
	v_readlane_b32 s6, v204, s31
	v_readlane_b32 s7, v203, s31
	v_readlane_b32 s8, v206, s31
	v_readlane_b32 s9, v205, s13
	v_fma_f32 v3, -s6, v178, v3
	v_fma_f32 v15, -s7, v148, v15
	v_fma_f32 v14, -s8, v174, v14
	v_fma_f32 v2, -s9, v146, v2
	s_nop 0
	s_nop 0
	v_readlane_b32 s6, v208, s13
	v_readlane_b32 s7, v207, s13
	v_readlane_b32 s8, v209, s13
	v_readlane_b32 s9, v205, s31
	v_fma_f32 v3, -s6, v170, v3
	v_fma_f32 v15, -s7, v144, v15
	v_fma_f32 v14, -s8, v166, v14
	v_fma_f32 v2, -s9, v142, v2
	s_nop 0
	s_nop 0
	v_readlane_b32 s6, v208, s31
	v_readlane_b32 s7, v207, s31
	v_readlane_b32 s8, v209, s31
	v_fma_f32 v3, -s6, v158, v3
	v_fma_f32 v15, -s7, v140, v15
	v_fma_f32 v14, -s8, v152, v14
	s_nop 0
	s_nop 0
	s_nop 0
	s_nop 0
	s_nop 0
	s_nop 0
	s_nop 0
	s_nop 0
	s_nop 0
	s_nop 0
	s_nop 0
	s_nop 0
	s_nop 0
	s_nop 0
	s_nop 0
	s_nop 0
	s_nop 1
	s_nop 0
	s_nop 0
	s_nop 1
	s_nop 0
	s_nop 0
	s_nop 1
	s_nop 0
	v_pk_add_f32 v[2:3], v[14:15], v[2:3]
	s_nop 0
	v_pk_add_f32 v[152:153], v[2:3], v[2:3] op_sel:[0,1] op_sel_hi:[1,0]
	v_readlane_b32 s6, v193, 0
	v_readlane_b32 s7, v193, 1
	v_mov_b32_e32 v153, v6
	s_nop 0
	v_pk_mul_f32 v[2:3], v[152:153], s[6:7]
	v_readlane_b32 s6, v193, 8
	v_readlane_b32 s7, v193, 9
	v_cvt_pk_bf16_f32 v62, v2, v3
	s_nop 0
	v_pk_mul_f32 v[4:5], v[168:169], s[6:7]
	v_readlane_b32 s6, v193, 2
	v_readlane_b32 s7, v193, 3
	v_cvt_pk_bf16_f32 v66, v4, v5
	s_nop 1
	v_permlane32_swap_b32_e32 v62, v66
	v_pk_mul_f32 v[6:7], v[188:189], s[6:7]
	v_readlane_b32 s6, v193, 10
	v_readlane_b32 s7, v193, 11
	v_cvt_pk_bf16_f32 v63, v6, v7
	s_nop 0
	v_pk_mul_f32 v[8:9], v[160:161], s[6:7]
	v_readlane_b32 s6, v193, 4
	v_readlane_b32 s7, v193, 5
	v_cvt_pk_bf16_f32 v67, v8, v9
	s_nop 1
	v_permlane32_swap_b32_e32 v63, v67
	v_pk_mul_f32 v[10:11], v[186:187], s[6:7]
	v_readlane_b32 s6, v193, 12
	v_readlane_b32 s7, v193, 13
	v_cvt_pk_bf16_f32 v64, v10, v11
	s_nop 0
	v_pk_mul_f32 v[12:13], v[154:155], s[6:7]
	v_readlane_b32 s6, v193, 6
	v_readlane_b32 s7, v193, 7
	v_cvt_pk_bf16_f32 v68, v12, v13
	s_nop 1
	v_permlane32_swap_b32_e32 v64, v68
	v_pk_mul_f32 v[14:15], v[182:183], s[6:7]
	v_readlane_b32 s6, v193, 14
	v_readlane_b32 s7, v193, 15
	v_cvt_pk_bf16_f32 v65, v14, v15
	s_nop 0
	v_pk_mul_f32 v[16:17], v[162:163], s[6:7]
	v_readlane_b32 s6, v193, 16
	v_readlane_b32 s7, v193, 17
	v_cvt_pk_bf16_f32 v69, v16, v17
	s_nop 1
	v_permlane32_swap_b32_e32 v65, v69
	v_pk_mul_f32 v[2:3], v[164:165], s[6:7]
	v_readlane_b32 s6, v193, 24
	v_readlane_b32 s7, v193, 25
	v_cvt_pk_bf16_f32 v70, v2, v3
	s_nop 0
	v_pk_mul_f32 v[4:5], v[146:147], s[6:7]
	v_readlane_b32 s6, v193, 18
	v_readlane_b32 s7, v193, 19
	v_cvt_pk_bf16_f32 v74, v4, v5
	s_nop 1
	v_permlane32_swap_b32_e32 v70, v74
	v_pk_mul_f32 v[6:7], v[156:157], s[6:7]
	v_readlane_b32 s6, v193, 26
	v_readlane_b32 s7, v193, 27
	v_cvt_pk_bf16_f32 v71, v6, v7
	s_nop 0
	v_pk_mul_f32 v[8:9], v[144:145], s[6:7]
	v_readlane_b32 s6, v193, 20
	v_readlane_b32 s7, v193, 21
	v_cvt_pk_bf16_f32 v75, v8, v9
	s_nop 1
	v_permlane32_swap_b32_e32 v71, v75
	v_pk_mul_f32 v[10:11], v[150:151], s[6:7]
	v_readlane_b32 s6, v193, 28
	v_readlane_b32 s7, v193, 29
	v_cvt_pk_bf16_f32 v72, v10, v11
	s_nop 0
	v_pk_mul_f32 v[12:13], v[142:143], s[6:7]
	v_readlane_b32 s6, v193, 22
	v_readlane_b32 s7, v193, 23
	v_cvt_pk_bf16_f32 v76, v12, v13
	s_nop 1
	v_permlane32_swap_b32_e32 v72, v76
	v_pk_mul_f32 v[14:15], v[148:149], s[6:7]
	v_readlane_b32 s6, v193, 30
	v_readlane_b32 s7, v193, 31
	v_cvt_pk_bf16_f32 v73, v14, v15
	s_nop 0
	v_pk_mul_f32 v[16:17], v[140:141], s[6:7]
	v_readlane_b32 s6, v193, 32
	v_readlane_b32 s7, v193, 33
	v_cvt_pk_bf16_f32 v77, v16, v17
	s_nop 1
	v_permlane32_swap_b32_e32 v73, v77
	v_pk_mul_f32 v[2:3], v[138:139], s[6:7]
	v_readlane_b32 s6, v193, 40
	v_readlane_b32 s7, v193, 41
	v_cvt_pk_bf16_f32 v2, v2, v3
	s_nop 0
	v_pk_mul_f32 v[4:5], v[130:131], s[6:7]
	v_readlane_b32 s6, v193, 34
	v_readlane_b32 s7, v193, 35
	v_cvt_pk_bf16_f32 v78, v4, v5
	s_nop 1
	v_permlane32_swap_b32_e32 v2, v78
	v_pk_mul_f32 v[6:7], v[136:137], s[6:7]
	v_readlane_b32 s6, v193, 42
	v_readlane_b32 s7, v193, 43
	v_cvt_pk_bf16_f32 v3, v6, v7
	s_nop 0
	v_pk_mul_f32 v[8:9], v[128:129], s[6:7]
	v_readlane_b32 s6, v193, 36
	v_readlane_b32 s7, v193, 37
	v_cvt_pk_bf16_f32 v79, v8, v9
	s_nop 1
	v_permlane32_swap_b32_e32 v3, v79
	v_pk_mul_f32 v[10:11], v[134:135], s[6:7]
	v_readlane_b32 s6, v193, 44
	v_readlane_b32 s7, v193, 45
	v_cvt_pk_bf16_f32 v6, v10, v11
	s_nop 0
	v_pk_mul_f32 v[12:13], v[118:119], s[6:7]
	v_readlane_b32 s6, v193, 38
	v_readlane_b32 s7, v193, 39
	v_cvt_pk_bf16_f32 v80, v12, v13
	s_nop 1
	v_permlane32_swap_b32_e32 v6, v80
	v_pk_mul_f32 v[14:15], v[132:133], s[6:7]
	v_readlane_b32 s6, v193, 46
	v_readlane_b32 s7, v193, 47
	v_cvt_pk_bf16_f32 v7, v14, v15
	s_nop 0
	v_pk_mul_f32 v[16:17], v[116:117], s[6:7]
	v_readlane_b32 s6, v193, 48
	v_readlane_b32 s7, v193, 49
	v_cvt_pk_bf16_f32 v81, v16, v17
	s_nop 1
	v_permlane32_swap_b32_e32 v7, v81
	v_pk_mul_f32 v[2:3], v[114:115], s[6:7]
	v_readlane_b32 s6, v193, 56
	v_readlane_b32 s7, v193, 57
	v_cvt_pk_bf16_f32 v2, v2, v3
	s_nop 0
	v_pk_mul_f32 v[4:5], v[94:95], s[6:7]
	v_readlane_b32 s6, v193, 50
	v_readlane_b32 s7, v193, 51
	v_cvt_pk_bf16_f32 v82, v4, v5
	s_nop 1
	v_permlane32_swap_b32_e32 v2, v82
	v_pk_mul_f32 v[6:7], v[110:111], s[6:7]
	v_readlane_b32 s6, v193, 58
	v_readlane_b32 s7, v193, 59
	v_cvt_pk_bf16_f32 v3, v6, v7
	s_nop 0
	v_pk_mul_f32 v[8:9], v[92:93], s[6:7]
	v_readlane_b32 s6, v193, 52
	v_readlane_b32 s7, v193, 53
	v_cvt_pk_bf16_f32 v83, v8, v9
	s_nop 1
	v_permlane32_swap_b32_e32 v3, v83
	v_pk_mul_f32 v[10:11], v[104:105], s[6:7]
	v_readlane_b32 s6, v193, 60
	v_readlane_b32 s7, v193, 61
	v_cvt_pk_bf16_f32 v6, v10, v11
	s_nop 0
	v_pk_mul_f32 v[12:13], v[90:91], s[6:7]
	v_readlane_b32 s6, v193, 54
	v_readlane_b32 s7, v193, 55
	v_cvt_pk_bf16_f32 v84, v12, v13
	s_nop 1
	v_permlane32_swap_b32_e32 v6, v84
	v_pk_mul_f32 v[14:15], v[96:97], s[6:7]
	v_readlane_b32 s6, v193, 62
	v_readlane_b32 s7, v193, 63
	v_cvt_pk_bf16_f32 v7, v14, v15
	s_nop 0
	v_pk_mul_f32 v[16:17], v[88:89], s[6:7]
	s_mov_b32 s7, 0x26400000
	v_cvt_pk_bf16_f32 v85, v16, v17
	s_nop 1
	v_permlane32_swap_b32_e32 v7, v85
	s_waitcnt vmcnt(5)
	v_mfma_f32_32x32x16_bf16 v[2:17], v[62:65], v[18:21], 0
	s_mov_b32 s6, 0x9002000
	v_mfma_f32_32x32x16_bf16 v[18:33], v[66:69], v[18:21], 0
	v_mfma_f32_32x32x16_bf16 v[18:33], v[74:77], v[58:61], v[18:33]
	v_mfma_f32_32x32x16_bf16 v[18:33], v[78:81], v[54:57], v[18:33]
	v_mfma_f32_32x32x16_bf16 v[2:17], v[70:73], v[58:61], v[2:17]
	s_waitcnt vmcnt(4)
	v_mfma_f32_32x32x16_bf16 v[18:33], v[82:85], v[50:53], v[18:33]
	v_add_co_u32_e32 v50, vcc, s7, v126
	s_nop 8
	v_cvt_pk_bf16_f32 v2, v2, v3
	v_cvt_pk_bf16_f32 v3, v4, v5
	v_cvt_pk_bf16_f32 v4, v6, v7
	v_cvt_pk_bf16_f32 v5, v8, v9
	v_addc_co_u32_e32 v51, vcc, 0, v127, vcc
	global_store_dwordx4 v[50:51], v[2:5], off
	v_add_co_u32_e32 v6, vcc, s7, v120
	s_nop 0
	v_cvt_pk_bf16_f32 v2, v10, v11
	v_cvt_pk_bf16_f32 v3, v12, v13
	v_cvt_pk_bf16_f32 v4, v14, v15
	v_cvt_pk_bf16_f32 v5, v16, v17
	global_store_dwordx4 v[50:51], v[2:5], off offset:16
	v_addc_co_u32_e32 v7, vcc, 0, v121, vcc
	s_nop 0
	v_cvt_pk_bf16_f32 v2, v18, v19
	v_cvt_pk_bf16_f32 v3, v20, v21
	v_cvt_pk_bf16_f32 v4, v22, v23
	v_cvt_pk_bf16_f32 v5, v24, v25
	global_store_dwordx4 v[6:7], v[2:5], off
	s_nop 1
	v_cvt_pk_bf16_f32 v2, v26, v27
	v_cvt_pk_bf16_f32 v3, v28, v29
	v_cvt_pk_bf16_f32 v4, v30, v31
	v_cvt_pk_bf16_f32 v5, v32, v33
	global_store_dwordx4 v[6:7], v[2:5], off offset:16
	s_waitcnt vmcnt(7)
	v_mfma_f32_32x32x16_bf16 v[18:33], v[62:65], v[46:49], 0
	v_mfma_f32_32x32x16_bf16 v[2:17], v[66:69], v[46:49], 0
	s_waitcnt vmcnt(6)
	v_mfma_f32_32x32x16_bf16 v[2:17], v[74:77], v[42:45], v[2:17]
	s_waitcnt vmcnt(5)
	v_mfma_f32_32x32x16_bf16 v[2:17], v[78:81], v[38:41], v[2:17]
	s_waitcnt vmcnt(4)
	v_mfma_f32_32x32x16_bf16 v[2:17], v[82:85], v[34:37], v[2:17]
	v_mfma_f32_32x32x16_bf16 v[18:33], v[70:73], v[42:45], v[18:33]
	s_nop 10
	v_cvt_pk_bf16_f32 v2, v2, v3
	v_cvt_pk_bf16_f32 v3, v4, v5
	v_cvt_pk_bf16_f32 v4, v6, v7
	v_add_co_u32_e32 v6, vcc, s7, v112
	v_cvt_pk_bf16_f32 v5, v8, v9
	s_nop 0
	v_addc_co_u32_e32 v7, vcc, 0, v113, vcc
	v_cvt_pk_bf16_f32 v18, v18, v19
	v_cvt_pk_bf16_f32 v19, v20, v21
	v_cvt_pk_bf16_f32 v20, v22, v23
	v_cvt_pk_bf16_f32 v21, v24, v25
	v_add_co_u32_e32 v38, vcc, s6, v98
	global_store_dwordx4 v[50:51], v[18:21], off offset:2048
	s_nop 0
	v_addc_co_u32_e32 v39, vcc, 0, v99, vcc
	v_cvt_pk_bf16_f32 v18, v26, v27
	v_cvt_pk_bf16_f32 v19, v28, v29
	v_cvt_pk_bf16_f32 v20, v30, v31
	v_cvt_pk_bf16_f32 v21, v32, v33
	s_mov_b32 s6, 0x9003000
	global_store_dwordx4 v[50:51], v[18:21], off offset:2064
	global_store_dwordx4 v[6:7], v[2:5], off
	v_add_co_u32_e32 v40, vcc, s6, v98
	s_nop 0
	v_cvt_pk_bf16_f32 v2, v10, v11
	v_cvt_pk_bf16_f32 v3, v12, v13
	v_cvt_pk_bf16_f32 v4, v14, v15
	v_cvt_pk_bf16_f32 v5, v16, v17
	global_store_dwordx4 v[6:7], v[2:5], off offset:16
	v_addc_co_u32_e32 v41, vcc, 0, v99, vcc
	s_nop 0
	s_nop 0
	s_nop 0
	v_mfma_f32_32x32x16_bf16 v[18:33], v[62:65], v[212:215], 0
	v_mfma_f32_32x32x16_bf16 v[2:17], v[66:69], v[212:215], 0
	s_nop 0
	v_mfma_f32_32x32x16_bf16 v[18:33], v[70:73], v[216:219], v[18:33]
	v_mfma_f32_32x32x16_bf16 v[2:17], v[74:77], v[216:219], v[2:17]
	s_nop 0
	s_nop 9
	v_cvt_pk_bf16_f32 v18, v18, v19
	v_cvt_pk_bf16_f32 v19, v20, v21
	v_cvt_pk_bf16_f32 v20, v22, v23
	v_add_co_u32_e32 v22, vcc, s7, v108
	v_cvt_pk_bf16_f32 v21, v24, v25
	s_nop 0
	v_mfma_f32_32x32x16_bf16 v[2:17], v[78:81], v[220:223], v[2:17]
	s_nop 0
	v_addc_co_u32_e32 v23, vcc, 0, v109, vcc
	global_store_dwordx4 v[22:23], v[18:21], off
	s_nop 1
	v_cvt_pk_bf16_f32 v18, v26, v27
	s_nop 0
	v_mfma_f32_32x32x16_bf16 v[2:17], v[82:85], v[224:227], v[2:17]
	v_cvt_pk_bf16_f32 v19, v28, v29
	v_cvt_pk_bf16_f32 v20, v30, v31
	v_cvt_pk_bf16_f32 v21, v32, v33
	global_store_dwordx4 v[22:23], v[18:21], off offset:16
	s_nop 7
	v_cvt_pk_bf16_f32 v2, v2, v3
	v_cvt_pk_bf16_f32 v3, v4, v5
	v_cvt_pk_bf16_f32 v4, v6, v7
	v_add_co_u32_e32 v6, vcc, s7, v106
	v_cvt_pk_bf16_f32 v5, v8, v9
	s_nop 0
	v_addc_co_u32_e32 v7, vcc, 0, v107, vcc
	global_store_dwordx4 v[6:7], v[2:5], off
	s_nop 1
	v_cvt_pk_bf16_f32 v2, v10, v11
	v_cvt_pk_bf16_f32 v3, v12, v13
	v_cvt_pk_bf16_f32 v4, v14, v15
	v_cvt_pk_bf16_f32 v5, v16, v17
	global_store_dwordx4 v[6:7], v[2:5], off offset:16
	s_nop 0
	s_nop 0
	s_nop 0
	s_nop 0
	v_mfma_f32_32x32x16_bf16 v[18:33], v[62:65], v[228:231], 0
	v_mfma_f32_32x32x16_bf16 v[2:17], v[66:69], v[228:231], 0
	s_nop 0
	v_mfma_f32_32x32x16_bf16 v[18:33], v[70:73], v[232:235], v[18:33]
	v_mfma_f32_32x32x16_bf16 v[2:17], v[74:77], v[232:235], v[2:17]
	s_nop 0
	s_nop 9
	v_cvt_pk_bf16_f32 v18, v18, v19
	v_cvt_pk_bf16_f32 v19, v20, v21
	v_cvt_pk_bf16_f32 v20, v22, v23
	v_add_co_u32_e32 v22, vcc, s7, v102
	v_cvt_pk_bf16_f32 v21, v24, v25
	s_nop 0
	v_mfma_f32_32x32x16_bf16 v[2:17], v[78:81], v[236:239], v[2:17]
	s_nop 0
	v_addc_co_u32_e32 v23, vcc, 0, v103, vcc
	global_store_dwordx4 v[22:23], v[18:21], off
	s_nop 1
	v_cvt_pk_bf16_f32 v18, v26, v27
	s_nop 0
	v_mfma_f32_32x32x16_bf16 v[2:17], v[82:85], v[240:243], v[2:17]
	v_cvt_pk_bf16_f32 v19, v28, v29
	v_cvt_pk_bf16_f32 v20, v30, v31
	v_cvt_pk_bf16_f32 v21, v32, v33
	global_store_dwordx4 v[22:23], v[18:21], off offset:16
	s_nop 7
	v_cvt_pk_bf16_f32 v2, v2, v3
	v_cvt_pk_bf16_f32 v3, v4, v5
	v_cvt_pk_bf16_f32 v4, v6, v7
	v_add_co_u32_e32 v6, vcc, s7, v100
	v_cvt_pk_bf16_f32 v5, v8, v9
	s_nop 0
	v_addc_co_u32_e32 v7, vcc, 0, v101, vcc
	global_store_dwordx4 v[6:7], v[2:5], off
	s_nop 1
	v_cvt_pk_bf16_f32 v2, v10, v11
	v_cvt_pk_bf16_f32 v3, v12, v13
	v_cvt_pk_bf16_f32 v4, v14, v15
	v_cvt_pk_bf16_f32 v5, v16, v17
	global_store_dwordx4 v[6:7], v[2:5], off offset:16
	s_lshl_b64 s[96:97], s[4:5], 20
	v_readlane_b32 s98, v250, 3
	s_add_u32 s96, s98, s96
	v_readlane_b32 s98, v250, 4
	s_addc_u32 s97, s98, s97
	v_readlane_b32 s98, v250, 13
	s_lshl_b32 s98, s98, 14
	s_add_u32 s96, s96, s98
	s_addc_u32 s97, s97, 0
	s_add_u32 s96, s96, 0x1000
	s_addc_u32 s97, s97, 0
	v_lshl_add_u64 v[246:247], s[96:97], 0, v[86:87]
	v_lshl_add_u64 v[246:247], v[246:247], 0, v[122:123]
	s_mov_b32 s96, 0x2000
	s_mov_b32 s97, 0
	v_lshl_add_u64 v[248:249], v[246:247], 0, s[96:97]
	global_load_dwordx4 v[224:227], v[246:247], off offset:-4096
	global_load_dwordx4 v[228:231], v[246:247], off offset:-4064
	global_load_dwordx4 v[212:215], v[246:247], off offset:-4032
	global_load_dwordx4 v[216:219], v[246:247], off offset:-4000
	global_load_dwordx4 v[220:223], v[246:247], off
	global_load_dwordx4 v[234:237], v[246:247], off offset:32
	global_load_dwordx4 v[238:241], v[246:247], off offset:64
	global_load_dwordx4 v[242:245], v[246:247], off offset:96
	global_load_dwordx4 v[70:73], v[248:249], off offset:-4096
	global_load_dwordx4 v[74:77], v[248:249], off offset:-4064
	global_load_dwordx4 v[78:81], v[248:249], off offset:-4032
	global_load_dwordx4 v[82:85], v[248:249], off offset:-4000
	global_load_dwordx4 v[98:101], v[248:249], off
	global_load_dwordx4 v[106:109], v[248:249], off offset:32
	global_load_dwordx4 v[194:197], v[248:249], off offset:64
	global_load_dwordx4 v[198:201], v[248:249], off offset:96
	v_readlane_b32 s6, v210, 0
	v_readlane_b32 s7, v210, 1
	s_lshl_b64 s[4:5], s[4:5], 20
	v_readlane_b32 s8, v250, 17
	v_pk_mul_f32 v[2:3], v[152:153], s[6:7]
	v_readlane_b32 s6, v210, 8
	v_readlane_b32 s7, v210, 9
	v_cvt_pk_bf16_f32 v34, v2, v3
	s_nop 0
	v_pk_mul_f32 v[4:5], v[168:169], s[6:7]
	v_readlane_b32 s6, v210, 2
	v_readlane_b32 s7, v210, 3
	v_cvt_pk_bf16_f32 v38, v4, v5
	s_nop 1
	v_permlane32_swap_b32_e32 v34, v38
	v_pk_mul_f32 v[6:7], v[188:189], s[6:7]
	v_readlane_b32 s6, v210, 10
	v_readlane_b32 s7, v210, 11
	v_cvt_pk_bf16_f32 v35, v6, v7
	s_nop 0
	v_pk_mul_f32 v[8:9], v[160:161], s[6:7]
	v_readlane_b32 s6, v210, 4
	v_readlane_b32 s7, v210, 5
	v_cvt_pk_bf16_f32 v39, v8, v9
	s_nop 1
	v_permlane32_swap_b32_e32 v35, v39
	v_pk_mul_f32 v[10:11], v[186:187], s[6:7]
	v_readlane_b32 s6, v210, 12
	v_readlane_b32 s7, v210, 13
	v_cvt_pk_bf16_f32 v36, v10, v11
	s_nop 0
	v_pk_mul_f32 v[12:13], v[154:155], s[6:7]
	v_readlane_b32 s6, v210, 6
	v_readlane_b32 s7, v210, 7
	v_cvt_pk_bf16_f32 v40, v12, v13
	s_nop 1
	v_permlane32_swap_b32_e32 v36, v40
	v_pk_mul_f32 v[14:15], v[182:183], s[6:7]
	v_readlane_b32 s6, v210, 14
	v_readlane_b32 s7, v210, 15
	v_cvt_pk_bf16_f32 v37, v14, v15
	s_nop 0
	v_pk_mul_f32 v[16:17], v[162:163], s[6:7]
	v_readlane_b32 s6, v210, 16
	v_readlane_b32 s7, v210, 17
	v_cvt_pk_bf16_f32 v41, v16, v17
	s_nop 1
	v_permlane32_swap_b32_e32 v37, v41
	v_pk_mul_f32 v[2:3], v[164:165], s[6:7]
	v_readlane_b32 s6, v210, 24
	v_readlane_b32 s7, v210, 25
	v_cvt_pk_bf16_f32 v42, v2, v3
	s_nop 0
	v_pk_mul_f32 v[4:5], v[146:147], s[6:7]
	v_readlane_b32 s6, v210, 18
	v_readlane_b32 s7, v210, 19
	v_cvt_pk_bf16_f32 v46, v4, v5
	s_nop 1
	v_permlane32_swap_b32_e32 v42, v46
	v_pk_mul_f32 v[6:7], v[156:157], s[6:7]
	v_readlane_b32 s6, v210, 26
	v_readlane_b32 s7, v210, 27
	v_cvt_pk_bf16_f32 v43, v6, v7
	s_nop 0
	v_pk_mul_f32 v[8:9], v[144:145], s[6:7]
	v_readlane_b32 s6, v210, 20
	v_readlane_b32 s7, v210, 21
	v_cvt_pk_bf16_f32 v47, v8, v9
	s_nop 1
	v_permlane32_swap_b32_e32 v43, v47
	v_pk_mul_f32 v[10:11], v[150:151], s[6:7]
	v_readlane_b32 s6, v210, 28
	v_readlane_b32 s7, v210, 29
	v_cvt_pk_bf16_f32 v44, v10, v11
	s_nop 0
	v_pk_mul_f32 v[12:13], v[142:143], s[6:7]
	v_readlane_b32 s6, v210, 22
	v_readlane_b32 s7, v210, 23
	v_cvt_pk_bf16_f32 v48, v12, v13
	s_nop 1
	v_permlane32_swap_b32_e32 v44, v48
	v_pk_mul_f32 v[14:15], v[148:149], s[6:7]
	v_readlane_b32 s6, v210, 30
	v_readlane_b32 s7, v210, 31
	v_cvt_pk_bf16_f32 v45, v14, v15
	s_nop 0
	v_pk_mul_f32 v[16:17], v[140:141], s[6:7]
	v_readlane_b32 s6, v210, 32
	v_readlane_b32 s7, v210, 33
	v_cvt_pk_bf16_f32 v49, v16, v17
	s_nop 1
	v_permlane32_swap_b32_e32 v45, v49
	v_pk_mul_f32 v[2:3], v[138:139], s[6:7]
	v_readlane_b32 s6, v210, 40
	v_readlane_b32 s7, v210, 41
	v_cvt_pk_bf16_f32 v2, v2, v3
	s_nop 0
	v_pk_mul_f32 v[4:5], v[130:131], s[6:7]
	v_readlane_b32 s6, v210, 34
	v_readlane_b32 s7, v210, 35
	v_cvt_pk_bf16_f32 v50, v4, v5
	s_nop 1
	v_permlane32_swap_b32_e32 v2, v50
	v_pk_mul_f32 v[6:7], v[136:137], s[6:7]
	v_readlane_b32 s6, v210, 42
	v_readlane_b32 s7, v210, 43
	v_cvt_pk_bf16_f32 v3, v6, v7
	s_nop 0
	v_pk_mul_f32 v[8:9], v[128:129], s[6:7]
	v_readlane_b32 s6, v210, 36
	v_readlane_b32 s7, v210, 37
	v_cvt_pk_bf16_f32 v51, v8, v9
	s_nop 1
	v_permlane32_swap_b32_e32 v3, v51
	v_pk_mul_f32 v[10:11], v[134:135], s[6:7]
	v_readlane_b32 s6, v210, 44
	v_readlane_b32 s7, v210, 45
	v_cvt_pk_bf16_f32 v6, v10, v11
	s_nop 0
	v_pk_mul_f32 v[12:13], v[118:119], s[6:7]
	v_readlane_b32 s6, v210, 38
	v_readlane_b32 s7, v210, 39
	v_cvt_pk_bf16_f32 v52, v12, v13
	s_nop 1
	v_permlane32_swap_b32_e32 v6, v52
	v_pk_mul_f32 v[14:15], v[132:133], s[6:7]
	v_readlane_b32 s6, v210, 46
	v_readlane_b32 s7, v210, 47
	v_cvt_pk_bf16_f32 v7, v14, v15
	s_nop 0
	v_pk_mul_f32 v[16:17], v[116:117], s[6:7]
	v_readlane_b32 s6, v210, 48
	v_readlane_b32 s7, v210, 49
	v_cvt_pk_bf16_f32 v53, v16, v17
	s_nop 1
	v_permlane32_swap_b32_e32 v7, v53
	v_pk_mul_f32 v[2:3], v[114:115], s[6:7]
	v_readlane_b32 s6, v210, 56
	v_readlane_b32 s7, v210, 57
	v_cvt_pk_bf16_f32 v2, v2, v3
	s_nop 0
	v_pk_mul_f32 v[4:5], v[94:95], s[6:7]
	v_readlane_b32 s6, v210, 50
	v_readlane_b32 s7, v210, 51
	v_cvt_pk_bf16_f32 v54, v4, v5
	s_nop 1
	v_permlane32_swap_b32_e32 v2, v54
	v_pk_mul_f32 v[6:7], v[110:111], s[6:7]
	v_readlane_b32 s6, v210, 58
	v_readlane_b32 s7, v210, 59
	v_cvt_pk_bf16_f32 v3, v6, v7
	v_lshlrev_b32_e32 v2, 8, v192
	v_pk_mul_f32 v[8:9], v[92:93], s[6:7]
	v_readlane_b32 s6, v210, 52
	v_readlane_b32 s7, v210, 53
	v_cvt_pk_bf16_f32 v55, v8, v9
	s_nop 1
	v_permlane32_swap_b32_e32 v3, v55
	v_pk_mul_f32 v[10:11], v[104:105], s[6:7]
	v_readlane_b32 s6, v210, 60
	v_readlane_b32 s7, v210, 61
	v_mov_b32_e32 v3, v123
	v_lshl_add_u64 v[2:3], v[2:3], 0, v[124:125]
	v_pk_mul_f32 v[12:13], v[90:91], s[6:7]
	v_readlane_b32 s6, v210, 54
	v_readlane_b32 s7, v210, 55
	v_lshl_add_u64 v[64:65], s[0:1], 0, v[2:3]
	v_cvt_pk_bf16_f32 v6, v10, v11
	v_pk_mul_f32 v[14:15], v[96:97], s[6:7]
	v_readlane_b32 s6, v210, 62
	v_readlane_b32 s7, v210, 63
	v_cvt_pk_bf16_f32 v7, v14, v15
	v_cvt_pk_bf16_f32 v56, v12, v13
	v_pk_mul_f32 v[16:17], v[88:89], s[6:7]
	v_readlane_b32 s6, v250, 3
	s_add_u32 s4, s6, s4
	v_readlane_b32 s6, v250, 4
	s_addc_u32 s5, s6, s5
	v_readlane_b32 s6, v250, 13
	s_lshl_b32 s6, s6, 14
	s_add_u32 s4, s4, s6
	s_addc_u32 s5, s5, 0
	v_lshl_add_u64 v[62:63], s[4:5], 0, v[86:87]
	v_lshl_add_u64 v[66:67], v[62:63], 0, v[122:123]
	v_mov_b32_e32 v142, 0x1000
	v_mov_b32_e32 v143, 0
	v_lshl_add_u64 v[130:131], v[66:67], 0, v[142:143]
	v_lshl_add_u64 v[134:135], v[130:131], 0, v[142:143]
	v_lshl_add_u64 v[138:139], v[134:135], 0, v[142:143]
	s_nop 0
	s_nop 0
	s_nop 0
	s_nop 0
	s_nop 0
	s_nop 0
	s_nop 0
	s_nop 0
	s_nop 0
	s_nop 0
	v_cvt_pk_bf16_f32 v57, v16, v17
	v_permlane32_swap_b32_e32 v6, v56
	s_nop 0
	v_permlane32_swap_b32_e32 v7, v57
	s_nop 0
	s_waitcnt vmcnt(15)
	v_mfma_f32_32x32x16_bf16 v[18:33], v[224:227], v[34:37], 0
	s_mov_b32 s0, 0x2e400000
	v_readlane_b32 s7, v250, 15
	v_mfma_f32_32x32x16_bf16 v[2:17], v[224:227], v[38:41], 0
	s_nop 0
	s_waitcnt vmcnt(14)
	v_mfma_f32_32x32x16_bf16 v[18:33], v[228:231], v[42:45], v[18:33]
	v_mfma_f32_32x32x16_bf16 v[2:17], v[228:231], v[46:49], v[2:17]
	s_nop 0
	s_nop 9
	v_cvt_pk_bf16_f32 v18, v18, v19
	v_cvt_pk_bf16_f32 v19, v20, v21
	s_nop 0
	s_waitcnt vmcnt(13)
	v_mfma_f32_32x32x16_bf16 v[2:17], v[212:215], v[50:53], v[2:17]
	s_nop 0
	s_nop 0
	s_waitcnt vmcnt(12)
	v_mfma_f32_32x32x16_bf16 v[2:17], v[216:219], v[54:57], v[2:17]
	v_add_co_u32_e32 v58, vcc, s0, v64
	s_mov_b32 s0, 0x2e402000
	s_nop 0
	v_addc_co_u32_e32 v59, vcc, 0, v65, vcc
	v_add_co_u32_e32 v60, vcc, s0, v64
	s_nop 6
	v_cvt_pk_bf16_f32 v2, v2, v3
	v_cvt_pk_bf16_f32 v3, v4, v5
	v_addc_co_u32_e32 v61, vcc, 0, v65, vcc
	global_store_dwordx2 v[60:61], v[2:3], off
	v_cvt_pk_bf16_f32 v2, v22, v23
	v_cvt_pk_bf16_f32 v3, v24, v25
	global_store_dwordx2 v[58:59], v[2:3], off offset:16
	v_cvt_pk_bf16_f32 v2, v6, v7
	v_cvt_pk_bf16_f32 v3, v8, v9
	global_store_dwordx2 v[60:61], v[2:3], off offset:16
	v_cvt_pk_bf16_f32 v2, v26, v27
	v_cvt_pk_bf16_f32 v3, v28, v29
	global_store_dwordx2 v[58:59], v[2:3], off offset:32
	v_cvt_pk_bf16_f32 v2, v10, v11
	v_cvt_pk_bf16_f32 v3, v12, v13
	global_store_dwordx2 v[60:61], v[2:3], off offset:32
	v_cvt_pk_bf16_f32 v2, v30, v31
	v_cvt_pk_bf16_f32 v3, v32, v33
	global_store_dwordx2 v[58:59], v[2:3], off offset:48
	v_cvt_pk_bf16_f32 v2, v14, v15
	v_cvt_pk_bf16_f32 v3, v16, v17
	global_store_dwordx2 v[60:61], v[2:3], off offset:48
	v_or_b32_e32 v2, 0x1000, v122
	v_mov_b32_e32 v3, v123
	global_store_dwordx2 v[58:59], v[18:19], off
	v_lshl_add_u64 v[68:69], v[62:63], 0, v[2:3]
	s_nop 0
	s_nop 0
	s_nop 0
	s_nop 0
	s_nop 0
	s_nop 0
	s_nop 0
	s_waitcnt vmcnt(19)
	v_mfma_f32_32x32x16_bf16 v[18:33], v[220:223], v[34:37], 0
	v_readlane_b32 s0, v250, 9
	v_readlane_b32 s1, v250, 10
	s_add_i32 s33, s33, s0
	v_readlane_b32 s0, v250, 5
	v_readlane_b32 s1, v250, 6
	s_add_u32 s24, s24, s0
	s_addc_u32 s25, s25, s1
	v_mfma_f32_32x32x16_bf16 v[2:17], v[220:223], v[38:41], 0
	v_readlane_b32 s0, v250, 7
	v_readlane_b32 s1, v250, 8
	s_add_u32 s28, s28, s0
	s_addc_u32 s29, s29, s1
	v_readlane_b32 s0, v250, 11
	v_readlane_b32 s1, v250, 12
	s_add_u32 s7, s7, s0
	s_nop 0
	s_waitcnt vmcnt(18)
	v_mfma_f32_32x32x16_bf16 v[18:33], v[234:237], v[42:45], v[18:33]
	s_addc_u32 s8, s8, s1
	s_cmpk_lt_i32 s33, 0x2000
	v_mfma_f32_32x32x16_bf16 v[2:17], v[234:237], v[46:49], v[2:17]
	s_nop 0
	s_nop 7
	v_cvt_pk_bf16_f32 v18, v18, v19
	v_cvt_pk_bf16_f32 v19, v20, v21
	s_nop 0
	s_waitcnt vmcnt(17)
	v_mfma_f32_32x32x16_bf16 v[2:17], v[238:241], v[50:53], v[2:17]
	s_nop 0
	s_nop 0
	global_store_dwordx2 v[58:59], v[18:19], off offset:64
	s_nop 0
	s_waitcnt vmcnt(17)
	v_mfma_f32_32x32x16_bf16 v[2:17], v[242:245], v[54:57], v[2:17]
	s_nop 11
	v_cvt_pk_bf16_f32 v2, v2, v3
	v_cvt_pk_bf16_f32 v3, v4, v5
	global_store_dwordx2 v[60:61], v[2:3], off offset:64
	v_cvt_pk_bf16_f32 v2, v22, v23
	v_cvt_pk_bf16_f32 v3, v24, v25
	global_store_dwordx2 v[58:59], v[2:3], off offset:80
	v_cvt_pk_bf16_f32 v2, v6, v7
	v_cvt_pk_bf16_f32 v3, v8, v9
	global_store_dwordx2 v[60:61], v[2:3], off offset:80
	v_cvt_pk_bf16_f32 v2, v26, v27
	v_cvt_pk_bf16_f32 v3, v28, v29
	global_store_dwordx2 v[58:59], v[2:3], off offset:96
	v_cvt_pk_bf16_f32 v2, v10, v11
	v_cvt_pk_bf16_f32 v3, v12, v13
	global_store_dwordx2 v[60:61], v[2:3], off offset:96
	v_cvt_pk_bf16_f32 v2, v30, v31
	v_cvt_pk_bf16_f32 v3, v32, v33
	global_store_dwordx2 v[58:59], v[2:3], off offset:112
	v_cvt_pk_bf16_f32 v2, v14, v15
	v_cvt_pk_bf16_f32 v3, v16, v17
	global_store_dwordx2 v[60:61], v[2:3], off offset:112
	v_or_b32_e32 v2, 0x2000, v122
	v_mov_b32_e32 v3, v123
	v_lshl_add_u64 v[68:69], v[62:63], 0, v[2:3]
	s_nop 0
	s_nop 0
	s_nop 0
	s_nop 0
	s_nop 0
	s_nop 0
	s_nop 0
	s_waitcnt vmcnt(23)
	v_mfma_f32_32x32x16_bf16 v[18:33], v[70:73], v[34:37], 0
	v_or_b32_e32 v122, 0x3000, v122
	v_lshl_add_u64 v[62:63], v[62:63], 0, v[122:123]
	v_mfma_f32_32x32x16_bf16 v[2:17], v[70:73], v[38:41], 0
	s_nop 0
	s_waitcnt vmcnt(22)
	v_mfma_f32_32x32x16_bf16 v[18:33], v[74:77], v[42:45], v[18:33]
	v_mfma_f32_32x32x16_bf16 v[2:17], v[74:77], v[46:49], v[2:17]
	s_nop 0
	s_nop 9
	v_cvt_pk_bf16_f32 v18, v18, v19
	v_cvt_pk_bf16_f32 v19, v20, v21
	s_nop 0
	s_waitcnt vmcnt(21)
	v_mfma_f32_32x32x16_bf16 v[2:17], v[78:81], v[50:53], v[2:17]
	s_nop 0
	s_nop 0
	global_store_dwordx2 v[58:59], v[18:19], off offset:128
	s_nop 0
	s_waitcnt vmcnt(21)
	v_mfma_f32_32x32x16_bf16 v[2:17], v[82:85], v[54:57], v[2:17]
	s_nop 11
	v_cvt_pk_bf16_f32 v2, v2, v3
	v_cvt_pk_bf16_f32 v3, v4, v5
	global_store_dwordx2 v[60:61], v[2:3], off offset:128
	v_cvt_pk_bf16_f32 v2, v22, v23
	v_cvt_pk_bf16_f32 v3, v24, v25
	global_store_dwordx2 v[58:59], v[2:3], off offset:144
	v_cvt_pk_bf16_f32 v2, v6, v7
	v_cvt_pk_bf16_f32 v3, v8, v9
	global_store_dwordx2 v[60:61], v[2:3], off offset:144
	v_cvt_pk_bf16_f32 v2, v26, v27
	v_cvt_pk_bf16_f32 v3, v28, v29
	global_store_dwordx2 v[58:59], v[2:3], off offset:160
	v_cvt_pk_bf16_f32 v2, v10, v11
	v_cvt_pk_bf16_f32 v3, v12, v13
	global_store_dwordx2 v[60:61], v[2:3], off offset:160
	v_cvt_pk_bf16_f32 v2, v30, v31
	v_cvt_pk_bf16_f32 v3, v32, v33
	global_store_dwordx2 v[58:59], v[2:3], off offset:176
	v_cvt_pk_bf16_f32 v2, v14, v15
	v_cvt_pk_bf16_f32 v3, v16, v17
	global_store_dwordx2 v[60:61], v[2:3], off offset:176
	s_nop 0
	s_nop 0
	s_waitcnt vmcnt(27)
	v_mfma_f32_32x32x16_bf16 v[18:33], v[98:101], v[34:37], 0
	s_nop 0
	v_mfma_f32_32x32x16_bf16 v[2:17], v[98:101], v[38:41], 0
	s_nop 0
	s_waitcnt vmcnt(26)
	v_mfma_f32_32x32x16_bf16 v[18:33], v[106:109], v[42:45], v[18:33]
	s_nop 11
	v_cvt_pk_bf16_f32 v18, v18, v19
	v_mfma_f32_32x32x16_bf16 v[2:17], v[106:109], v[46:49], v[2:17]
	s_nop 0
	v_cvt_pk_bf16_f32 v19, v20, v21
	s_nop 0
	s_waitcnt vmcnt(25)
	v_mfma_f32_32x32x16_bf16 v[2:17], v[194:197], v[50:53], v[2:17]
	s_nop 0
	s_nop 0
	global_store_dwordx2 v[58:59], v[18:19], off offset:192
	s_nop 0
	s_waitcnt vmcnt(25)
	v_mfma_f32_32x32x16_bf16 v[2:17], v[198:201], v[54:57], v[2:17]
	s_nop 11
	v_cvt_pk_bf16_f32 v2, v2, v3
	v_cvt_pk_bf16_f32 v3, v4, v5
	global_store_dwordx2 v[60:61], v[2:3], off offset:192
	v_cvt_pk_bf16_f32 v2, v22, v23
	v_cvt_pk_bf16_f32 v3, v24, v25
	global_store_dwordx2 v[58:59], v[2:3], off offset:208
	v_cvt_pk_bf16_f32 v2, v6, v7
	v_cvt_pk_bf16_f32 v3, v8, v9
	global_store_dwordx2 v[60:61], v[2:3], off offset:208
	v_cvt_pk_bf16_f32 v2, v26, v27
	v_cvt_pk_bf16_f32 v3, v28, v29
	global_store_dwordx2 v[58:59], v[2:3], off offset:224
	v_cvt_pk_bf16_f32 v2, v10, v11
	v_cvt_pk_bf16_f32 v3, v12, v13
	global_store_dwordx2 v[60:61], v[2:3], off offset:224
	v_cvt_pk_bf16_f32 v2, v30, v31
	v_cvt_pk_bf16_f32 v3, v32, v33
	global_store_dwordx2 v[58:59], v[2:3], off offset:240
	v_cvt_pk_bf16_f32 v2, v14, v15
	v_cvt_pk_bf16_f32 v3, v16, v17
	global_store_dwordx2 v[60:61], v[2:3], off offset:240
	s_waitcnt lgkmcnt(0)
	s_cbranch_scc0 .LBB0_782
